# phase0: modulation GEMV kk loops unrolled with 32 weight loads in flight; mod items moved to CUs>=144
# speedup vs baseline: 1.0271x; 1.0065x over previous
.LBB0_5:
	s_or_b64 exec, exec, s[4:5]
	s_load_dwordx8 s[4:11], s[0:1], 0x100
	s_load_dwordx16 s[36:51], s[0:1], 0x0
	v_mov_b32_e32 v18, v211
	s_not_b32 s3, s54
	s_waitcnt lgkmcnt(0)
	s_add_i32 s3, s10, s3
	v_and_b32_e32 v148, 63, v18
	v_ashrrev_i32_e32 v7, 6, v18
	s_cmpk_gt_i32 s3, 0x6f
	v_lshlrev_b32_e32 v4, 2, v148
	s_cbranch_scc1 .LBB0_43
	s_load_dwordx8 s[16:23], s[0:1], 0x100
	s_movk_i32 s10, 0x2100
	v_mov_b32_e32 v5, 0
	v_max_i32_e32 v1, 0x4000, v18
	v_and_b32_e32 v6, 0x1ff, v18
	v_mul_lo_u32 v16, v7, s10
	s_waitcnt lgkmcnt(0)
	v_lshl_add_u64 v[2:3], s[20:21], 0, v[4:5]
	s_mov_b64 s[10:11], 0x3200000
	v_sub_u32_e32 v1, v1, v18
	v_lshl_add_u64 v[8:9], v[2:3], 0, s[10:11]
	v_lshlrev_b32_e32 v2, 2, v6
	v_mov_b32_e32 v3, v5
	v_add_u32_e32 v1, 0x1ff, v1
	v_lshl_add_u64 v[10:11], s[42:43], 0, v[2:3]
	v_lshrrev_b32_e32 v2, 9, v1
	v_add_u32_e32 v12, 1, v2
	s_movk_i32 s12, 0x1ff
	v_add_u32_e32 v13, -1, v2
	v_and_b32_e32 v17, 0xfffffe, v12
	v_lshlrev_b32_e32 v55, 2, v18
	v_and_b32_e32 v14, 0xffffffc0, v18
	v_lshrrev_b32_e32 v2, 1, v13
	v_cmp_lt_u32_e64 s[10:11], s12, v1
	v_cmp_lt_u32_e64 s[12:13], 1, v13
	v_and_b32_e32 v13, 2, v13
	v_cmp_ne_u32_e64 s[16:17], v12, v17
	v_and_b32_e32 v12, 0xffffff00, v55
	s_movk_i32 s60, 0x6000
	v_add_u32_e32 v15, 1, v2
	v_cmp_eq_u32_e64 s[14:15], 0, v13
	v_add_u32_e32 v57, 0, v12
	v_mad_i64_i32 v[12:13], s[18:19], v14, s60, 0
	v_add_u32_e32 v14, 0x200, v14
	v_and_b32_e32 v54, -2, v15
	v_mad_i64_i32 v[14:15], s[18:19], v14, s60, 0
	s_movk_i32 s4, 0x4200
	v_add_u32_e32 v53, 0, v4
	s_movk_i32 s8, 0x840
	v_or_b32_e32 v12, v12, v4
	v_or_b32_e32 v14, v14, v4
	v_cmp_gt_i32_e64 s[4:5], s4, v18
	v_cmp_gt_i32_e64 s[8:9], s8, v18
	v_lshl_add_u32 v5, v17, 9, v18
	v_mov_b32_e32 v1, v6
	v_mov_b32_e32 v2, v10
	v_mov_b32_e32 v3, v11
	v_add_u32_e32 v19, 0x200, v18
	v_add_u32_e32 v56, 0, v55
	v_lshl_add_u64 v[12:13], s[44:45], 0, v[12:13]
	v_lshl_add_u64 v[14:15], s[44:45], 0, v[14:15]
	s_mov_b32 s61, 0xbfb8aa3b
	s_mov_b32 s62, 0x42ce8ed0
	s_mov_b32 s63, 0xc2b17218
	s_movk_i32 s64, 0x3fff
	s_mov_b64 s[24:25], 0xc000
	v_add_u32_e32 v58, v53, v16
	s_movk_i32 s65, 0x63f
	v_mov_b32_e32 v59, 0x7f800000
	s_branch .LBB0_8
.LBB0_7:
	s_or_b64 exec, exec, s[18:19]
	s_mov_b32 s2, s54
	s_load_dwordx8 s[52:59], s[0:1], 0x100
	s_waitcnt lgkmcnt(0)
	s_mov_b32 s54, s2
	s_barrier
	s_addk_i32 s3, 0x70
	s_cmpk_gt_i32 s3, 0xbf
	s_cbranch_scc1 .LBB0_43

.LBB0_22:
	s_or_b64 exec, exec, s[26:27]
	s_mul_hi_i32 s18, s3, 0x2aaaaaab
	s_lshr_b32 s19, s18, 31
	s_ashr_i32 s66, s18, 4
	s_add_i32 s66, s66, s19
	s_mul_i32 s18, s66, 0x60
	s_sub_i32 s18, s3, s18
	s_lshl_b32 s26, s18, 6
	s_ashr_i32 s27, s26, 31
	s_mul_i32 s21, s66, 0x1800000
	s_lshl_b64 s[18:19], s[26:27], 2
	s_mul_hi_i32 s20, s66, 0x1800000
	s_add_u32 s28, s21, s18
	s_addc_u32 s29, s20, s19
	v_mov_b32_e32 v60, 0
	v_lshl_add_u64 v[50:51], v[12:13], 0, s[28:29]
	s_movk_i32 s18, 0xff00
	v_mov_b32_e32 v16, 0
	v_mov_b32_e32 v17, v60
	v_mov_b32_e32 v20, 0
	v_mov_b32_e32 v21, v60
	v_mov_b32_e32 v22, 0
	v_mov_b32_e32 v23, v60
	v_mov_b32_e32 v24, 0
	v_mov_b32_e32 v25, v60
	v_mov_b32_e32 v26, 0
	v_mov_b32_e32 v27, v60
	v_mov_b32_e32 v28, 0
	v_mov_b32_e32 v29, v60
	v_mov_b32_e32 v34, 0
	v_mov_b32_e32 v35, v60
	v_mov_b32_e32 v42, 0
	v_mov_b32_e32 v43, v60
	v_mov_b32_e32 v30, 0
	v_mov_b32_e32 v31, v60
	v_mov_b32_e32 v32, 0
	v_mov_b32_e32 v33, v60
	v_mov_b32_e32 v36, 0
	v_mov_b32_e32 v37, v60
	v_mov_b32_e32 v38, 0
	v_mov_b32_e32 v39, v60
	v_mov_b32_e32 v40, 0
	v_mov_b32_e32 v41, v60
	v_mov_b32_e32 v44, 0
	v_mov_b32_e32 v45, v60
	v_mov_b32_e32 v46, 0
	v_mov_b32_e32 v47, v60
	v_mov_b32_e32 v48, 0
	v_mov_b32_e32 v49, v60
	s_waitcnt lgkmcnt(0)
	s_barrier
	global_load_dword v164, v[50:51], off
	v_add_co_u32_e32 v62, vcc, s60, v50
	s_nop 1
	v_addc_co_u32_e32 v63, vcc, 0, v51, vcc
	v_lshl_add_u64 v[50:51], v[50:51], 0, s[24:25]
	global_load_dword v165, v[62:63], off
	global_load_dword v166, v[50:51], off
	v_add_co_u32_e32 v62, vcc, s60, v50
	s_nop 1
	v_addc_co_u32_e32 v63, vcc, 0, v51, vcc
	v_lshl_add_u64 v[50:51], v[50:51], 0, s[24:25]
	global_load_dword v167, v[62:63], off
	global_load_dword v168, v[50:51], off
	v_add_co_u32_e32 v62, vcc, s60, v50
	s_nop 1
	v_addc_co_u32_e32 v63, vcc, 0, v51, vcc
	v_lshl_add_u64 v[50:51], v[50:51], 0, s[24:25]
	global_load_dword v169, v[62:63], off
	global_load_dword v170, v[50:51], off
	v_add_co_u32_e32 v62, vcc, s60, v50
	s_nop 1
	v_addc_co_u32_e32 v63, vcc, 0, v51, vcc
	v_lshl_add_u64 v[50:51], v[50:51], 0, s[24:25]
	global_load_dword v171, v[62:63], off
	global_load_dword v172, v[50:51], off
	v_add_co_u32_e32 v62, vcc, s60, v50
	s_nop 1
	v_addc_co_u32_e32 v63, vcc, 0, v51, vcc
	v_lshl_add_u64 v[50:51], v[50:51], 0, s[24:25]
	global_load_dword v173, v[62:63], off
	global_load_dword v174, v[50:51], off
	v_add_co_u32_e32 v62, vcc, s60, v50
	s_nop 1
	v_addc_co_u32_e32 v63, vcc, 0, v51, vcc
	v_lshl_add_u64 v[50:51], v[50:51], 0, s[24:25]
	global_load_dword v175, v[62:63], off
	global_load_dword v176, v[50:51], off
	v_add_co_u32_e32 v62, vcc, s60, v50
	s_nop 1
	v_addc_co_u32_e32 v63, vcc, 0, v51, vcc
	v_lshl_add_u64 v[50:51], v[50:51], 0, s[24:25]
	global_load_dword v177, v[62:63], off
	global_load_dword v178, v[50:51], off
	v_add_co_u32_e32 v62, vcc, s60, v50
	s_nop 1
	v_addc_co_u32_e32 v63, vcc, 0, v51, vcc
	v_lshl_add_u64 v[50:51], v[50:51], 0, s[24:25]
	global_load_dword v179, v[62:63], off
	global_load_dword v180, v[50:51], off
	v_add_co_u32_e32 v62, vcc, s60, v50
	s_nop 1
	v_addc_co_u32_e32 v63, vcc, 0, v51, vcc
	v_lshl_add_u64 v[50:51], v[50:51], 0, s[24:25]
	global_load_dword v181, v[62:63], off
	global_load_dword v182, v[50:51], off
	v_add_co_u32_e32 v62, vcc, s60, v50
	s_nop 1
	v_addc_co_u32_e32 v63, vcc, 0, v51, vcc
	v_lshl_add_u64 v[50:51], v[50:51], 0, s[24:25]
	global_load_dword v183, v[62:63], off
	global_load_dword v184, v[50:51], off
	v_add_co_u32_e32 v62, vcc, s60, v50
	s_nop 1
	v_addc_co_u32_e32 v63, vcc, 0, v51, vcc
	v_lshl_add_u64 v[50:51], v[50:51], 0, s[24:25]
	global_load_dword v185, v[62:63], off
	global_load_dword v186, v[50:51], off
	v_add_co_u32_e32 v62, vcc, s60, v50
	s_nop 1
	v_addc_co_u32_e32 v63, vcc, 0, v51, vcc
	v_lshl_add_u64 v[50:51], v[50:51], 0, s[24:25]
	global_load_dword v187, v[62:63], off
	global_load_dword v188, v[50:51], off
	v_add_co_u32_e32 v62, vcc, s60, v50
	s_nop 1
	v_addc_co_u32_e32 v63, vcc, 0, v51, vcc
	v_lshl_add_u64 v[50:51], v[50:51], 0, s[24:25]
	global_load_dword v189, v[62:63], off
	global_load_dword v190, v[50:51], off
	v_add_co_u32_e32 v62, vcc, s60, v50
	s_nop 1
	v_addc_co_u32_e32 v63, vcc, 0, v51, vcc
	v_lshl_add_u64 v[50:51], v[50:51], 0, s[24:25]
	global_load_dword v191, v[62:63], off
	global_load_dword v192, v[50:51], off
	v_add_co_u32_e32 v62, vcc, s60, v50
	s_nop 1
	v_addc_co_u32_e32 v63, vcc, 0, v51, vcc
	v_lshl_add_u64 v[50:51], v[50:51], 0, s[24:25]
	global_load_dword v193, v[62:63], off
	global_load_dword v194, v[50:51], off
	v_add_co_u32_e32 v62, vcc, s60, v50
	s_nop 1
	v_addc_co_u32_e32 v63, vcc, 0, v51, vcc
	v_lshl_add_u64 v[50:51], v[50:51], 0, s[24:25]
	global_load_dword v195, v[62:63], off
	v_add_u32_e32 v149, 0x10000, v57
	v_mov_b32_e32 v61, v57
	v_mov_b32_e32 v150, v149
	ds_read2st64_b64 v[62:65], v61 offset1:4
	ds_read2st64_b64 v[66:69], v61 offset0:8 offset1:12
	ds_read2st64_b64 v[70:73], v61 offset0:16 offset1:20
	ds_read2st64_b64 v[74:77], v61 offset0:24 offset1:28
	ds_read2st64_b64 v[78:81], v61 offset0:32 offset1:36
	ds_read2st64_b64 v[82:85], v61 offset0:40 offset1:44
	ds_read2st64_b64 v[86:89], v61 offset0:48 offset1:52
	ds_read2st64_b64 v[90:93], v61 offset0:56 offset1:60
	ds_read2st64_b64 v[94:97], v61 offset0:64 offset1:68
	ds_read2st64_b64 v[98:101], v61 offset0:72 offset1:76
	ds_read2st64_b64 v[102:105], v61 offset0:80 offset1:84
	ds_read2st64_b64 v[106:109], v61 offset0:88 offset1:92
	ds_read2st64_b64 v[110:113], v61 offset0:96 offset1:100
	ds_read2st64_b64 v[114:117], v61 offset0:104 offset1:108
	ds_read2st64_b64 v[118:121], v61 offset0:112 offset1:116
	ds_read2st64_b64 v[122:125], v61 offset0:120 offset1:124
	ds_read_b64 v[128:129], v150
	s_waitcnt vmcnt(30)
	s_waitcnt lgkmcnt(15)
	v_fmac_f32_e32 v30, v164, v62
	v_fmac_f32_e32 v43, v164, v64
	s_waitcnt lgkmcnt(15)
	v_fmac_f32_e32 v42, v164, v66
	v_fmac_f32_e32 v35, v164, v68
	s_waitcnt lgkmcnt(14)
	v_fmac_f32_e32 v34, v164, v70
	v_fmac_f32_e32 v29, v164, v72
	s_waitcnt lgkmcnt(13)
	v_fmac_f32_e32 v28, v164, v74
	v_fmac_f32_e32 v27, v164, v76
	s_waitcnt lgkmcnt(12)
	v_fmac_f32_e32 v26, v164, v78
	v_fmac_f32_e32 v25, v164, v80
	s_waitcnt lgkmcnt(11)
	v_fmac_f32_e32 v24, v164, v82
	v_fmac_f32_e32 v23, v164, v84
	s_waitcnt lgkmcnt(10)
	v_fmac_f32_e32 v22, v164, v86
	v_fmac_f32_e32 v21, v164, v88
	s_waitcnt lgkmcnt(9)
	v_fmac_f32_e32 v20, v164, v90
	v_fmac_f32_e32 v17, v164, v92
	s_waitcnt lgkmcnt(8)
	v_fmac_f32_e32 v16, v164, v94
	v_fmac_f32_e32 v31, v164, v96
	s_waitcnt lgkmcnt(7)
	v_fmac_f32_e32 v32, v164, v98
	v_fmac_f32_e32 v33, v164, v100
	s_waitcnt lgkmcnt(6)
	v_fmac_f32_e32 v36, v164, v102
	v_fmac_f32_e32 v37, v164, v104
	s_waitcnt lgkmcnt(5)
	v_fmac_f32_e32 v38, v164, v106
	v_fmac_f32_e32 v39, v164, v108
	s_waitcnt lgkmcnt(4)
	v_fmac_f32_e32 v40, v164, v110
	v_fmac_f32_e32 v41, v164, v112
	s_waitcnt lgkmcnt(3)
	v_fmac_f32_e32 v44, v164, v114
	v_fmac_f32_e32 v45, v164, v116
	s_waitcnt lgkmcnt(2)
	v_fmac_f32_e32 v46, v164, v118
	v_fmac_f32_e32 v47, v164, v120
	s_waitcnt lgkmcnt(1)
	v_fmac_f32_e32 v48, v164, v122
	v_fmac_f32_e32 v49, v164, v124
	s_waitcnt lgkmcnt(0)
	v_fmac_f32_e32 v60, v164, v128
	v_fmac_f32_e32 v30, v165, v63
	v_fmac_f32_e32 v43, v165, v65
	v_fmac_f32_e32 v42, v165, v67
	v_fmac_f32_e32 v35, v165, v69
	v_fmac_f32_e32 v34, v165, v71
	v_fmac_f32_e32 v29, v165, v73
	v_fmac_f32_e32 v28, v165, v75
	v_fmac_f32_e32 v27, v165, v77
	v_fmac_f32_e32 v26, v165, v79
	v_fmac_f32_e32 v25, v165, v81
	v_fmac_f32_e32 v24, v165, v83
	v_fmac_f32_e32 v23, v165, v85
	v_fmac_f32_e32 v22, v165, v87
	v_fmac_f32_e32 v21, v165, v89
	v_fmac_f32_e32 v20, v165, v91
	v_fmac_f32_e32 v17, v165, v93
	v_fmac_f32_e32 v16, v165, v95
	v_fmac_f32_e32 v31, v165, v97
	v_fmac_f32_e32 v32, v165, v99
	v_fmac_f32_e32 v33, v165, v101
	v_fmac_f32_e32 v36, v165, v103
	v_fmac_f32_e32 v37, v165, v105
	v_fmac_f32_e32 v38, v165, v107
	v_fmac_f32_e32 v39, v165, v109
	v_fmac_f32_e32 v40, v165, v111
	v_fmac_f32_e32 v41, v165, v113
	v_fmac_f32_e32 v44, v165, v115
	v_fmac_f32_e32 v45, v165, v117
	v_fmac_f32_e32 v46, v165, v119
	v_fmac_f32_e32 v47, v165, v121
	v_fmac_f32_e32 v48, v165, v123
	v_fmac_f32_e32 v49, v165, v125
	v_fmac_f32_e32 v60, v165, v129
	global_load_dword v196, v[50:51], off
	v_add_co_u32_e32 v62, vcc, s60, v50
	s_nop 1
	v_addc_co_u32_e32 v63, vcc, 0, v51, vcc
	v_lshl_add_u64 v[50:51], v[50:51], 0, s[24:25]
	global_load_dword v197, v[62:63], off
	v_add_u32_e32 v61, 8, v57
	v_add_u32_e32 v150, 8, v149
	ds_read2st64_b64 v[62:65], v61 offset1:4
	ds_read2st64_b64 v[66:69], v61 offset0:8 offset1:12
	ds_read2st64_b64 v[70:73], v61 offset0:16 offset1:20
	ds_read2st64_b64 v[74:77], v61 offset0:24 offset1:28
	ds_read2st64_b64 v[78:81], v61 offset0:32 offset1:36
	ds_read2st64_b64 v[82:85], v61 offset0:40 offset1:44
	ds_read2st64_b64 v[86:89], v61 offset0:48 offset1:52
	ds_read2st64_b64 v[90:93], v61 offset0:56 offset1:60
	ds_read2st64_b64 v[94:97], v61 offset0:64 offset1:68
	ds_read2st64_b64 v[98:101], v61 offset0:72 offset1:76
	ds_read2st64_b64 v[102:105], v61 offset0:80 offset1:84
	ds_read2st64_b64 v[106:109], v61 offset0:88 offset1:92
	ds_read2st64_b64 v[110:113], v61 offset0:96 offset1:100
	ds_read2st64_b64 v[114:117], v61 offset0:104 offset1:108
	ds_read2st64_b64 v[118:121], v61 offset0:112 offset1:116
	ds_read2st64_b64 v[122:125], v61 offset0:120 offset1:124
	ds_read_b64 v[128:129], v150
	s_waitcnt vmcnt(30)
	s_waitcnt lgkmcnt(15)
	v_fmac_f32_e32 v30, v166, v62
	v_fmac_f32_e32 v43, v166, v64
	s_waitcnt lgkmcnt(15)
	v_fmac_f32_e32 v42, v166, v66
	v_fmac_f32_e32 v35, v166, v68
	s_waitcnt lgkmcnt(14)
	v_fmac_f32_e32 v34, v166, v70
	v_fmac_f32_e32 v29, v166, v72
	s_waitcnt lgkmcnt(13)
	v_fmac_f32_e32 v28, v166, v74
	v_fmac_f32_e32 v27, v166, v76
	s_waitcnt lgkmcnt(12)
	v_fmac_f32_e32 v26, v166, v78
	v_fmac_f32_e32 v25, v166, v80
	s_waitcnt lgkmcnt(11)
	v_fmac_f32_e32 v24, v166, v82
	v_fmac_f32_e32 v23, v166, v84
	s_waitcnt lgkmcnt(10)
	v_fmac_f32_e32 v22, v166, v86
	v_fmac_f32_e32 v21, v166, v88
	s_waitcnt lgkmcnt(9)
	v_fmac_f32_e32 v20, v166, v90
	v_fmac_f32_e32 v17, v166, v92
	s_waitcnt lgkmcnt(8)
	v_fmac_f32_e32 v16, v166, v94
	v_fmac_f32_e32 v31, v166, v96
	s_waitcnt lgkmcnt(7)
	v_fmac_f32_e32 v32, v166, v98
	v_fmac_f32_e32 v33, v166, v100
	s_waitcnt lgkmcnt(6)
	v_fmac_f32_e32 v36, v166, v102
	v_fmac_f32_e32 v37, v166, v104
	s_waitcnt lgkmcnt(5)
	v_fmac_f32_e32 v38, v166, v106
	v_fmac_f32_e32 v39, v166, v108
	s_waitcnt lgkmcnt(4)
	v_fmac_f32_e32 v40, v166, v110
	v_fmac_f32_e32 v41, v166, v112
	s_waitcnt lgkmcnt(3)
	v_fmac_f32_e32 v44, v166, v114
	v_fmac_f32_e32 v45, v166, v116
	s_waitcnt lgkmcnt(2)
	v_fmac_f32_e32 v46, v166, v118
	v_fmac_f32_e32 v47, v166, v120
	s_waitcnt lgkmcnt(1)
	v_fmac_f32_e32 v48, v166, v122
	v_fmac_f32_e32 v49, v166, v124
	s_waitcnt lgkmcnt(0)
	v_fmac_f32_e32 v60, v166, v128
	v_fmac_f32_e32 v30, v167, v63
	v_fmac_f32_e32 v43, v167, v65
	v_fmac_f32_e32 v42, v167, v67
	v_fmac_f32_e32 v35, v167, v69
	v_fmac_f32_e32 v34, v167, v71
	v_fmac_f32_e32 v29, v167, v73
	v_fmac_f32_e32 v28, v167, v75
	v_fmac_f32_e32 v27, v167, v77
	v_fmac_f32_e32 v26, v167, v79
	v_fmac_f32_e32 v25, v167, v81
	v_fmac_f32_e32 v24, v167, v83
	v_fmac_f32_e32 v23, v167, v85
	v_fmac_f32_e32 v22, v167, v87
	v_fmac_f32_e32 v21, v167, v89
	v_fmac_f32_e32 v20, v167, v91
	v_fmac_f32_e32 v17, v167, v93
	v_fmac_f32_e32 v16, v167, v95
	v_fmac_f32_e32 v31, v167, v97
	v_fmac_f32_e32 v32, v167, v99
	v_fmac_f32_e32 v33, v167, v101
	v_fmac_f32_e32 v36, v167, v103
	v_fmac_f32_e32 v37, v167, v105
	v_fmac_f32_e32 v38, v167, v107
	v_fmac_f32_e32 v39, v167, v109
	v_fmac_f32_e32 v40, v167, v111
	v_fmac_f32_e32 v41, v167, v113
	v_fmac_f32_e32 v44, v167, v115
	v_fmac_f32_e32 v45, v167, v117
	v_fmac_f32_e32 v46, v167, v119
	v_fmac_f32_e32 v47, v167, v121
	v_fmac_f32_e32 v48, v167, v123
	v_fmac_f32_e32 v49, v167, v125
	v_fmac_f32_e32 v60, v167, v129
	global_load_dword v198, v[50:51], off
	v_add_co_u32_e32 v62, vcc, s60, v50
	s_nop 1
	v_addc_co_u32_e32 v63, vcc, 0, v51, vcc
	v_lshl_add_u64 v[50:51], v[50:51], 0, s[24:25]
	global_load_dword v199, v[62:63], off
	v_add_u32_e32 v61, 16, v57
	v_add_u32_e32 v150, 16, v149
	ds_read2st64_b64 v[62:65], v61 offset1:4
	ds_read2st64_b64 v[66:69], v61 offset0:8 offset1:12
	ds_read2st64_b64 v[70:73], v61 offset0:16 offset1:20
	ds_read2st64_b64 v[74:77], v61 offset0:24 offset1:28
	ds_read2st64_b64 v[78:81], v61 offset0:32 offset1:36
	ds_read2st64_b64 v[82:85], v61 offset0:40 offset1:44
	ds_read2st64_b64 v[86:89], v61 offset0:48 offset1:52
	ds_read2st64_b64 v[90:93], v61 offset0:56 offset1:60
	ds_read2st64_b64 v[94:97], v61 offset0:64 offset1:68
	ds_read2st64_b64 v[98:101], v61 offset0:72 offset1:76
	ds_read2st64_b64 v[102:105], v61 offset0:80 offset1:84
	ds_read2st64_b64 v[106:109], v61 offset0:88 offset1:92
	ds_read2st64_b64 v[110:113], v61 offset0:96 offset1:100
	ds_read2st64_b64 v[114:117], v61 offset0:104 offset1:108
	ds_read2st64_b64 v[118:121], v61 offset0:112 offset1:116
	ds_read2st64_b64 v[122:125], v61 offset0:120 offset1:124
	ds_read_b64 v[128:129], v150
	s_waitcnt vmcnt(30)
	s_waitcnt lgkmcnt(15)
	v_fmac_f32_e32 v30, v168, v62
	v_fmac_f32_e32 v43, v168, v64
	s_waitcnt lgkmcnt(15)
	v_fmac_f32_e32 v42, v168, v66
	v_fmac_f32_e32 v35, v168, v68
	s_waitcnt lgkmcnt(14)
	v_fmac_f32_e32 v34, v168, v70
	v_fmac_f32_e32 v29, v168, v72
	s_waitcnt lgkmcnt(13)
	v_fmac_f32_e32 v28, v168, v74
	v_fmac_f32_e32 v27, v168, v76
	s_waitcnt lgkmcnt(12)
	v_fmac_f32_e32 v26, v168, v78
	v_fmac_f32_e32 v25, v168, v80
	s_waitcnt lgkmcnt(11)
	v_fmac_f32_e32 v24, v168, v82
	v_fmac_f32_e32 v23, v168, v84
	s_waitcnt lgkmcnt(10)
	v_fmac_f32_e32 v22, v168, v86
	v_fmac_f32_e32 v21, v168, v88
	s_waitcnt lgkmcnt(9)
	v_fmac_f32_e32 v20, v168, v90
	v_fmac_f32_e32 v17, v168, v92
	s_waitcnt lgkmcnt(8)
	v_fmac_f32_e32 v16, v168, v94
	v_fmac_f32_e32 v31, v168, v96
	s_waitcnt lgkmcnt(7)
	v_fmac_f32_e32 v32, v168, v98
	v_fmac_f32_e32 v33, v168, v100
	s_waitcnt lgkmcnt(6)
	v_fmac_f32_e32 v36, v168, v102
	v_fmac_f32_e32 v37, v168, v104
	s_waitcnt lgkmcnt(5)
	v_fmac_f32_e32 v38, v168, v106
	v_fmac_f32_e32 v39, v168, v108
	s_waitcnt lgkmcnt(4)
	v_fmac_f32_e32 v40, v168, v110
	v_fmac_f32_e32 v41, v168, v112
	s_waitcnt lgkmcnt(3)
	v_fmac_f32_e32 v44, v168, v114
	v_fmac_f32_e32 v45, v168, v116
	s_waitcnt lgkmcnt(2)
	v_fmac_f32_e32 v46, v168, v118
	v_fmac_f32_e32 v47, v168, v120
	s_waitcnt lgkmcnt(1)
	v_fmac_f32_e32 v48, v168, v122
	v_fmac_f32_e32 v49, v168, v124
	s_waitcnt lgkmcnt(0)
	v_fmac_f32_e32 v60, v168, v128
	v_fmac_f32_e32 v30, v169, v63
	v_fmac_f32_e32 v43, v169, v65
	v_fmac_f32_e32 v42, v169, v67
	v_fmac_f32_e32 v35, v169, v69
	v_fmac_f32_e32 v34, v169, v71
	v_fmac_f32_e32 v29, v169, v73
	v_fmac_f32_e32 v28, v169, v75
	v_fmac_f32_e32 v27, v169, v77
	v_fmac_f32_e32 v26, v169, v79
	v_fmac_f32_e32 v25, v169, v81
	v_fmac_f32_e32 v24, v169, v83
	v_fmac_f32_e32 v23, v169, v85
	v_fmac_f32_e32 v22, v169, v87
	v_fmac_f32_e32 v21, v169, v89
	v_fmac_f32_e32 v20, v169, v91
	v_fmac_f32_e32 v17, v169, v93
	v_fmac_f32_e32 v16, v169, v95
	v_fmac_f32_e32 v31, v169, v97
	v_fmac_f32_e32 v32, v169, v99
	v_fmac_f32_e32 v33, v169, v101
	v_fmac_f32_e32 v36, v169, v103
	v_fmac_f32_e32 v37, v169, v105
	v_fmac_f32_e32 v38, v169, v107
	v_fmac_f32_e32 v39, v169, v109
	v_fmac_f32_e32 v40, v169, v111
	v_fmac_f32_e32 v41, v169, v113
	v_fmac_f32_e32 v44, v169, v115
	v_fmac_f32_e32 v45, v169, v117
	v_fmac_f32_e32 v46, v169, v119
	v_fmac_f32_e32 v47, v169, v121
	v_fmac_f32_e32 v48, v169, v123
	v_fmac_f32_e32 v49, v169, v125
	v_fmac_f32_e32 v60, v169, v129
	global_load_dword v200, v[50:51], off
	v_add_co_u32_e32 v62, vcc, s60, v50
	s_nop 1
	v_addc_co_u32_e32 v63, vcc, 0, v51, vcc
	v_lshl_add_u64 v[50:51], v[50:51], 0, s[24:25]
	global_load_dword v201, v[62:63], off
	v_add_u32_e32 v61, 24, v57
	v_add_u32_e32 v150, 24, v149
	ds_read2st64_b64 v[62:65], v61 offset1:4
	ds_read2st64_b64 v[66:69], v61 offset0:8 offset1:12
	ds_read2st64_b64 v[70:73], v61 offset0:16 offset1:20
	ds_read2st64_b64 v[74:77], v61 offset0:24 offset1:28
	ds_read2st64_b64 v[78:81], v61 offset0:32 offset1:36
	ds_read2st64_b64 v[82:85], v61 offset0:40 offset1:44
	ds_read2st64_b64 v[86:89], v61 offset0:48 offset1:52
	ds_read2st64_b64 v[90:93], v61 offset0:56 offset1:60
	ds_read2st64_b64 v[94:97], v61 offset0:64 offset1:68
	ds_read2st64_b64 v[98:101], v61 offset0:72 offset1:76
	ds_read2st64_b64 v[102:105], v61 offset0:80 offset1:84
	ds_read2st64_b64 v[106:109], v61 offset0:88 offset1:92
	ds_read2st64_b64 v[110:113], v61 offset0:96 offset1:100
	ds_read2st64_b64 v[114:117], v61 offset0:104 offset1:108
	ds_read2st64_b64 v[118:121], v61 offset0:112 offset1:116
	ds_read2st64_b64 v[122:125], v61 offset0:120 offset1:124
	ds_read_b64 v[128:129], v150
	s_waitcnt vmcnt(30)
	s_waitcnt lgkmcnt(15)
	v_fmac_f32_e32 v30, v170, v62
	v_fmac_f32_e32 v43, v170, v64
	s_waitcnt lgkmcnt(15)
	v_fmac_f32_e32 v42, v170, v66
	v_fmac_f32_e32 v35, v170, v68
	s_waitcnt lgkmcnt(14)
	v_fmac_f32_e32 v34, v170, v70
	v_fmac_f32_e32 v29, v170, v72
	s_waitcnt lgkmcnt(13)
	v_fmac_f32_e32 v28, v170, v74
	v_fmac_f32_e32 v27, v170, v76
	s_waitcnt lgkmcnt(12)
	v_fmac_f32_e32 v26, v170, v78
	v_fmac_f32_e32 v25, v170, v80
	s_waitcnt lgkmcnt(11)
	v_fmac_f32_e32 v24, v170, v82
	v_fmac_f32_e32 v23, v170, v84
	s_waitcnt lgkmcnt(10)
	v_fmac_f32_e32 v22, v170, v86
	v_fmac_f32_e32 v21, v170, v88
	s_waitcnt lgkmcnt(9)
	v_fmac_f32_e32 v20, v170, v90
	v_fmac_f32_e32 v17, v170, v92
	s_waitcnt lgkmcnt(8)
	v_fmac_f32_e32 v16, v170, v94
	v_fmac_f32_e32 v31, v170, v96
	s_waitcnt lgkmcnt(7)
	v_fmac_f32_e32 v32, v170, v98
	v_fmac_f32_e32 v33, v170, v100
	s_waitcnt lgkmcnt(6)
	v_fmac_f32_e32 v36, v170, v102
	v_fmac_f32_e32 v37, v170, v104
	s_waitcnt lgkmcnt(5)
	v_fmac_f32_e32 v38, v170, v106
	v_fmac_f32_e32 v39, v170, v108
	s_waitcnt lgkmcnt(4)
	v_fmac_f32_e32 v40, v170, v110
	v_fmac_f32_e32 v41, v170, v112
	s_waitcnt lgkmcnt(3)
	v_fmac_f32_e32 v44, v170, v114
	v_fmac_f32_e32 v45, v170, v116
	s_waitcnt lgkmcnt(2)
	v_fmac_f32_e32 v46, v170, v118
	v_fmac_f32_e32 v47, v170, v120
	s_waitcnt lgkmcnt(1)
	v_fmac_f32_e32 v48, v170, v122
	v_fmac_f32_e32 v49, v170, v124
	s_waitcnt lgkmcnt(0)
	v_fmac_f32_e32 v60, v170, v128
	v_fmac_f32_e32 v30, v171, v63
	v_fmac_f32_e32 v43, v171, v65
	v_fmac_f32_e32 v42, v171, v67
	v_fmac_f32_e32 v35, v171, v69
	v_fmac_f32_e32 v34, v171, v71
	v_fmac_f32_e32 v29, v171, v73
	v_fmac_f32_e32 v28, v171, v75
	v_fmac_f32_e32 v27, v171, v77
	v_fmac_f32_e32 v26, v171, v79
	v_fmac_f32_e32 v25, v171, v81
	v_fmac_f32_e32 v24, v171, v83
	v_fmac_f32_e32 v23, v171, v85
	v_fmac_f32_e32 v22, v171, v87
	v_fmac_f32_e32 v21, v171, v89
	v_fmac_f32_e32 v20, v171, v91
	v_fmac_f32_e32 v17, v171, v93
	v_fmac_f32_e32 v16, v171, v95
	v_fmac_f32_e32 v31, v171, v97
	v_fmac_f32_e32 v32, v171, v99
	v_fmac_f32_e32 v33, v171, v101
	v_fmac_f32_e32 v36, v171, v103
	v_fmac_f32_e32 v37, v171, v105
	v_fmac_f32_e32 v38, v171, v107
	v_fmac_f32_e32 v39, v171, v109
	v_fmac_f32_e32 v40, v171, v111
	v_fmac_f32_e32 v41, v171, v113
	v_fmac_f32_e32 v44, v171, v115
	v_fmac_f32_e32 v45, v171, v117
	v_fmac_f32_e32 v46, v171, v119
	v_fmac_f32_e32 v47, v171, v121
	v_fmac_f32_e32 v48, v171, v123
	v_fmac_f32_e32 v49, v171, v125
	v_fmac_f32_e32 v60, v171, v129
	global_load_dword v202, v[50:51], off
	v_add_co_u32_e32 v62, vcc, s60, v50
	s_nop 1
	v_addc_co_u32_e32 v63, vcc, 0, v51, vcc
	v_lshl_add_u64 v[50:51], v[50:51], 0, s[24:25]
	global_load_dword v203, v[62:63], off
	v_add_u32_e32 v61, 32, v57
	v_add_u32_e32 v150, 32, v149
	ds_read2st64_b64 v[62:65], v61 offset1:4
	ds_read2st64_b64 v[66:69], v61 offset0:8 offset1:12
	ds_read2st64_b64 v[70:73], v61 offset0:16 offset1:20
	ds_read2st64_b64 v[74:77], v61 offset0:24 offset1:28
	ds_read2st64_b64 v[78:81], v61 offset0:32 offset1:36
	ds_read2st64_b64 v[82:85], v61 offset0:40 offset1:44
	ds_read2st64_b64 v[86:89], v61 offset0:48 offset1:52
	ds_read2st64_b64 v[90:93], v61 offset0:56 offset1:60
	ds_read2st64_b64 v[94:97], v61 offset0:64 offset1:68
	ds_read2st64_b64 v[98:101], v61 offset0:72 offset1:76
	ds_read2st64_b64 v[102:105], v61 offset0:80 offset1:84
	ds_read2st64_b64 v[106:109], v61 offset0:88 offset1:92
	ds_read2st64_b64 v[110:113], v61 offset0:96 offset1:100
	ds_read2st64_b64 v[114:117], v61 offset0:104 offset1:108
	ds_read2st64_b64 v[118:121], v61 offset0:112 offset1:116
	ds_read2st64_b64 v[122:125], v61 offset0:120 offset1:124
	ds_read_b64 v[128:129], v150
	s_waitcnt vmcnt(30)
	s_waitcnt lgkmcnt(15)
	v_fmac_f32_e32 v30, v172, v62
	v_fmac_f32_e32 v43, v172, v64
	s_waitcnt lgkmcnt(15)
	v_fmac_f32_e32 v42, v172, v66
	v_fmac_f32_e32 v35, v172, v68
	s_waitcnt lgkmcnt(14)
	v_fmac_f32_e32 v34, v172, v70
	v_fmac_f32_e32 v29, v172, v72
	s_waitcnt lgkmcnt(13)
	v_fmac_f32_e32 v28, v172, v74
	v_fmac_f32_e32 v27, v172, v76
	s_waitcnt lgkmcnt(12)
	v_fmac_f32_e32 v26, v172, v78
	v_fmac_f32_e32 v25, v172, v80
	s_waitcnt lgkmcnt(11)
	v_fmac_f32_e32 v24, v172, v82
	v_fmac_f32_e32 v23, v172, v84
	s_waitcnt lgkmcnt(10)
	v_fmac_f32_e32 v22, v172, v86
	v_fmac_f32_e32 v21, v172, v88
	s_waitcnt lgkmcnt(9)
	v_fmac_f32_e32 v20, v172, v90
	v_fmac_f32_e32 v17, v172, v92
	s_waitcnt lgkmcnt(8)
	v_fmac_f32_e32 v16, v172, v94
	v_fmac_f32_e32 v31, v172, v96
	s_waitcnt lgkmcnt(7)
	v_fmac_f32_e32 v32, v172, v98
	v_fmac_f32_e32 v33, v172, v100
	s_waitcnt lgkmcnt(6)
	v_fmac_f32_e32 v36, v172, v102
	v_fmac_f32_e32 v37, v172, v104
	s_waitcnt lgkmcnt(5)
	v_fmac_f32_e32 v38, v172, v106
	v_fmac_f32_e32 v39, v172, v108
	s_waitcnt lgkmcnt(4)
	v_fmac_f32_e32 v40, v172, v110
	v_fmac_f32_e32 v41, v172, v112
	s_waitcnt lgkmcnt(3)
	v_fmac_f32_e32 v44, v172, v114
	v_fmac_f32_e32 v45, v172, v116
	s_waitcnt lgkmcnt(2)
	v_fmac_f32_e32 v46, v172, v118
	v_fmac_f32_e32 v47, v172, v120
	s_waitcnt lgkmcnt(1)
	v_fmac_f32_e32 v48, v172, v122
	v_fmac_f32_e32 v49, v172, v124
	s_waitcnt lgkmcnt(0)
	v_fmac_f32_e32 v60, v172, v128
	v_fmac_f32_e32 v30, v173, v63
	v_fmac_f32_e32 v43, v173, v65
	v_fmac_f32_e32 v42, v173, v67
	v_fmac_f32_e32 v35, v173, v69
	v_fmac_f32_e32 v34, v173, v71
	v_fmac_f32_e32 v29, v173, v73
	v_fmac_f32_e32 v28, v173, v75
	v_fmac_f32_e32 v27, v173, v77
	v_fmac_f32_e32 v26, v173, v79
	v_fmac_f32_e32 v25, v173, v81
	v_fmac_f32_e32 v24, v173, v83
	v_fmac_f32_e32 v23, v173, v85
	v_fmac_f32_e32 v22, v173, v87
	v_fmac_f32_e32 v21, v173, v89
	v_fmac_f32_e32 v20, v173, v91
	v_fmac_f32_e32 v17, v173, v93
	v_fmac_f32_e32 v16, v173, v95
	v_fmac_f32_e32 v31, v173, v97
	v_fmac_f32_e32 v32, v173, v99
	v_fmac_f32_e32 v33, v173, v101
	v_fmac_f32_e32 v36, v173, v103
	v_fmac_f32_e32 v37, v173, v105
	v_fmac_f32_e32 v38, v173, v107
	v_fmac_f32_e32 v39, v173, v109
	v_fmac_f32_e32 v40, v173, v111
	v_fmac_f32_e32 v41, v173, v113
	v_fmac_f32_e32 v44, v173, v115
	v_fmac_f32_e32 v45, v173, v117
	v_fmac_f32_e32 v46, v173, v119
	v_fmac_f32_e32 v47, v173, v121
	v_fmac_f32_e32 v48, v173, v123
	v_fmac_f32_e32 v49, v173, v125
	v_fmac_f32_e32 v60, v173, v129
	global_load_dword v204, v[50:51], off
	v_add_co_u32_e32 v62, vcc, s60, v50
	s_nop 1
	v_addc_co_u32_e32 v63, vcc, 0, v51, vcc
	v_lshl_add_u64 v[50:51], v[50:51], 0, s[24:25]
	global_load_dword v205, v[62:63], off
	v_add_u32_e32 v61, 40, v57
	v_add_u32_e32 v150, 40, v149
	ds_read2st64_b64 v[62:65], v61 offset1:4
	ds_read2st64_b64 v[66:69], v61 offset0:8 offset1:12
	ds_read2st64_b64 v[70:73], v61 offset0:16 offset1:20
	ds_read2st64_b64 v[74:77], v61 offset0:24 offset1:28
	ds_read2st64_b64 v[78:81], v61 offset0:32 offset1:36
	ds_read2st64_b64 v[82:85], v61 offset0:40 offset1:44
	ds_read2st64_b64 v[86:89], v61 offset0:48 offset1:52
	ds_read2st64_b64 v[90:93], v61 offset0:56 offset1:60
	ds_read2st64_b64 v[94:97], v61 offset0:64 offset1:68
	ds_read2st64_b64 v[98:101], v61 offset0:72 offset1:76
	ds_read2st64_b64 v[102:105], v61 offset0:80 offset1:84
	ds_read2st64_b64 v[106:109], v61 offset0:88 offset1:92
	ds_read2st64_b64 v[110:113], v61 offset0:96 offset1:100
	ds_read2st64_b64 v[114:117], v61 offset0:104 offset1:108
	ds_read2st64_b64 v[118:121], v61 offset0:112 offset1:116
	ds_read2st64_b64 v[122:125], v61 offset0:120 offset1:124
	ds_read_b64 v[128:129], v150
	s_waitcnt vmcnt(30)
	s_waitcnt lgkmcnt(15)
	v_fmac_f32_e32 v30, v174, v62
	v_fmac_f32_e32 v43, v174, v64
	s_waitcnt lgkmcnt(15)
	v_fmac_f32_e32 v42, v174, v66
	v_fmac_f32_e32 v35, v174, v68
	s_waitcnt lgkmcnt(14)
	v_fmac_f32_e32 v34, v174, v70
	v_fmac_f32_e32 v29, v174, v72
	s_waitcnt lgkmcnt(13)
	v_fmac_f32_e32 v28, v174, v74
	v_fmac_f32_e32 v27, v174, v76
	s_waitcnt lgkmcnt(12)
	v_fmac_f32_e32 v26, v174, v78
	v_fmac_f32_e32 v25, v174, v80
	s_waitcnt lgkmcnt(11)
	v_fmac_f32_e32 v24, v174, v82
	v_fmac_f32_e32 v23, v174, v84
	s_waitcnt lgkmcnt(10)
	v_fmac_f32_e32 v22, v174, v86
	v_fmac_f32_e32 v21, v174, v88
	s_waitcnt lgkmcnt(9)
	v_fmac_f32_e32 v20, v174, v90
	v_fmac_f32_e32 v17, v174, v92
	s_waitcnt lgkmcnt(8)
	v_fmac_f32_e32 v16, v174, v94
	v_fmac_f32_e32 v31, v174, v96
	s_waitcnt lgkmcnt(7)
	v_fmac_f32_e32 v32, v174, v98
	v_fmac_f32_e32 v33, v174, v100
	s_waitcnt lgkmcnt(6)
	v_fmac_f32_e32 v36, v174, v102
	v_fmac_f32_e32 v37, v174, v104
	s_waitcnt lgkmcnt(5)
	v_fmac_f32_e32 v38, v174, v106
	v_fmac_f32_e32 v39, v174, v108
	s_waitcnt lgkmcnt(4)
	v_fmac_f32_e32 v40, v174, v110
	v_fmac_f32_e32 v41, v174, v112
	s_waitcnt lgkmcnt(3)
	v_fmac_f32_e32 v44, v174, v114
	v_fmac_f32_e32 v45, v174, v116
	s_waitcnt lgkmcnt(2)
	v_fmac_f32_e32 v46, v174, v118
	v_fmac_f32_e32 v47, v174, v120
	s_waitcnt lgkmcnt(1)
	v_fmac_f32_e32 v48, v174, v122
	v_fmac_f32_e32 v49, v174, v124
	s_waitcnt lgkmcnt(0)
	v_fmac_f32_e32 v60, v174, v128
	v_fmac_f32_e32 v30, v175, v63
	v_fmac_f32_e32 v43, v175, v65
	v_fmac_f32_e32 v42, v175, v67
	v_fmac_f32_e32 v35, v175, v69
	v_fmac_f32_e32 v34, v175, v71
	v_fmac_f32_e32 v29, v175, v73
	v_fmac_f32_e32 v28, v175, v75
	v_fmac_f32_e32 v27, v175, v77
	v_fmac_f32_e32 v26, v175, v79
	v_fmac_f32_e32 v25, v175, v81
	v_fmac_f32_e32 v24, v175, v83
	v_fmac_f32_e32 v23, v175, v85
	v_fmac_f32_e32 v22, v175, v87
	v_fmac_f32_e32 v21, v175, v89
	v_fmac_f32_e32 v20, v175, v91
	v_fmac_f32_e32 v17, v175, v93
	v_fmac_f32_e32 v16, v175, v95
	v_fmac_f32_e32 v31, v175, v97
	v_fmac_f32_e32 v32, v175, v99
	v_fmac_f32_e32 v33, v175, v101
	v_fmac_f32_e32 v36, v175, v103
	v_fmac_f32_e32 v37, v175, v105
	v_fmac_f32_e32 v38, v175, v107
	v_fmac_f32_e32 v39, v175, v109
	v_fmac_f32_e32 v40, v175, v111
	v_fmac_f32_e32 v41, v175, v113
	v_fmac_f32_e32 v44, v175, v115
	v_fmac_f32_e32 v45, v175, v117
	v_fmac_f32_e32 v46, v175, v119
	v_fmac_f32_e32 v47, v175, v121
	v_fmac_f32_e32 v48, v175, v123
	v_fmac_f32_e32 v49, v175, v125
	v_fmac_f32_e32 v60, v175, v129
	global_load_dword v206, v[50:51], off
	v_add_co_u32_e32 v62, vcc, s60, v50
	s_nop 1
	v_addc_co_u32_e32 v63, vcc, 0, v51, vcc
	v_lshl_add_u64 v[50:51], v[50:51], 0, s[24:25]
	global_load_dword v207, v[62:63], off
	v_add_u32_e32 v61, 48, v57
	v_add_u32_e32 v150, 48, v149
	ds_read2st64_b64 v[62:65], v61 offset1:4
	ds_read2st64_b64 v[66:69], v61 offset0:8 offset1:12
	ds_read2st64_b64 v[70:73], v61 offset0:16 offset1:20
	ds_read2st64_b64 v[74:77], v61 offset0:24 offset1:28
	ds_read2st64_b64 v[78:81], v61 offset0:32 offset1:36
	ds_read2st64_b64 v[82:85], v61 offset0:40 offset1:44
	ds_read2st64_b64 v[86:89], v61 offset0:48 offset1:52
	ds_read2st64_b64 v[90:93], v61 offset0:56 offset1:60
	ds_read2st64_b64 v[94:97], v61 offset0:64 offset1:68
	ds_read2st64_b64 v[98:101], v61 offset0:72 offset1:76
	ds_read2st64_b64 v[102:105], v61 offset0:80 offset1:84
	ds_read2st64_b64 v[106:109], v61 offset0:88 offset1:92
	ds_read2st64_b64 v[110:113], v61 offset0:96 offset1:100
	ds_read2st64_b64 v[114:117], v61 offset0:104 offset1:108
	ds_read2st64_b64 v[118:121], v61 offset0:112 offset1:116
	ds_read2st64_b64 v[122:125], v61 offset0:120 offset1:124
	ds_read_b64 v[128:129], v150
	s_waitcnt vmcnt(30)
	s_waitcnt lgkmcnt(15)
	v_fmac_f32_e32 v30, v176, v62
	v_fmac_f32_e32 v43, v176, v64
	s_waitcnt lgkmcnt(15)
	v_fmac_f32_e32 v42, v176, v66
	v_fmac_f32_e32 v35, v176, v68
	s_waitcnt lgkmcnt(14)
	v_fmac_f32_e32 v34, v176, v70
	v_fmac_f32_e32 v29, v176, v72
	s_waitcnt lgkmcnt(13)
	v_fmac_f32_e32 v28, v176, v74
	v_fmac_f32_e32 v27, v176, v76
	s_waitcnt lgkmcnt(12)
	v_fmac_f32_e32 v26, v176, v78
	v_fmac_f32_e32 v25, v176, v80
	s_waitcnt lgkmcnt(11)
	v_fmac_f32_e32 v24, v176, v82
	v_fmac_f32_e32 v23, v176, v84
	s_waitcnt lgkmcnt(10)
	v_fmac_f32_e32 v22, v176, v86
	v_fmac_f32_e32 v21, v176, v88
	s_waitcnt lgkmcnt(9)
	v_fmac_f32_e32 v20, v176, v90
	v_fmac_f32_e32 v17, v176, v92
	s_waitcnt lgkmcnt(8)
	v_fmac_f32_e32 v16, v176, v94
	v_fmac_f32_e32 v31, v176, v96
	s_waitcnt lgkmcnt(7)
	v_fmac_f32_e32 v32, v176, v98
	v_fmac_f32_e32 v33, v176, v100
	s_waitcnt lgkmcnt(6)
	v_fmac_f32_e32 v36, v176, v102
	v_fmac_f32_e32 v37, v176, v104
	s_waitcnt lgkmcnt(5)
	v_fmac_f32_e32 v38, v176, v106
	v_fmac_f32_e32 v39, v176, v108
	s_waitcnt lgkmcnt(4)
	v_fmac_f32_e32 v40, v176, v110
	v_fmac_f32_e32 v41, v176, v112
	s_waitcnt lgkmcnt(3)
	v_fmac_f32_e32 v44, v176, v114
	v_fmac_f32_e32 v45, v176, v116
	s_waitcnt lgkmcnt(2)
	v_fmac_f32_e32 v46, v176, v118
	v_fmac_f32_e32 v47, v176, v120
	s_waitcnt lgkmcnt(1)
	v_fmac_f32_e32 v48, v176, v122
	v_fmac_f32_e32 v49, v176, v124
	s_waitcnt lgkmcnt(0)
	v_fmac_f32_e32 v60, v176, v128
	v_fmac_f32_e32 v30, v177, v63
	v_fmac_f32_e32 v43, v177, v65
	v_fmac_f32_e32 v42, v177, v67
	v_fmac_f32_e32 v35, v177, v69
	v_fmac_f32_e32 v34, v177, v71
	v_fmac_f32_e32 v29, v177, v73
	v_fmac_f32_e32 v28, v177, v75
	v_fmac_f32_e32 v27, v177, v77
	v_fmac_f32_e32 v26, v177, v79
	v_fmac_f32_e32 v25, v177, v81
	v_fmac_f32_e32 v24, v177, v83
	v_fmac_f32_e32 v23, v177, v85
	v_fmac_f32_e32 v22, v177, v87
	v_fmac_f32_e32 v21, v177, v89
	v_fmac_f32_e32 v20, v177, v91
	v_fmac_f32_e32 v17, v177, v93
	v_fmac_f32_e32 v16, v177, v95
	v_fmac_f32_e32 v31, v177, v97
	v_fmac_f32_e32 v32, v177, v99
	v_fmac_f32_e32 v33, v177, v101
	v_fmac_f32_e32 v36, v177, v103
	v_fmac_f32_e32 v37, v177, v105
	v_fmac_f32_e32 v38, v177, v107
	v_fmac_f32_e32 v39, v177, v109
	v_fmac_f32_e32 v40, v177, v111
	v_fmac_f32_e32 v41, v177, v113
	v_fmac_f32_e32 v44, v177, v115
	v_fmac_f32_e32 v45, v177, v117
	v_fmac_f32_e32 v46, v177, v119
	v_fmac_f32_e32 v47, v177, v121
	v_fmac_f32_e32 v48, v177, v123
	v_fmac_f32_e32 v49, v177, v125
	v_fmac_f32_e32 v60, v177, v129
	global_load_dword v208, v[50:51], off
	v_add_co_u32_e32 v62, vcc, s60, v50
	s_nop 1
	v_addc_co_u32_e32 v63, vcc, 0, v51, vcc
	v_lshl_add_u64 v[50:51], v[50:51], 0, s[24:25]
	global_load_dword v209, v[62:63], off
	v_add_u32_e32 v61, 56, v57
	v_add_u32_e32 v150, 56, v149
	ds_read2st64_b64 v[62:65], v61 offset1:4
	ds_read2st64_b64 v[66:69], v61 offset0:8 offset1:12
	ds_read2st64_b64 v[70:73], v61 offset0:16 offset1:20
	ds_read2st64_b64 v[74:77], v61 offset0:24 offset1:28
	ds_read2st64_b64 v[78:81], v61 offset0:32 offset1:36
	ds_read2st64_b64 v[82:85], v61 offset0:40 offset1:44
	ds_read2st64_b64 v[86:89], v61 offset0:48 offset1:52
	ds_read2st64_b64 v[90:93], v61 offset0:56 offset1:60
	ds_read2st64_b64 v[94:97], v61 offset0:64 offset1:68
	ds_read2st64_b64 v[98:101], v61 offset0:72 offset1:76
	ds_read2st64_b64 v[102:105], v61 offset0:80 offset1:84
	ds_read2st64_b64 v[106:109], v61 offset0:88 offset1:92
	ds_read2st64_b64 v[110:113], v61 offset0:96 offset1:100
	ds_read2st64_b64 v[114:117], v61 offset0:104 offset1:108
	ds_read2st64_b64 v[118:121], v61 offset0:112 offset1:116
	ds_read2st64_b64 v[122:125], v61 offset0:120 offset1:124
	ds_read_b64 v[128:129], v150
	s_waitcnt vmcnt(30)
	s_waitcnt lgkmcnt(15)
	v_fmac_f32_e32 v30, v178, v62
	v_fmac_f32_e32 v43, v178, v64
	s_waitcnt lgkmcnt(15)
	v_fmac_f32_e32 v42, v178, v66
	v_fmac_f32_e32 v35, v178, v68
	s_waitcnt lgkmcnt(14)
	v_fmac_f32_e32 v34, v178, v70
	v_fmac_f32_e32 v29, v178, v72
	s_waitcnt lgkmcnt(13)
	v_fmac_f32_e32 v28, v178, v74
	v_fmac_f32_e32 v27, v178, v76
	s_waitcnt lgkmcnt(12)
	v_fmac_f32_e32 v26, v178, v78
	v_fmac_f32_e32 v25, v178, v80
	s_waitcnt lgkmcnt(11)
	v_fmac_f32_e32 v24, v178, v82
	v_fmac_f32_e32 v23, v178, v84
	s_waitcnt lgkmcnt(10)
	v_fmac_f32_e32 v22, v178, v86
	v_fmac_f32_e32 v21, v178, v88
	s_waitcnt lgkmcnt(9)
	v_fmac_f32_e32 v20, v178, v90
	v_fmac_f32_e32 v17, v178, v92
	s_waitcnt lgkmcnt(8)
	v_fmac_f32_e32 v16, v178, v94
	v_fmac_f32_e32 v31, v178, v96
	s_waitcnt lgkmcnt(7)
	v_fmac_f32_e32 v32, v178, v98
	v_fmac_f32_e32 v33, v178, v100
	s_waitcnt lgkmcnt(6)
	v_fmac_f32_e32 v36, v178, v102
	v_fmac_f32_e32 v37, v178, v104
	s_waitcnt lgkmcnt(5)
	v_fmac_f32_e32 v38, v178, v106
	v_fmac_f32_e32 v39, v178, v108
	s_waitcnt lgkmcnt(4)
	v_fmac_f32_e32 v40, v178, v110
	v_fmac_f32_e32 v41, v178, v112
	s_waitcnt lgkmcnt(3)
	v_fmac_f32_e32 v44, v178, v114
	v_fmac_f32_e32 v45, v178, v116
	s_waitcnt lgkmcnt(2)
	v_fmac_f32_e32 v46, v178, v118
	v_fmac_f32_e32 v47, v178, v120
	s_waitcnt lgkmcnt(1)
	v_fmac_f32_e32 v48, v178, v122
	v_fmac_f32_e32 v49, v178, v124
	s_waitcnt lgkmcnt(0)
	v_fmac_f32_e32 v60, v178, v128
	v_fmac_f32_e32 v30, v179, v63
	v_fmac_f32_e32 v43, v179, v65
	v_fmac_f32_e32 v42, v179, v67
	v_fmac_f32_e32 v35, v179, v69
	v_fmac_f32_e32 v34, v179, v71
	v_fmac_f32_e32 v29, v179, v73
	v_fmac_f32_e32 v28, v179, v75
	v_fmac_f32_e32 v27, v179, v77
	v_fmac_f32_e32 v26, v179, v79
	v_fmac_f32_e32 v25, v179, v81
	v_fmac_f32_e32 v24, v179, v83
	v_fmac_f32_e32 v23, v179, v85
	v_fmac_f32_e32 v22, v179, v87
	v_fmac_f32_e32 v21, v179, v89
	v_fmac_f32_e32 v20, v179, v91
	v_fmac_f32_e32 v17, v179, v93
	v_fmac_f32_e32 v16, v179, v95
	v_fmac_f32_e32 v31, v179, v97
	v_fmac_f32_e32 v32, v179, v99
	v_fmac_f32_e32 v33, v179, v101
	v_fmac_f32_e32 v36, v179, v103
	v_fmac_f32_e32 v37, v179, v105
	v_fmac_f32_e32 v38, v179, v107
	v_fmac_f32_e32 v39, v179, v109
	v_fmac_f32_e32 v40, v179, v111
	v_fmac_f32_e32 v41, v179, v113
	v_fmac_f32_e32 v44, v179, v115
	v_fmac_f32_e32 v45, v179, v117
	v_fmac_f32_e32 v46, v179, v119
	v_fmac_f32_e32 v47, v179, v121
	v_fmac_f32_e32 v48, v179, v123
	v_fmac_f32_e32 v49, v179, v125
	v_fmac_f32_e32 v60, v179, v129
	global_load_dword v210, v[50:51], off
	v_add_co_u32_e32 v62, vcc, s60, v50
	s_nop 1
	v_addc_co_u32_e32 v63, vcc, 0, v51, vcc
	v_lshl_add_u64 v[50:51], v[50:51], 0, s[24:25]
	global_load_dword v212, v[62:63], off
	v_add_u32_e32 v61, 64, v57
	v_add_u32_e32 v150, 64, v149
	ds_read2st64_b64 v[62:65], v61 offset1:4
	ds_read2st64_b64 v[66:69], v61 offset0:8 offset1:12
	ds_read2st64_b64 v[70:73], v61 offset0:16 offset1:20
	ds_read2st64_b64 v[74:77], v61 offset0:24 offset1:28
	ds_read2st64_b64 v[78:81], v61 offset0:32 offset1:36
	ds_read2st64_b64 v[82:85], v61 offset0:40 offset1:44
	ds_read2st64_b64 v[86:89], v61 offset0:48 offset1:52
	ds_read2st64_b64 v[90:93], v61 offset0:56 offset1:60
	ds_read2st64_b64 v[94:97], v61 offset0:64 offset1:68
	ds_read2st64_b64 v[98:101], v61 offset0:72 offset1:76
	ds_read2st64_b64 v[102:105], v61 offset0:80 offset1:84
	ds_read2st64_b64 v[106:109], v61 offset0:88 offset1:92
	ds_read2st64_b64 v[110:113], v61 offset0:96 offset1:100
	ds_read2st64_b64 v[114:117], v61 offset0:104 offset1:108
	ds_read2st64_b64 v[118:121], v61 offset0:112 offset1:116
	ds_read2st64_b64 v[122:125], v61 offset0:120 offset1:124
	ds_read_b64 v[128:129], v150
	s_waitcnt vmcnt(30)
	s_waitcnt lgkmcnt(15)
	v_fmac_f32_e32 v30, v180, v62
	v_fmac_f32_e32 v43, v180, v64
	s_waitcnt lgkmcnt(15)
	v_fmac_f32_e32 v42, v180, v66
	v_fmac_f32_e32 v35, v180, v68
	s_waitcnt lgkmcnt(14)
	v_fmac_f32_e32 v34, v180, v70
	v_fmac_f32_e32 v29, v180, v72
	s_waitcnt lgkmcnt(13)
	v_fmac_f32_e32 v28, v180, v74
	v_fmac_f32_e32 v27, v180, v76
	s_waitcnt lgkmcnt(12)
	v_fmac_f32_e32 v26, v180, v78
	v_fmac_f32_e32 v25, v180, v80
	s_waitcnt lgkmcnt(11)
	v_fmac_f32_e32 v24, v180, v82
	v_fmac_f32_e32 v23, v180, v84
	s_waitcnt lgkmcnt(10)
	v_fmac_f32_e32 v22, v180, v86
	v_fmac_f32_e32 v21, v180, v88
	s_waitcnt lgkmcnt(9)
	v_fmac_f32_e32 v20, v180, v90
	v_fmac_f32_e32 v17, v180, v92
	s_waitcnt lgkmcnt(8)
	v_fmac_f32_e32 v16, v180, v94
	v_fmac_f32_e32 v31, v180, v96
	s_waitcnt lgkmcnt(7)
	v_fmac_f32_e32 v32, v180, v98
	v_fmac_f32_e32 v33, v180, v100
	s_waitcnt lgkmcnt(6)
	v_fmac_f32_e32 v36, v180, v102
	v_fmac_f32_e32 v37, v180, v104
	s_waitcnt lgkmcnt(5)
	v_fmac_f32_e32 v38, v180, v106
	v_fmac_f32_e32 v39, v180, v108
	s_waitcnt lgkmcnt(4)
	v_fmac_f32_e32 v40, v180, v110
	v_fmac_f32_e32 v41, v180, v112
	s_waitcnt lgkmcnt(3)
	v_fmac_f32_e32 v44, v180, v114
	v_fmac_f32_e32 v45, v180, v116
	s_waitcnt lgkmcnt(2)
	v_fmac_f32_e32 v46, v180, v118
	v_fmac_f32_e32 v47, v180, v120
	s_waitcnt lgkmcnt(1)
	v_fmac_f32_e32 v48, v180, v122
	v_fmac_f32_e32 v49, v180, v124
	s_waitcnt lgkmcnt(0)
	v_fmac_f32_e32 v60, v180, v128
	v_fmac_f32_e32 v30, v181, v63
	v_fmac_f32_e32 v43, v181, v65
	v_fmac_f32_e32 v42, v181, v67
	v_fmac_f32_e32 v35, v181, v69
	v_fmac_f32_e32 v34, v181, v71
	v_fmac_f32_e32 v29, v181, v73
	v_fmac_f32_e32 v28, v181, v75
	v_fmac_f32_e32 v27, v181, v77
	v_fmac_f32_e32 v26, v181, v79
	v_fmac_f32_e32 v25, v181, v81
	v_fmac_f32_e32 v24, v181, v83
	v_fmac_f32_e32 v23, v181, v85
	v_fmac_f32_e32 v22, v181, v87
	v_fmac_f32_e32 v21, v181, v89
	v_fmac_f32_e32 v20, v181, v91
	v_fmac_f32_e32 v17, v181, v93
	v_fmac_f32_e32 v16, v181, v95
	v_fmac_f32_e32 v31, v181, v97
	v_fmac_f32_e32 v32, v181, v99
	v_fmac_f32_e32 v33, v181, v101
	v_fmac_f32_e32 v36, v181, v103
	v_fmac_f32_e32 v37, v181, v105
	v_fmac_f32_e32 v38, v181, v107
	v_fmac_f32_e32 v39, v181, v109
	v_fmac_f32_e32 v40, v181, v111
	v_fmac_f32_e32 v41, v181, v113
	v_fmac_f32_e32 v44, v181, v115
	v_fmac_f32_e32 v45, v181, v117
	v_fmac_f32_e32 v46, v181, v119
	v_fmac_f32_e32 v47, v181, v121
	v_fmac_f32_e32 v48, v181, v123
	v_fmac_f32_e32 v49, v181, v125
	v_fmac_f32_e32 v60, v181, v129
	global_load_dword v213, v[50:51], off
	v_add_co_u32_e32 v62, vcc, s60, v50
	s_nop 1
	v_addc_co_u32_e32 v63, vcc, 0, v51, vcc
	v_lshl_add_u64 v[50:51], v[50:51], 0, s[24:25]
	global_load_dword v214, v[62:63], off
	v_add_u32_e32 v61, 72, v57
	v_add_u32_e32 v150, 72, v149
	ds_read2st64_b64 v[62:65], v61 offset1:4
	ds_read2st64_b64 v[66:69], v61 offset0:8 offset1:12
	ds_read2st64_b64 v[70:73], v61 offset0:16 offset1:20
	ds_read2st64_b64 v[74:77], v61 offset0:24 offset1:28
	ds_read2st64_b64 v[78:81], v61 offset0:32 offset1:36
	ds_read2st64_b64 v[82:85], v61 offset0:40 offset1:44
	ds_read2st64_b64 v[86:89], v61 offset0:48 offset1:52
	ds_read2st64_b64 v[90:93], v61 offset0:56 offset1:60
	ds_read2st64_b64 v[94:97], v61 offset0:64 offset1:68
	ds_read2st64_b64 v[98:101], v61 offset0:72 offset1:76
	ds_read2st64_b64 v[102:105], v61 offset0:80 offset1:84
	ds_read2st64_b64 v[106:109], v61 offset0:88 offset1:92
	ds_read2st64_b64 v[110:113], v61 offset0:96 offset1:100
	ds_read2st64_b64 v[114:117], v61 offset0:104 offset1:108
	ds_read2st64_b64 v[118:121], v61 offset0:112 offset1:116
	ds_read2st64_b64 v[122:125], v61 offset0:120 offset1:124
	ds_read_b64 v[128:129], v150
	s_waitcnt vmcnt(30)
	s_waitcnt lgkmcnt(15)
	v_fmac_f32_e32 v30, v182, v62
	v_fmac_f32_e32 v43, v182, v64
	s_waitcnt lgkmcnt(15)
	v_fmac_f32_e32 v42, v182, v66
	v_fmac_f32_e32 v35, v182, v68
	s_waitcnt lgkmcnt(14)
	v_fmac_f32_e32 v34, v182, v70
	v_fmac_f32_e32 v29, v182, v72
	s_waitcnt lgkmcnt(13)
	v_fmac_f32_e32 v28, v182, v74
	v_fmac_f32_e32 v27, v182, v76
	s_waitcnt lgkmcnt(12)
	v_fmac_f32_e32 v26, v182, v78
	v_fmac_f32_e32 v25, v182, v80
	s_waitcnt lgkmcnt(11)
	v_fmac_f32_e32 v24, v182, v82
	v_fmac_f32_e32 v23, v182, v84
	s_waitcnt lgkmcnt(10)
	v_fmac_f32_e32 v22, v182, v86
	v_fmac_f32_e32 v21, v182, v88
	s_waitcnt lgkmcnt(9)
	v_fmac_f32_e32 v20, v182, v90
	v_fmac_f32_e32 v17, v182, v92
	s_waitcnt lgkmcnt(8)
	v_fmac_f32_e32 v16, v182, v94
	v_fmac_f32_e32 v31, v182, v96
	s_waitcnt lgkmcnt(7)
	v_fmac_f32_e32 v32, v182, v98
	v_fmac_f32_e32 v33, v182, v100
	s_waitcnt lgkmcnt(6)
	v_fmac_f32_e32 v36, v182, v102
	v_fmac_f32_e32 v37, v182, v104
	s_waitcnt lgkmcnt(5)
	v_fmac_f32_e32 v38, v182, v106
	v_fmac_f32_e32 v39, v182, v108
	s_waitcnt lgkmcnt(4)
	v_fmac_f32_e32 v40, v182, v110
	v_fmac_f32_e32 v41, v182, v112
	s_waitcnt lgkmcnt(3)
	v_fmac_f32_e32 v44, v182, v114
	v_fmac_f32_e32 v45, v182, v116
	s_waitcnt lgkmcnt(2)
	v_fmac_f32_e32 v46, v182, v118
	v_fmac_f32_e32 v47, v182, v120
	s_waitcnt lgkmcnt(1)
	v_fmac_f32_e32 v48, v182, v122
	v_fmac_f32_e32 v49, v182, v124
	s_waitcnt lgkmcnt(0)
	v_fmac_f32_e32 v60, v182, v128
	v_fmac_f32_e32 v30, v183, v63
	v_fmac_f32_e32 v43, v183, v65
	v_fmac_f32_e32 v42, v183, v67
	v_fmac_f32_e32 v35, v183, v69
	v_fmac_f32_e32 v34, v183, v71
	v_fmac_f32_e32 v29, v183, v73
	v_fmac_f32_e32 v28, v183, v75
	v_fmac_f32_e32 v27, v183, v77
	v_fmac_f32_e32 v26, v183, v79
	v_fmac_f32_e32 v25, v183, v81
	v_fmac_f32_e32 v24, v183, v83
	v_fmac_f32_e32 v23, v183, v85
	v_fmac_f32_e32 v22, v183, v87
	v_fmac_f32_e32 v21, v183, v89
	v_fmac_f32_e32 v20, v183, v91
	v_fmac_f32_e32 v17, v183, v93
	v_fmac_f32_e32 v16, v183, v95
	v_fmac_f32_e32 v31, v183, v97
	v_fmac_f32_e32 v32, v183, v99
	v_fmac_f32_e32 v33, v183, v101
	v_fmac_f32_e32 v36, v183, v103
	v_fmac_f32_e32 v37, v183, v105
	v_fmac_f32_e32 v38, v183, v107
	v_fmac_f32_e32 v39, v183, v109
	v_fmac_f32_e32 v40, v183, v111
	v_fmac_f32_e32 v41, v183, v113
	v_fmac_f32_e32 v44, v183, v115
	v_fmac_f32_e32 v45, v183, v117
	v_fmac_f32_e32 v46, v183, v119
	v_fmac_f32_e32 v47, v183, v121
	v_fmac_f32_e32 v48, v183, v123
	v_fmac_f32_e32 v49, v183, v125
	v_fmac_f32_e32 v60, v183, v129
	global_load_dword v215, v[50:51], off
	v_add_co_u32_e32 v62, vcc, s60, v50
	s_nop 1
	v_addc_co_u32_e32 v63, vcc, 0, v51, vcc
	v_lshl_add_u64 v[50:51], v[50:51], 0, s[24:25]
	global_load_dword v216, v[62:63], off
	v_add_u32_e32 v61, 80, v57
	v_add_u32_e32 v150, 80, v149
	ds_read2st64_b64 v[62:65], v61 offset1:4
	ds_read2st64_b64 v[66:69], v61 offset0:8 offset1:12
	ds_read2st64_b64 v[70:73], v61 offset0:16 offset1:20
	ds_read2st64_b64 v[74:77], v61 offset0:24 offset1:28
	ds_read2st64_b64 v[78:81], v61 offset0:32 offset1:36
	ds_read2st64_b64 v[82:85], v61 offset0:40 offset1:44
	ds_read2st64_b64 v[86:89], v61 offset0:48 offset1:52
	ds_read2st64_b64 v[90:93], v61 offset0:56 offset1:60
	ds_read2st64_b64 v[94:97], v61 offset0:64 offset1:68
	ds_read2st64_b64 v[98:101], v61 offset0:72 offset1:76
	ds_read2st64_b64 v[102:105], v61 offset0:80 offset1:84
	ds_read2st64_b64 v[106:109], v61 offset0:88 offset1:92
	ds_read2st64_b64 v[110:113], v61 offset0:96 offset1:100
	ds_read2st64_b64 v[114:117], v61 offset0:104 offset1:108
	ds_read2st64_b64 v[118:121], v61 offset0:112 offset1:116
	ds_read2st64_b64 v[122:125], v61 offset0:120 offset1:124
	ds_read_b64 v[128:129], v150
	s_waitcnt vmcnt(30)
	s_waitcnt lgkmcnt(15)
	v_fmac_f32_e32 v30, v184, v62
	v_fmac_f32_e32 v43, v184, v64
	s_waitcnt lgkmcnt(15)
	v_fmac_f32_e32 v42, v184, v66
	v_fmac_f32_e32 v35, v184, v68
	s_waitcnt lgkmcnt(14)
	v_fmac_f32_e32 v34, v184, v70
	v_fmac_f32_e32 v29, v184, v72
	s_waitcnt lgkmcnt(13)
	v_fmac_f32_e32 v28, v184, v74
	v_fmac_f32_e32 v27, v184, v76
	s_waitcnt lgkmcnt(12)
	v_fmac_f32_e32 v26, v184, v78
	v_fmac_f32_e32 v25, v184, v80
	s_waitcnt lgkmcnt(11)
	v_fmac_f32_e32 v24, v184, v82
	v_fmac_f32_e32 v23, v184, v84
	s_waitcnt lgkmcnt(10)
	v_fmac_f32_e32 v22, v184, v86
	v_fmac_f32_e32 v21, v184, v88
	s_waitcnt lgkmcnt(9)
	v_fmac_f32_e32 v20, v184, v90
	v_fmac_f32_e32 v17, v184, v92
	s_waitcnt lgkmcnt(8)
	v_fmac_f32_e32 v16, v184, v94
	v_fmac_f32_e32 v31, v184, v96
	s_waitcnt lgkmcnt(7)
	v_fmac_f32_e32 v32, v184, v98
	v_fmac_f32_e32 v33, v184, v100
	s_waitcnt lgkmcnt(6)
	v_fmac_f32_e32 v36, v184, v102
	v_fmac_f32_e32 v37, v184, v104
	s_waitcnt lgkmcnt(5)
	v_fmac_f32_e32 v38, v184, v106
	v_fmac_f32_e32 v39, v184, v108
	s_waitcnt lgkmcnt(4)
	v_fmac_f32_e32 v40, v184, v110
	v_fmac_f32_e32 v41, v184, v112
	s_waitcnt lgkmcnt(3)
	v_fmac_f32_e32 v44, v184, v114
	v_fmac_f32_e32 v45, v184, v116
	s_waitcnt lgkmcnt(2)
	v_fmac_f32_e32 v46, v184, v118
	v_fmac_f32_e32 v47, v184, v120
	s_waitcnt lgkmcnt(1)
	v_fmac_f32_e32 v48, v184, v122
	v_fmac_f32_e32 v49, v184, v124
	s_waitcnt lgkmcnt(0)
	v_fmac_f32_e32 v60, v184, v128
	v_fmac_f32_e32 v30, v185, v63
	v_fmac_f32_e32 v43, v185, v65
	v_fmac_f32_e32 v42, v185, v67
	v_fmac_f32_e32 v35, v185, v69
	v_fmac_f32_e32 v34, v185, v71
	v_fmac_f32_e32 v29, v185, v73
	v_fmac_f32_e32 v28, v185, v75
	v_fmac_f32_e32 v27, v185, v77
	v_fmac_f32_e32 v26, v185, v79
	v_fmac_f32_e32 v25, v185, v81
	v_fmac_f32_e32 v24, v185, v83
	v_fmac_f32_e32 v23, v185, v85
	v_fmac_f32_e32 v22, v185, v87
	v_fmac_f32_e32 v21, v185, v89
	v_fmac_f32_e32 v20, v185, v91
	v_fmac_f32_e32 v17, v185, v93
	v_fmac_f32_e32 v16, v185, v95
	v_fmac_f32_e32 v31, v185, v97
	v_fmac_f32_e32 v32, v185, v99
	v_fmac_f32_e32 v33, v185, v101
	v_fmac_f32_e32 v36, v185, v103
	v_fmac_f32_e32 v37, v185, v105
	v_fmac_f32_e32 v38, v185, v107
	v_fmac_f32_e32 v39, v185, v109
	v_fmac_f32_e32 v40, v185, v111
	v_fmac_f32_e32 v41, v185, v113
	v_fmac_f32_e32 v44, v185, v115
	v_fmac_f32_e32 v45, v185, v117
	v_fmac_f32_e32 v46, v185, v119
	v_fmac_f32_e32 v47, v185, v121
	v_fmac_f32_e32 v48, v185, v123
	v_fmac_f32_e32 v49, v185, v125
	v_fmac_f32_e32 v60, v185, v129
	global_load_dword v217, v[50:51], off
	v_add_co_u32_e32 v62, vcc, s60, v50
	s_nop 1
	v_addc_co_u32_e32 v63, vcc, 0, v51, vcc
	v_lshl_add_u64 v[50:51], v[50:51], 0, s[24:25]
	global_load_dword v218, v[62:63], off
	v_add_u32_e32 v61, 88, v57
	v_add_u32_e32 v150, 88, v149
	ds_read2st64_b64 v[62:65], v61 offset1:4
	ds_read2st64_b64 v[66:69], v61 offset0:8 offset1:12
	ds_read2st64_b64 v[70:73], v61 offset0:16 offset1:20
	ds_read2st64_b64 v[74:77], v61 offset0:24 offset1:28
	ds_read2st64_b64 v[78:81], v61 offset0:32 offset1:36
	ds_read2st64_b64 v[82:85], v61 offset0:40 offset1:44
	ds_read2st64_b64 v[86:89], v61 offset0:48 offset1:52
	ds_read2st64_b64 v[90:93], v61 offset0:56 offset1:60
	ds_read2st64_b64 v[94:97], v61 offset0:64 offset1:68
	ds_read2st64_b64 v[98:101], v61 offset0:72 offset1:76
	ds_read2st64_b64 v[102:105], v61 offset0:80 offset1:84
	ds_read2st64_b64 v[106:109], v61 offset0:88 offset1:92
	ds_read2st64_b64 v[110:113], v61 offset0:96 offset1:100
	ds_read2st64_b64 v[114:117], v61 offset0:104 offset1:108
	ds_read2st64_b64 v[118:121], v61 offset0:112 offset1:116
	ds_read2st64_b64 v[122:125], v61 offset0:120 offset1:124
	ds_read_b64 v[128:129], v150
	s_waitcnt vmcnt(30)
	s_waitcnt lgkmcnt(15)
	v_fmac_f32_e32 v30, v186, v62
	v_fmac_f32_e32 v43, v186, v64
	s_waitcnt lgkmcnt(15)
	v_fmac_f32_e32 v42, v186, v66
	v_fmac_f32_e32 v35, v186, v68
	s_waitcnt lgkmcnt(14)
	v_fmac_f32_e32 v34, v186, v70
	v_fmac_f32_e32 v29, v186, v72
	s_waitcnt lgkmcnt(13)
	v_fmac_f32_e32 v28, v186, v74
	v_fmac_f32_e32 v27, v186, v76
	s_waitcnt lgkmcnt(12)
	v_fmac_f32_e32 v26, v186, v78
	v_fmac_f32_e32 v25, v186, v80
	s_waitcnt lgkmcnt(11)
	v_fmac_f32_e32 v24, v186, v82
	v_fmac_f32_e32 v23, v186, v84
	s_waitcnt lgkmcnt(10)
	v_fmac_f32_e32 v22, v186, v86
	v_fmac_f32_e32 v21, v186, v88
	s_waitcnt lgkmcnt(9)
	v_fmac_f32_e32 v20, v186, v90
	v_fmac_f32_e32 v17, v186, v92
	s_waitcnt lgkmcnt(8)
	v_fmac_f32_e32 v16, v186, v94
	v_fmac_f32_e32 v31, v186, v96
	s_waitcnt lgkmcnt(7)
	v_fmac_f32_e32 v32, v186, v98
	v_fmac_f32_e32 v33, v186, v100
	s_waitcnt lgkmcnt(6)
	v_fmac_f32_e32 v36, v186, v102
	v_fmac_f32_e32 v37, v186, v104
	s_waitcnt lgkmcnt(5)
	v_fmac_f32_e32 v38, v186, v106
	v_fmac_f32_e32 v39, v186, v108
	s_waitcnt lgkmcnt(4)
	v_fmac_f32_e32 v40, v186, v110
	v_fmac_f32_e32 v41, v186, v112
	s_waitcnt lgkmcnt(3)
	v_fmac_f32_e32 v44, v186, v114
	v_fmac_f32_e32 v45, v186, v116
	s_waitcnt lgkmcnt(2)
	v_fmac_f32_e32 v46, v186, v118
	v_fmac_f32_e32 v47, v186, v120
	s_waitcnt lgkmcnt(1)
	v_fmac_f32_e32 v48, v186, v122
	v_fmac_f32_e32 v49, v186, v124
	s_waitcnt lgkmcnt(0)
	v_fmac_f32_e32 v60, v186, v128
	v_fmac_f32_e32 v30, v187, v63
	v_fmac_f32_e32 v43, v187, v65
	v_fmac_f32_e32 v42, v187, v67
	v_fmac_f32_e32 v35, v187, v69
	v_fmac_f32_e32 v34, v187, v71
	v_fmac_f32_e32 v29, v187, v73
	v_fmac_f32_e32 v28, v187, v75
	v_fmac_f32_e32 v27, v187, v77
	v_fmac_f32_e32 v26, v187, v79
	v_fmac_f32_e32 v25, v187, v81
	v_fmac_f32_e32 v24, v187, v83
	v_fmac_f32_e32 v23, v187, v85
	v_fmac_f32_e32 v22, v187, v87
	v_fmac_f32_e32 v21, v187, v89
	v_fmac_f32_e32 v20, v187, v91
	v_fmac_f32_e32 v17, v187, v93
	v_fmac_f32_e32 v16, v187, v95
	v_fmac_f32_e32 v31, v187, v97
	v_fmac_f32_e32 v32, v187, v99
	v_fmac_f32_e32 v33, v187, v101
	v_fmac_f32_e32 v36, v187, v103
	v_fmac_f32_e32 v37, v187, v105
	v_fmac_f32_e32 v38, v187, v107
	v_fmac_f32_e32 v39, v187, v109
	v_fmac_f32_e32 v40, v187, v111
	v_fmac_f32_e32 v41, v187, v113
	v_fmac_f32_e32 v44, v187, v115
	v_fmac_f32_e32 v45, v187, v117
	v_fmac_f32_e32 v46, v187, v119
	v_fmac_f32_e32 v47, v187, v121
	v_fmac_f32_e32 v48, v187, v123
	v_fmac_f32_e32 v49, v187, v125
	v_fmac_f32_e32 v60, v187, v129
	global_load_dword v219, v[50:51], off
	v_add_co_u32_e32 v62, vcc, s60, v50
	s_nop 1
	v_addc_co_u32_e32 v63, vcc, 0, v51, vcc
	v_lshl_add_u64 v[50:51], v[50:51], 0, s[24:25]
	global_load_dword v220, v[62:63], off
	v_add_u32_e32 v61, 96, v57
	v_add_u32_e32 v150, 96, v149
	ds_read2st64_b64 v[62:65], v61 offset1:4
	ds_read2st64_b64 v[66:69], v61 offset0:8 offset1:12
	ds_read2st64_b64 v[70:73], v61 offset0:16 offset1:20
	ds_read2st64_b64 v[74:77], v61 offset0:24 offset1:28
	ds_read2st64_b64 v[78:81], v61 offset0:32 offset1:36
	ds_read2st64_b64 v[82:85], v61 offset0:40 offset1:44
	ds_read2st64_b64 v[86:89], v61 offset0:48 offset1:52
	ds_read2st64_b64 v[90:93], v61 offset0:56 offset1:60
	ds_read2st64_b64 v[94:97], v61 offset0:64 offset1:68
	ds_read2st64_b64 v[98:101], v61 offset0:72 offset1:76
	ds_read2st64_b64 v[102:105], v61 offset0:80 offset1:84
	ds_read2st64_b64 v[106:109], v61 offset0:88 offset1:92
	ds_read2st64_b64 v[110:113], v61 offset0:96 offset1:100
	ds_read2st64_b64 v[114:117], v61 offset0:104 offset1:108
	ds_read2st64_b64 v[118:121], v61 offset0:112 offset1:116
	ds_read2st64_b64 v[122:125], v61 offset0:120 offset1:124
	ds_read_b64 v[128:129], v150
	s_waitcnt vmcnt(30)
	s_waitcnt lgkmcnt(15)
	v_fmac_f32_e32 v30, v188, v62
	v_fmac_f32_e32 v43, v188, v64
	s_waitcnt lgkmcnt(15)
	v_fmac_f32_e32 v42, v188, v66
	v_fmac_f32_e32 v35, v188, v68
	s_waitcnt lgkmcnt(14)
	v_fmac_f32_e32 v34, v188, v70
	v_fmac_f32_e32 v29, v188, v72
	s_waitcnt lgkmcnt(13)
	v_fmac_f32_e32 v28, v188, v74
	v_fmac_f32_e32 v27, v188, v76
	s_waitcnt lgkmcnt(12)
	v_fmac_f32_e32 v26, v188, v78
	v_fmac_f32_e32 v25, v188, v80
	s_waitcnt lgkmcnt(11)
	v_fmac_f32_e32 v24, v188, v82
	v_fmac_f32_e32 v23, v188, v84
	s_waitcnt lgkmcnt(10)
	v_fmac_f32_e32 v22, v188, v86
	v_fmac_f32_e32 v21, v188, v88
	s_waitcnt lgkmcnt(9)
	v_fmac_f32_e32 v20, v188, v90
	v_fmac_f32_e32 v17, v188, v92
	s_waitcnt lgkmcnt(8)
	v_fmac_f32_e32 v16, v188, v94
	v_fmac_f32_e32 v31, v188, v96
	s_waitcnt lgkmcnt(7)
	v_fmac_f32_e32 v32, v188, v98
	v_fmac_f32_e32 v33, v188, v100
	s_waitcnt lgkmcnt(6)
	v_fmac_f32_e32 v36, v188, v102
	v_fmac_f32_e32 v37, v188, v104
	s_waitcnt lgkmcnt(5)
	v_fmac_f32_e32 v38, v188, v106
	v_fmac_f32_e32 v39, v188, v108
	s_waitcnt lgkmcnt(4)
	v_fmac_f32_e32 v40, v188, v110
	v_fmac_f32_e32 v41, v188, v112
	s_waitcnt lgkmcnt(3)
	v_fmac_f32_e32 v44, v188, v114
	v_fmac_f32_e32 v45, v188, v116
	s_waitcnt lgkmcnt(2)
	v_fmac_f32_e32 v46, v188, v118
	v_fmac_f32_e32 v47, v188, v120
	s_waitcnt lgkmcnt(1)
	v_fmac_f32_e32 v48, v188, v122
	v_fmac_f32_e32 v49, v188, v124
	s_waitcnt lgkmcnt(0)
	v_fmac_f32_e32 v60, v188, v128
	v_fmac_f32_e32 v30, v189, v63
	v_fmac_f32_e32 v43, v189, v65
	v_fmac_f32_e32 v42, v189, v67
	v_fmac_f32_e32 v35, v189, v69
	v_fmac_f32_e32 v34, v189, v71
	v_fmac_f32_e32 v29, v189, v73
	v_fmac_f32_e32 v28, v189, v75
	v_fmac_f32_e32 v27, v189, v77
	v_fmac_f32_e32 v26, v189, v79
	v_fmac_f32_e32 v25, v189, v81
	v_fmac_f32_e32 v24, v189, v83
	v_fmac_f32_e32 v23, v189, v85
	v_fmac_f32_e32 v22, v189, v87
	v_fmac_f32_e32 v21, v189, v89
	v_fmac_f32_e32 v20, v189, v91
	v_fmac_f32_e32 v17, v189, v93
	v_fmac_f32_e32 v16, v189, v95
	v_fmac_f32_e32 v31, v189, v97
	v_fmac_f32_e32 v32, v189, v99
	v_fmac_f32_e32 v33, v189, v101
	v_fmac_f32_e32 v36, v189, v103
	v_fmac_f32_e32 v37, v189, v105
	v_fmac_f32_e32 v38, v189, v107
	v_fmac_f32_e32 v39, v189, v109
	v_fmac_f32_e32 v40, v189, v111
	v_fmac_f32_e32 v41, v189, v113
	v_fmac_f32_e32 v44, v189, v115
	v_fmac_f32_e32 v45, v189, v117
	v_fmac_f32_e32 v46, v189, v119
	v_fmac_f32_e32 v47, v189, v121
	v_fmac_f32_e32 v48, v189, v123
	v_fmac_f32_e32 v49, v189, v125
	v_fmac_f32_e32 v60, v189, v129
	global_load_dword v221, v[50:51], off
	v_add_co_u32_e32 v62, vcc, s60, v50
	s_nop 1
	v_addc_co_u32_e32 v63, vcc, 0, v51, vcc
	v_lshl_add_u64 v[50:51], v[50:51], 0, s[24:25]
	global_load_dword v222, v[62:63], off
	v_add_u32_e32 v61, 104, v57
	v_add_u32_e32 v150, 104, v149
	ds_read2st64_b64 v[62:65], v61 offset1:4
	ds_read2st64_b64 v[66:69], v61 offset0:8 offset1:12
	ds_read2st64_b64 v[70:73], v61 offset0:16 offset1:20
	ds_read2st64_b64 v[74:77], v61 offset0:24 offset1:28
	ds_read2st64_b64 v[78:81], v61 offset0:32 offset1:36
	ds_read2st64_b64 v[82:85], v61 offset0:40 offset1:44
	ds_read2st64_b64 v[86:89], v61 offset0:48 offset1:52
	ds_read2st64_b64 v[90:93], v61 offset0:56 offset1:60
	ds_read2st64_b64 v[94:97], v61 offset0:64 offset1:68
	ds_read2st64_b64 v[98:101], v61 offset0:72 offset1:76
	ds_read2st64_b64 v[102:105], v61 offset0:80 offset1:84
	ds_read2st64_b64 v[106:109], v61 offset0:88 offset1:92
	ds_read2st64_b64 v[110:113], v61 offset0:96 offset1:100
	ds_read2st64_b64 v[114:117], v61 offset0:104 offset1:108
	ds_read2st64_b64 v[118:121], v61 offset0:112 offset1:116
	ds_read2st64_b64 v[122:125], v61 offset0:120 offset1:124
	ds_read_b64 v[128:129], v150
	s_waitcnt vmcnt(30)
	s_waitcnt lgkmcnt(15)
	v_fmac_f32_e32 v30, v190, v62
	v_fmac_f32_e32 v43, v190, v64
	s_waitcnt lgkmcnt(15)
	v_fmac_f32_e32 v42, v190, v66
	v_fmac_f32_e32 v35, v190, v68
	s_waitcnt lgkmcnt(14)
	v_fmac_f32_e32 v34, v190, v70
	v_fmac_f32_e32 v29, v190, v72
	s_waitcnt lgkmcnt(13)
	v_fmac_f32_e32 v28, v190, v74
	v_fmac_f32_e32 v27, v190, v76
	s_waitcnt lgkmcnt(12)
	v_fmac_f32_e32 v26, v190, v78
	v_fmac_f32_e32 v25, v190, v80
	s_waitcnt lgkmcnt(11)
	v_fmac_f32_e32 v24, v190, v82
	v_fmac_f32_e32 v23, v190, v84
	s_waitcnt lgkmcnt(10)
	v_fmac_f32_e32 v22, v190, v86
	v_fmac_f32_e32 v21, v190, v88
	s_waitcnt lgkmcnt(9)
	v_fmac_f32_e32 v20, v190, v90
	v_fmac_f32_e32 v17, v190, v92
	s_waitcnt lgkmcnt(8)
	v_fmac_f32_e32 v16, v190, v94
	v_fmac_f32_e32 v31, v190, v96
	s_waitcnt lgkmcnt(7)
	v_fmac_f32_e32 v32, v190, v98
	v_fmac_f32_e32 v33, v190, v100
	s_waitcnt lgkmcnt(6)
	v_fmac_f32_e32 v36, v190, v102
	v_fmac_f32_e32 v37, v190, v104
	s_waitcnt lgkmcnt(5)
	v_fmac_f32_e32 v38, v190, v106
	v_fmac_f32_e32 v39, v190, v108
	s_waitcnt lgkmcnt(4)
	v_fmac_f32_e32 v40, v190, v110
	v_fmac_f32_e32 v41, v190, v112
	s_waitcnt lgkmcnt(3)
	v_fmac_f32_e32 v44, v190, v114
	v_fmac_f32_e32 v45, v190, v116
	s_waitcnt lgkmcnt(2)
	v_fmac_f32_e32 v46, v190, v118
	v_fmac_f32_e32 v47, v190, v120
	s_waitcnt lgkmcnt(1)
	v_fmac_f32_e32 v48, v190, v122
	v_fmac_f32_e32 v49, v190, v124
	s_waitcnt lgkmcnt(0)
	v_fmac_f32_e32 v60, v190, v128
	v_fmac_f32_e32 v30, v191, v63
	v_fmac_f32_e32 v43, v191, v65
	v_fmac_f32_e32 v42, v191, v67
	v_fmac_f32_e32 v35, v191, v69
	v_fmac_f32_e32 v34, v191, v71
	v_fmac_f32_e32 v29, v191, v73
	v_fmac_f32_e32 v28, v191, v75
	v_fmac_f32_e32 v27, v191, v77
	v_fmac_f32_e32 v26, v191, v79
	v_fmac_f32_e32 v25, v191, v81
	v_fmac_f32_e32 v24, v191, v83
	v_fmac_f32_e32 v23, v191, v85
	v_fmac_f32_e32 v22, v191, v87
	v_fmac_f32_e32 v21, v191, v89
	v_fmac_f32_e32 v20, v191, v91
	v_fmac_f32_e32 v17, v191, v93
	v_fmac_f32_e32 v16, v191, v95
	v_fmac_f32_e32 v31, v191, v97
	v_fmac_f32_e32 v32, v191, v99
	v_fmac_f32_e32 v33, v191, v101
	v_fmac_f32_e32 v36, v191, v103
	v_fmac_f32_e32 v37, v191, v105
	v_fmac_f32_e32 v38, v191, v107
	v_fmac_f32_e32 v39, v191, v109
	v_fmac_f32_e32 v40, v191, v111
	v_fmac_f32_e32 v41, v191, v113
	v_fmac_f32_e32 v44, v191, v115
	v_fmac_f32_e32 v45, v191, v117
	v_fmac_f32_e32 v46, v191, v119
	v_fmac_f32_e32 v47, v191, v121
	v_fmac_f32_e32 v48, v191, v123
	v_fmac_f32_e32 v49, v191, v125
	v_fmac_f32_e32 v60, v191, v129
	global_load_dword v223, v[50:51], off
	v_add_co_u32_e32 v62, vcc, s60, v50
	s_nop 1
	v_addc_co_u32_e32 v63, vcc, 0, v51, vcc
	v_lshl_add_u64 v[50:51], v[50:51], 0, s[24:25]
	global_load_dword v224, v[62:63], off
	v_add_u32_e32 v61, 112, v57
	v_add_u32_e32 v150, 112, v149
	ds_read2st64_b64 v[62:65], v61 offset1:4
	ds_read2st64_b64 v[66:69], v61 offset0:8 offset1:12
	ds_read2st64_b64 v[70:73], v61 offset0:16 offset1:20
	ds_read2st64_b64 v[74:77], v61 offset0:24 offset1:28
	ds_read2st64_b64 v[78:81], v61 offset0:32 offset1:36
	ds_read2st64_b64 v[82:85], v61 offset0:40 offset1:44
	ds_read2st64_b64 v[86:89], v61 offset0:48 offset1:52
	ds_read2st64_b64 v[90:93], v61 offset0:56 offset1:60
	ds_read2st64_b64 v[94:97], v61 offset0:64 offset1:68
	ds_read2st64_b64 v[98:101], v61 offset0:72 offset1:76
	ds_read2st64_b64 v[102:105], v61 offset0:80 offset1:84
	ds_read2st64_b64 v[106:109], v61 offset0:88 offset1:92
	ds_read2st64_b64 v[110:113], v61 offset0:96 offset1:100
	ds_read2st64_b64 v[114:117], v61 offset0:104 offset1:108
	ds_read2st64_b64 v[118:121], v61 offset0:112 offset1:116
	ds_read2st64_b64 v[122:125], v61 offset0:120 offset1:124
	ds_read_b64 v[128:129], v150
	s_waitcnt vmcnt(30)
	s_waitcnt lgkmcnt(15)
	v_fmac_f32_e32 v30, v192, v62
	v_fmac_f32_e32 v43, v192, v64
	s_waitcnt lgkmcnt(15)
	v_fmac_f32_e32 v42, v192, v66
	v_fmac_f32_e32 v35, v192, v68
	s_waitcnt lgkmcnt(14)
	v_fmac_f32_e32 v34, v192, v70
	v_fmac_f32_e32 v29, v192, v72
	s_waitcnt lgkmcnt(13)
	v_fmac_f32_e32 v28, v192, v74
	v_fmac_f32_e32 v27, v192, v76
	s_waitcnt lgkmcnt(12)
	v_fmac_f32_e32 v26, v192, v78
	v_fmac_f32_e32 v25, v192, v80
	s_waitcnt lgkmcnt(11)
	v_fmac_f32_e32 v24, v192, v82
	v_fmac_f32_e32 v23, v192, v84
	s_waitcnt lgkmcnt(10)
	v_fmac_f32_e32 v22, v192, v86
	v_fmac_f32_e32 v21, v192, v88
	s_waitcnt lgkmcnt(9)
	v_fmac_f32_e32 v20, v192, v90
	v_fmac_f32_e32 v17, v192, v92
	s_waitcnt lgkmcnt(8)
	v_fmac_f32_e32 v16, v192, v94
	v_fmac_f32_e32 v31, v192, v96
	s_waitcnt lgkmcnt(7)
	v_fmac_f32_e32 v32, v192, v98
	v_fmac_f32_e32 v33, v192, v100
	s_waitcnt lgkmcnt(6)
	v_fmac_f32_e32 v36, v192, v102
	v_fmac_f32_e32 v37, v192, v104
	s_waitcnt lgkmcnt(5)
	v_fmac_f32_e32 v38, v192, v106
	v_fmac_f32_e32 v39, v192, v108
	s_waitcnt lgkmcnt(4)
	v_fmac_f32_e32 v40, v192, v110
	v_fmac_f32_e32 v41, v192, v112
	s_waitcnt lgkmcnt(3)
	v_fmac_f32_e32 v44, v192, v114
	v_fmac_f32_e32 v45, v192, v116
	s_waitcnt lgkmcnt(2)
	v_fmac_f32_e32 v46, v192, v118
	v_fmac_f32_e32 v47, v192, v120
	s_waitcnt lgkmcnt(1)
	v_fmac_f32_e32 v48, v192, v122
	v_fmac_f32_e32 v49, v192, v124
	s_waitcnt lgkmcnt(0)
	v_fmac_f32_e32 v60, v192, v128
	v_fmac_f32_e32 v30, v193, v63
	v_fmac_f32_e32 v43, v193, v65
	v_fmac_f32_e32 v42, v193, v67
	v_fmac_f32_e32 v35, v193, v69
	v_fmac_f32_e32 v34, v193, v71
	v_fmac_f32_e32 v29, v193, v73
	v_fmac_f32_e32 v28, v193, v75
	v_fmac_f32_e32 v27, v193, v77
	v_fmac_f32_e32 v26, v193, v79
	v_fmac_f32_e32 v25, v193, v81
	v_fmac_f32_e32 v24, v193, v83
	v_fmac_f32_e32 v23, v193, v85
	v_fmac_f32_e32 v22, v193, v87
	v_fmac_f32_e32 v21, v193, v89
	v_fmac_f32_e32 v20, v193, v91
	v_fmac_f32_e32 v17, v193, v93
	v_fmac_f32_e32 v16, v193, v95
	v_fmac_f32_e32 v31, v193, v97
	v_fmac_f32_e32 v32, v193, v99
	v_fmac_f32_e32 v33, v193, v101
	v_fmac_f32_e32 v36, v193, v103
	v_fmac_f32_e32 v37, v193, v105
	v_fmac_f32_e32 v38, v193, v107
	v_fmac_f32_e32 v39, v193, v109
	v_fmac_f32_e32 v40, v193, v111
	v_fmac_f32_e32 v41, v193, v113
	v_fmac_f32_e32 v44, v193, v115
	v_fmac_f32_e32 v45, v193, v117
	v_fmac_f32_e32 v46, v193, v119
	v_fmac_f32_e32 v47, v193, v121
	v_fmac_f32_e32 v48, v193, v123
	v_fmac_f32_e32 v49, v193, v125
	v_fmac_f32_e32 v60, v193, v129
	global_load_dword v225, v[50:51], off
	v_add_co_u32_e32 v62, vcc, s60, v50
	s_nop 1
	v_addc_co_u32_e32 v63, vcc, 0, v51, vcc
	v_lshl_add_u64 v[50:51], v[50:51], 0, s[24:25]
	global_load_dword v226, v[62:63], off
	v_add_u32_e32 v61, 120, v57
	v_add_u32_e32 v150, 120, v149
	ds_read2st64_b64 v[62:65], v61 offset1:4
	ds_read2st64_b64 v[66:69], v61 offset0:8 offset1:12
	ds_read2st64_b64 v[70:73], v61 offset0:16 offset1:20
	ds_read2st64_b64 v[74:77], v61 offset0:24 offset1:28
	ds_read2st64_b64 v[78:81], v61 offset0:32 offset1:36
	ds_read2st64_b64 v[82:85], v61 offset0:40 offset1:44
	ds_read2st64_b64 v[86:89], v61 offset0:48 offset1:52
	ds_read2st64_b64 v[90:93], v61 offset0:56 offset1:60
	ds_read2st64_b64 v[94:97], v61 offset0:64 offset1:68
	ds_read2st64_b64 v[98:101], v61 offset0:72 offset1:76
	ds_read2st64_b64 v[102:105], v61 offset0:80 offset1:84
	ds_read2st64_b64 v[106:109], v61 offset0:88 offset1:92
	ds_read2st64_b64 v[110:113], v61 offset0:96 offset1:100
	ds_read2st64_b64 v[114:117], v61 offset0:104 offset1:108
	ds_read2st64_b64 v[118:121], v61 offset0:112 offset1:116
	ds_read2st64_b64 v[122:125], v61 offset0:120 offset1:124
	ds_read_b64 v[128:129], v150
	s_waitcnt vmcnt(30)
	s_waitcnt lgkmcnt(15)
	v_fmac_f32_e32 v30, v194, v62
	v_fmac_f32_e32 v43, v194, v64
	s_waitcnt lgkmcnt(15)
	v_fmac_f32_e32 v42, v194, v66
	v_fmac_f32_e32 v35, v194, v68
	s_waitcnt lgkmcnt(14)
	v_fmac_f32_e32 v34, v194, v70
	v_fmac_f32_e32 v29, v194, v72
	s_waitcnt lgkmcnt(13)
	v_fmac_f32_e32 v28, v194, v74
	v_fmac_f32_e32 v27, v194, v76
	s_waitcnt lgkmcnt(12)
	v_fmac_f32_e32 v26, v194, v78
	v_fmac_f32_e32 v25, v194, v80
	s_waitcnt lgkmcnt(11)
	v_fmac_f32_e32 v24, v194, v82
	v_fmac_f32_e32 v23, v194, v84
	s_waitcnt lgkmcnt(10)
	v_fmac_f32_e32 v22, v194, v86
	v_fmac_f32_e32 v21, v194, v88
	s_waitcnt lgkmcnt(9)
	v_fmac_f32_e32 v20, v194, v90
	v_fmac_f32_e32 v17, v194, v92
	s_waitcnt lgkmcnt(8)
	v_fmac_f32_e32 v16, v194, v94
	v_fmac_f32_e32 v31, v194, v96
	s_waitcnt lgkmcnt(7)
	v_fmac_f32_e32 v32, v194, v98
	v_fmac_f32_e32 v33, v194, v100
	s_waitcnt lgkmcnt(6)
	v_fmac_f32_e32 v36, v194, v102
	v_fmac_f32_e32 v37, v194, v104
	s_waitcnt lgkmcnt(5)
	v_fmac_f32_e32 v38, v194, v106
	v_fmac_f32_e32 v39, v194, v108
	s_waitcnt lgkmcnt(4)
	v_fmac_f32_e32 v40, v194, v110
	v_fmac_f32_e32 v41, v194, v112
	s_waitcnt lgkmcnt(3)
	v_fmac_f32_e32 v44, v194, v114
	v_fmac_f32_e32 v45, v194, v116
	s_waitcnt lgkmcnt(2)
	v_fmac_f32_e32 v46, v194, v118
	v_fmac_f32_e32 v47, v194, v120
	s_waitcnt lgkmcnt(1)
	v_fmac_f32_e32 v48, v194, v122
	v_fmac_f32_e32 v49, v194, v124
	s_waitcnt lgkmcnt(0)
	v_fmac_f32_e32 v60, v194, v128
	v_fmac_f32_e32 v30, v195, v63
	v_fmac_f32_e32 v43, v195, v65
	v_fmac_f32_e32 v42, v195, v67
	v_fmac_f32_e32 v35, v195, v69
	v_fmac_f32_e32 v34, v195, v71
	v_fmac_f32_e32 v29, v195, v73
	v_fmac_f32_e32 v28, v195, v75
	v_fmac_f32_e32 v27, v195, v77
	v_fmac_f32_e32 v26, v195, v79
	v_fmac_f32_e32 v25, v195, v81
	v_fmac_f32_e32 v24, v195, v83
	v_fmac_f32_e32 v23, v195, v85
	v_fmac_f32_e32 v22, v195, v87
	v_fmac_f32_e32 v21, v195, v89
	v_fmac_f32_e32 v20, v195, v91
	v_fmac_f32_e32 v17, v195, v93
	v_fmac_f32_e32 v16, v195, v95
	v_fmac_f32_e32 v31, v195, v97
	v_fmac_f32_e32 v32, v195, v99
	v_fmac_f32_e32 v33, v195, v101
	v_fmac_f32_e32 v36, v195, v103
	v_fmac_f32_e32 v37, v195, v105
	v_fmac_f32_e32 v38, v195, v107
	v_fmac_f32_e32 v39, v195, v109
	v_fmac_f32_e32 v40, v195, v111
	v_fmac_f32_e32 v41, v195, v113
	v_fmac_f32_e32 v44, v195, v115
	v_fmac_f32_e32 v45, v195, v117
	v_fmac_f32_e32 v46, v195, v119
	v_fmac_f32_e32 v47, v195, v121
	v_fmac_f32_e32 v48, v195, v123
	v_fmac_f32_e32 v49, v195, v125
	v_fmac_f32_e32 v60, v195, v129
	global_load_dword v227, v[50:51], off
	v_add_co_u32_e32 v62, vcc, s60, v50
	s_nop 1
	v_addc_co_u32_e32 v63, vcc, 0, v51, vcc
	v_lshl_add_u64 v[50:51], v[50:51], 0, s[24:25]
	global_load_dword v228, v[62:63], off
	v_add_u32_e32 v61, 128, v57
	v_add_u32_e32 v150, 128, v149
	ds_read2st64_b64 v[62:65], v61 offset1:4
	ds_read2st64_b64 v[66:69], v61 offset0:8 offset1:12
	ds_read2st64_b64 v[70:73], v61 offset0:16 offset1:20
	ds_read2st64_b64 v[74:77], v61 offset0:24 offset1:28
	ds_read2st64_b64 v[78:81], v61 offset0:32 offset1:36
	ds_read2st64_b64 v[82:85], v61 offset0:40 offset1:44
	ds_read2st64_b64 v[86:89], v61 offset0:48 offset1:52
	ds_read2st64_b64 v[90:93], v61 offset0:56 offset1:60
	ds_read2st64_b64 v[94:97], v61 offset0:64 offset1:68
	ds_read2st64_b64 v[98:101], v61 offset0:72 offset1:76
	ds_read2st64_b64 v[102:105], v61 offset0:80 offset1:84
	ds_read2st64_b64 v[106:109], v61 offset0:88 offset1:92
	ds_read2st64_b64 v[110:113], v61 offset0:96 offset1:100
	ds_read2st64_b64 v[114:117], v61 offset0:104 offset1:108
	ds_read2st64_b64 v[118:121], v61 offset0:112 offset1:116
	ds_read2st64_b64 v[122:125], v61 offset0:120 offset1:124
	ds_read_b64 v[128:129], v150
	s_waitcnt vmcnt(30)
	s_waitcnt lgkmcnt(15)
	v_fmac_f32_e32 v30, v196, v62
	v_fmac_f32_e32 v43, v196, v64
	s_waitcnt lgkmcnt(15)
	v_fmac_f32_e32 v42, v196, v66
	v_fmac_f32_e32 v35, v196, v68
	s_waitcnt lgkmcnt(14)
	v_fmac_f32_e32 v34, v196, v70
	v_fmac_f32_e32 v29, v196, v72
	s_waitcnt lgkmcnt(13)
	v_fmac_f32_e32 v28, v196, v74
	v_fmac_f32_e32 v27, v196, v76
	s_waitcnt lgkmcnt(12)
	v_fmac_f32_e32 v26, v196, v78
	v_fmac_f32_e32 v25, v196, v80
	s_waitcnt lgkmcnt(11)
	v_fmac_f32_e32 v24, v196, v82
	v_fmac_f32_e32 v23, v196, v84
	s_waitcnt lgkmcnt(10)
	v_fmac_f32_e32 v22, v196, v86
	v_fmac_f32_e32 v21, v196, v88
	s_waitcnt lgkmcnt(9)
	v_fmac_f32_e32 v20, v196, v90
	v_fmac_f32_e32 v17, v196, v92
	s_waitcnt lgkmcnt(8)
	v_fmac_f32_e32 v16, v196, v94
	v_fmac_f32_e32 v31, v196, v96
	s_waitcnt lgkmcnt(7)
	v_fmac_f32_e32 v32, v196, v98
	v_fmac_f32_e32 v33, v196, v100
	s_waitcnt lgkmcnt(6)
	v_fmac_f32_e32 v36, v196, v102
	v_fmac_f32_e32 v37, v196, v104
	s_waitcnt lgkmcnt(5)
	v_fmac_f32_e32 v38, v196, v106
	v_fmac_f32_e32 v39, v196, v108
	s_waitcnt lgkmcnt(4)
	v_fmac_f32_e32 v40, v196, v110
	v_fmac_f32_e32 v41, v196, v112
	s_waitcnt lgkmcnt(3)
	v_fmac_f32_e32 v44, v196, v114
	v_fmac_f32_e32 v45, v196, v116
	s_waitcnt lgkmcnt(2)
	v_fmac_f32_e32 v46, v196, v118
	v_fmac_f32_e32 v47, v196, v120
	s_waitcnt lgkmcnt(1)
	v_fmac_f32_e32 v48, v196, v122
	v_fmac_f32_e32 v49, v196, v124
	s_waitcnt lgkmcnt(0)
	v_fmac_f32_e32 v60, v196, v128
	v_fmac_f32_e32 v30, v197, v63
	v_fmac_f32_e32 v43, v197, v65
	v_fmac_f32_e32 v42, v197, v67
	v_fmac_f32_e32 v35, v197, v69
	v_fmac_f32_e32 v34, v197, v71
	v_fmac_f32_e32 v29, v197, v73
	v_fmac_f32_e32 v28, v197, v75
	v_fmac_f32_e32 v27, v197, v77
	v_fmac_f32_e32 v26, v197, v79
	v_fmac_f32_e32 v25, v197, v81
	v_fmac_f32_e32 v24, v197, v83
	v_fmac_f32_e32 v23, v197, v85
	v_fmac_f32_e32 v22, v197, v87
	v_fmac_f32_e32 v21, v197, v89
	v_fmac_f32_e32 v20, v197, v91
	v_fmac_f32_e32 v17, v197, v93
	v_fmac_f32_e32 v16, v197, v95
	v_fmac_f32_e32 v31, v197, v97
	v_fmac_f32_e32 v32, v197, v99
	v_fmac_f32_e32 v33, v197, v101
	v_fmac_f32_e32 v36, v197, v103
	v_fmac_f32_e32 v37, v197, v105
	v_fmac_f32_e32 v38, v197, v107
	v_fmac_f32_e32 v39, v197, v109
	v_fmac_f32_e32 v40, v197, v111
	v_fmac_f32_e32 v41, v197, v113
	v_fmac_f32_e32 v44, v197, v115
	v_fmac_f32_e32 v45, v197, v117
	v_fmac_f32_e32 v46, v197, v119
	v_fmac_f32_e32 v47, v197, v121
	v_fmac_f32_e32 v48, v197, v123
	v_fmac_f32_e32 v49, v197, v125
	v_fmac_f32_e32 v60, v197, v129
	v_add_u32_e32 v61, 136, v57
	v_add_u32_e32 v150, 136, v149
	ds_read2st64_b64 v[62:65], v61 offset1:4
	ds_read2st64_b64 v[66:69], v61 offset0:8 offset1:12
	ds_read2st64_b64 v[70:73], v61 offset0:16 offset1:20
	ds_read2st64_b64 v[74:77], v61 offset0:24 offset1:28
	ds_read2st64_b64 v[78:81], v61 offset0:32 offset1:36
	ds_read2st64_b64 v[82:85], v61 offset0:40 offset1:44
	ds_read2st64_b64 v[86:89], v61 offset0:48 offset1:52
	ds_read2st64_b64 v[90:93], v61 offset0:56 offset1:60
	ds_read2st64_b64 v[94:97], v61 offset0:64 offset1:68
	ds_read2st64_b64 v[98:101], v61 offset0:72 offset1:76
	ds_read2st64_b64 v[102:105], v61 offset0:80 offset1:84
	ds_read2st64_b64 v[106:109], v61 offset0:88 offset1:92
	ds_read2st64_b64 v[110:113], v61 offset0:96 offset1:100
	ds_read2st64_b64 v[114:117], v61 offset0:104 offset1:108
	ds_read2st64_b64 v[118:121], v61 offset0:112 offset1:116
	ds_read2st64_b64 v[122:125], v61 offset0:120 offset1:124
	ds_read_b64 v[128:129], v150
	s_waitcnt vmcnt(28)
	s_waitcnt lgkmcnt(15)
	v_fmac_f32_e32 v30, v198, v62
	v_fmac_f32_e32 v43, v198, v64
	s_waitcnt lgkmcnt(15)
	v_fmac_f32_e32 v42, v198, v66
	v_fmac_f32_e32 v35, v198, v68
	s_waitcnt lgkmcnt(14)
	v_fmac_f32_e32 v34, v198, v70
	v_fmac_f32_e32 v29, v198, v72
	s_waitcnt lgkmcnt(13)
	v_fmac_f32_e32 v28, v198, v74
	v_fmac_f32_e32 v27, v198, v76
	s_waitcnt lgkmcnt(12)
	v_fmac_f32_e32 v26, v198, v78
	v_fmac_f32_e32 v25, v198, v80
	s_waitcnt lgkmcnt(11)
	v_fmac_f32_e32 v24, v198, v82
	v_fmac_f32_e32 v23, v198, v84
	s_waitcnt lgkmcnt(10)
	v_fmac_f32_e32 v22, v198, v86
	v_fmac_f32_e32 v21, v198, v88
	s_waitcnt lgkmcnt(9)
	v_fmac_f32_e32 v20, v198, v90
	v_fmac_f32_e32 v17, v198, v92
	s_waitcnt lgkmcnt(8)
	v_fmac_f32_e32 v16, v198, v94
	v_fmac_f32_e32 v31, v198, v96
	s_waitcnt lgkmcnt(7)
	v_fmac_f32_e32 v32, v198, v98
	v_fmac_f32_e32 v33, v198, v100
	s_waitcnt lgkmcnt(6)
	v_fmac_f32_e32 v36, v198, v102
	v_fmac_f32_e32 v37, v198, v104
	s_waitcnt lgkmcnt(5)
	v_fmac_f32_e32 v38, v198, v106
	v_fmac_f32_e32 v39, v198, v108
	s_waitcnt lgkmcnt(4)
	v_fmac_f32_e32 v40, v198, v110
	v_fmac_f32_e32 v41, v198, v112
	s_waitcnt lgkmcnt(3)
	v_fmac_f32_e32 v44, v198, v114
	v_fmac_f32_e32 v45, v198, v116
	s_waitcnt lgkmcnt(2)
	v_fmac_f32_e32 v46, v198, v118
	v_fmac_f32_e32 v47, v198, v120
	s_waitcnt lgkmcnt(1)
	v_fmac_f32_e32 v48, v198, v122
	v_fmac_f32_e32 v49, v198, v124
	s_waitcnt lgkmcnt(0)
	v_fmac_f32_e32 v60, v198, v128
	v_fmac_f32_e32 v30, v199, v63
	v_fmac_f32_e32 v43, v199, v65
	v_fmac_f32_e32 v42, v199, v67
	v_fmac_f32_e32 v35, v199, v69
	v_fmac_f32_e32 v34, v199, v71
	v_fmac_f32_e32 v29, v199, v73
	v_fmac_f32_e32 v28, v199, v75
	v_fmac_f32_e32 v27, v199, v77
	v_fmac_f32_e32 v26, v199, v79
	v_fmac_f32_e32 v25, v199, v81
	v_fmac_f32_e32 v24, v199, v83
	v_fmac_f32_e32 v23, v199, v85
	v_fmac_f32_e32 v22, v199, v87
	v_fmac_f32_e32 v21, v199, v89
	v_fmac_f32_e32 v20, v199, v91
	v_fmac_f32_e32 v17, v199, v93
	v_fmac_f32_e32 v16, v199, v95
	v_fmac_f32_e32 v31, v199, v97
	v_fmac_f32_e32 v32, v199, v99
	v_fmac_f32_e32 v33, v199, v101
	v_fmac_f32_e32 v36, v199, v103
	v_fmac_f32_e32 v37, v199, v105
	v_fmac_f32_e32 v38, v199, v107
	v_fmac_f32_e32 v39, v199, v109
	v_fmac_f32_e32 v40, v199, v111
	v_fmac_f32_e32 v41, v199, v113
	v_fmac_f32_e32 v44, v199, v115
	v_fmac_f32_e32 v45, v199, v117
	v_fmac_f32_e32 v46, v199, v119
	v_fmac_f32_e32 v47, v199, v121
	v_fmac_f32_e32 v48, v199, v123
	v_fmac_f32_e32 v49, v199, v125
	v_fmac_f32_e32 v60, v199, v129
	v_add_u32_e32 v61, 144, v57
	v_add_u32_e32 v150, 144, v149
	ds_read2st64_b64 v[62:65], v61 offset1:4
	ds_read2st64_b64 v[66:69], v61 offset0:8 offset1:12
	ds_read2st64_b64 v[70:73], v61 offset0:16 offset1:20
	ds_read2st64_b64 v[74:77], v61 offset0:24 offset1:28
	ds_read2st64_b64 v[78:81], v61 offset0:32 offset1:36
	ds_read2st64_b64 v[82:85], v61 offset0:40 offset1:44
	ds_read2st64_b64 v[86:89], v61 offset0:48 offset1:52
	ds_read2st64_b64 v[90:93], v61 offset0:56 offset1:60
	ds_read2st64_b64 v[94:97], v61 offset0:64 offset1:68
	ds_read2st64_b64 v[98:101], v61 offset0:72 offset1:76
	ds_read2st64_b64 v[102:105], v61 offset0:80 offset1:84
	ds_read2st64_b64 v[106:109], v61 offset0:88 offset1:92
	ds_read2st64_b64 v[110:113], v61 offset0:96 offset1:100
	ds_read2st64_b64 v[114:117], v61 offset0:104 offset1:108
	ds_read2st64_b64 v[118:121], v61 offset0:112 offset1:116
	ds_read2st64_b64 v[122:125], v61 offset0:120 offset1:124
	ds_read_b64 v[128:129], v150
	s_waitcnt vmcnt(26)
	s_waitcnt lgkmcnt(15)
	v_fmac_f32_e32 v30, v200, v62
	v_fmac_f32_e32 v43, v200, v64
	s_waitcnt lgkmcnt(15)
	v_fmac_f32_e32 v42, v200, v66
	v_fmac_f32_e32 v35, v200, v68
	s_waitcnt lgkmcnt(14)
	v_fmac_f32_e32 v34, v200, v70
	v_fmac_f32_e32 v29, v200, v72
	s_waitcnt lgkmcnt(13)
	v_fmac_f32_e32 v28, v200, v74
	v_fmac_f32_e32 v27, v200, v76
	s_waitcnt lgkmcnt(12)
	v_fmac_f32_e32 v26, v200, v78
	v_fmac_f32_e32 v25, v200, v80
	s_waitcnt lgkmcnt(11)
	v_fmac_f32_e32 v24, v200, v82
	v_fmac_f32_e32 v23, v200, v84
	s_waitcnt lgkmcnt(10)
	v_fmac_f32_e32 v22, v200, v86
	v_fmac_f32_e32 v21, v200, v88
	s_waitcnt lgkmcnt(9)
	v_fmac_f32_e32 v20, v200, v90
	v_fmac_f32_e32 v17, v200, v92
	s_waitcnt lgkmcnt(8)
	v_fmac_f32_e32 v16, v200, v94
	v_fmac_f32_e32 v31, v200, v96
	s_waitcnt lgkmcnt(7)
	v_fmac_f32_e32 v32, v200, v98
	v_fmac_f32_e32 v33, v200, v100
	s_waitcnt lgkmcnt(6)
	v_fmac_f32_e32 v36, v200, v102
	v_fmac_f32_e32 v37, v200, v104
	s_waitcnt lgkmcnt(5)
	v_fmac_f32_e32 v38, v200, v106
	v_fmac_f32_e32 v39, v200, v108
	s_waitcnt lgkmcnt(4)
	v_fmac_f32_e32 v40, v200, v110
	v_fmac_f32_e32 v41, v200, v112
	s_waitcnt lgkmcnt(3)
	v_fmac_f32_e32 v44, v200, v114
	v_fmac_f32_e32 v45, v200, v116
	s_waitcnt lgkmcnt(2)
	v_fmac_f32_e32 v46, v200, v118
	v_fmac_f32_e32 v47, v200, v120
	s_waitcnt lgkmcnt(1)
	v_fmac_f32_e32 v48, v200, v122
	v_fmac_f32_e32 v49, v200, v124
	s_waitcnt lgkmcnt(0)
	v_fmac_f32_e32 v60, v200, v128
	v_fmac_f32_e32 v30, v201, v63
	v_fmac_f32_e32 v43, v201, v65
	v_fmac_f32_e32 v42, v201, v67
	v_fmac_f32_e32 v35, v201, v69
	v_fmac_f32_e32 v34, v201, v71
	v_fmac_f32_e32 v29, v201, v73
	v_fmac_f32_e32 v28, v201, v75
	v_fmac_f32_e32 v27, v201, v77
	v_fmac_f32_e32 v26, v201, v79
	v_fmac_f32_e32 v25, v201, v81
	v_fmac_f32_e32 v24, v201, v83
	v_fmac_f32_e32 v23, v201, v85
	v_fmac_f32_e32 v22, v201, v87
	v_fmac_f32_e32 v21, v201, v89
	v_fmac_f32_e32 v20, v201, v91
	v_fmac_f32_e32 v17, v201, v93
	v_fmac_f32_e32 v16, v201, v95
	v_fmac_f32_e32 v31, v201, v97
	v_fmac_f32_e32 v32, v201, v99
	v_fmac_f32_e32 v33, v201, v101
	v_fmac_f32_e32 v36, v201, v103
	v_fmac_f32_e32 v37, v201, v105
	v_fmac_f32_e32 v38, v201, v107
	v_fmac_f32_e32 v39, v201, v109
	v_fmac_f32_e32 v40, v201, v111
	v_fmac_f32_e32 v41, v201, v113
	v_fmac_f32_e32 v44, v201, v115
	v_fmac_f32_e32 v45, v201, v117
	v_fmac_f32_e32 v46, v201, v119
	v_fmac_f32_e32 v47, v201, v121
	v_fmac_f32_e32 v48, v201, v123
	v_fmac_f32_e32 v49, v201, v125
	v_fmac_f32_e32 v60, v201, v129
	v_add_u32_e32 v61, 152, v57
	v_add_u32_e32 v150, 152, v149
	ds_read2st64_b64 v[62:65], v61 offset1:4
	ds_read2st64_b64 v[66:69], v61 offset0:8 offset1:12
	ds_read2st64_b64 v[70:73], v61 offset0:16 offset1:20
	ds_read2st64_b64 v[74:77], v61 offset0:24 offset1:28
	ds_read2st64_b64 v[78:81], v61 offset0:32 offset1:36
	ds_read2st64_b64 v[82:85], v61 offset0:40 offset1:44
	ds_read2st64_b64 v[86:89], v61 offset0:48 offset1:52
	ds_read2st64_b64 v[90:93], v61 offset0:56 offset1:60
	ds_read2st64_b64 v[94:97], v61 offset0:64 offset1:68
	ds_read2st64_b64 v[98:101], v61 offset0:72 offset1:76
	ds_read2st64_b64 v[102:105], v61 offset0:80 offset1:84
	ds_read2st64_b64 v[106:109], v61 offset0:88 offset1:92
	ds_read2st64_b64 v[110:113], v61 offset0:96 offset1:100
	ds_read2st64_b64 v[114:117], v61 offset0:104 offset1:108
	ds_read2st64_b64 v[118:121], v61 offset0:112 offset1:116
	ds_read2st64_b64 v[122:125], v61 offset0:120 offset1:124
	ds_read_b64 v[128:129], v150
	s_waitcnt vmcnt(24)
	s_waitcnt lgkmcnt(15)
	v_fmac_f32_e32 v30, v202, v62
	v_fmac_f32_e32 v43, v202, v64
	s_waitcnt lgkmcnt(15)
	v_fmac_f32_e32 v42, v202, v66
	v_fmac_f32_e32 v35, v202, v68
	s_waitcnt lgkmcnt(14)
	v_fmac_f32_e32 v34, v202, v70
	v_fmac_f32_e32 v29, v202, v72
	s_waitcnt lgkmcnt(13)
	v_fmac_f32_e32 v28, v202, v74
	v_fmac_f32_e32 v27, v202, v76
	s_waitcnt lgkmcnt(12)
	v_fmac_f32_e32 v26, v202, v78
	v_fmac_f32_e32 v25, v202, v80
	s_waitcnt lgkmcnt(11)
	v_fmac_f32_e32 v24, v202, v82
	v_fmac_f32_e32 v23, v202, v84
	s_waitcnt lgkmcnt(10)
	v_fmac_f32_e32 v22, v202, v86
	v_fmac_f32_e32 v21, v202, v88
	s_waitcnt lgkmcnt(9)
	v_fmac_f32_e32 v20, v202, v90
	v_fmac_f32_e32 v17, v202, v92
	s_waitcnt lgkmcnt(8)
	v_fmac_f32_e32 v16, v202, v94
	v_fmac_f32_e32 v31, v202, v96
	s_waitcnt lgkmcnt(7)
	v_fmac_f32_e32 v32, v202, v98
	v_fmac_f32_e32 v33, v202, v100
	s_waitcnt lgkmcnt(6)
	v_fmac_f32_e32 v36, v202, v102
	v_fmac_f32_e32 v37, v202, v104
	s_waitcnt lgkmcnt(5)
	v_fmac_f32_e32 v38, v202, v106
	v_fmac_f32_e32 v39, v202, v108
	s_waitcnt lgkmcnt(4)
	v_fmac_f32_e32 v40, v202, v110
	v_fmac_f32_e32 v41, v202, v112
	s_waitcnt lgkmcnt(3)
	v_fmac_f32_e32 v44, v202, v114
	v_fmac_f32_e32 v45, v202, v116
	s_waitcnt lgkmcnt(2)
	v_fmac_f32_e32 v46, v202, v118
	v_fmac_f32_e32 v47, v202, v120
	s_waitcnt lgkmcnt(1)
	v_fmac_f32_e32 v48, v202, v122
	v_fmac_f32_e32 v49, v202, v124
	s_waitcnt lgkmcnt(0)
	v_fmac_f32_e32 v60, v202, v128
	v_fmac_f32_e32 v30, v203, v63
	v_fmac_f32_e32 v43, v203, v65
	v_fmac_f32_e32 v42, v203, v67
	v_fmac_f32_e32 v35, v203, v69
	v_fmac_f32_e32 v34, v203, v71
	v_fmac_f32_e32 v29, v203, v73
	v_fmac_f32_e32 v28, v203, v75
	v_fmac_f32_e32 v27, v203, v77
	v_fmac_f32_e32 v26, v203, v79
	v_fmac_f32_e32 v25, v203, v81
	v_fmac_f32_e32 v24, v203, v83
	v_fmac_f32_e32 v23, v203, v85
	v_fmac_f32_e32 v22, v203, v87
	v_fmac_f32_e32 v21, v203, v89
	v_fmac_f32_e32 v20, v203, v91
	v_fmac_f32_e32 v17, v203, v93
	v_fmac_f32_e32 v16, v203, v95
	v_fmac_f32_e32 v31, v203, v97
	v_fmac_f32_e32 v32, v203, v99
	v_fmac_f32_e32 v33, v203, v101
	v_fmac_f32_e32 v36, v203, v103
	v_fmac_f32_e32 v37, v203, v105
	v_fmac_f32_e32 v38, v203, v107
	v_fmac_f32_e32 v39, v203, v109
	v_fmac_f32_e32 v40, v203, v111
	v_fmac_f32_e32 v41, v203, v113
	v_fmac_f32_e32 v44, v203, v115
	v_fmac_f32_e32 v45, v203, v117
	v_fmac_f32_e32 v46, v203, v119
	v_fmac_f32_e32 v47, v203, v121
	v_fmac_f32_e32 v48, v203, v123
	v_fmac_f32_e32 v49, v203, v125
	v_fmac_f32_e32 v60, v203, v129
	v_add_u32_e32 v61, 160, v57
	v_add_u32_e32 v150, 160, v149
	ds_read2st64_b64 v[62:65], v61 offset1:4
	ds_read2st64_b64 v[66:69], v61 offset0:8 offset1:12
	ds_read2st64_b64 v[70:73], v61 offset0:16 offset1:20
	ds_read2st64_b64 v[74:77], v61 offset0:24 offset1:28
	ds_read2st64_b64 v[78:81], v61 offset0:32 offset1:36
	ds_read2st64_b64 v[82:85], v61 offset0:40 offset1:44
	ds_read2st64_b64 v[86:89], v61 offset0:48 offset1:52
	ds_read2st64_b64 v[90:93], v61 offset0:56 offset1:60
	ds_read2st64_b64 v[94:97], v61 offset0:64 offset1:68
	ds_read2st64_b64 v[98:101], v61 offset0:72 offset1:76
	ds_read2st64_b64 v[102:105], v61 offset0:80 offset1:84
	ds_read2st64_b64 v[106:109], v61 offset0:88 offset1:92
	ds_read2st64_b64 v[110:113], v61 offset0:96 offset1:100
	ds_read2st64_b64 v[114:117], v61 offset0:104 offset1:108
	ds_read2st64_b64 v[118:121], v61 offset0:112 offset1:116
	ds_read2st64_b64 v[122:125], v61 offset0:120 offset1:124
	ds_read_b64 v[128:129], v150
	s_waitcnt vmcnt(22)
	s_waitcnt lgkmcnt(15)
	v_fmac_f32_e32 v30, v204, v62
	v_fmac_f32_e32 v43, v204, v64
	s_waitcnt lgkmcnt(15)
	v_fmac_f32_e32 v42, v204, v66
	v_fmac_f32_e32 v35, v204, v68
	s_waitcnt lgkmcnt(14)
	v_fmac_f32_e32 v34, v204, v70
	v_fmac_f32_e32 v29, v204, v72
	s_waitcnt lgkmcnt(13)
	v_fmac_f32_e32 v28, v204, v74
	v_fmac_f32_e32 v27, v204, v76
	s_waitcnt lgkmcnt(12)
	v_fmac_f32_e32 v26, v204, v78
	v_fmac_f32_e32 v25, v204, v80
	s_waitcnt lgkmcnt(11)
	v_fmac_f32_e32 v24, v204, v82
	v_fmac_f32_e32 v23, v204, v84
	s_waitcnt lgkmcnt(10)
	v_fmac_f32_e32 v22, v204, v86
	v_fmac_f32_e32 v21, v204, v88
	s_waitcnt lgkmcnt(9)
	v_fmac_f32_e32 v20, v204, v90
	v_fmac_f32_e32 v17, v204, v92
	s_waitcnt lgkmcnt(8)
	v_fmac_f32_e32 v16, v204, v94
	v_fmac_f32_e32 v31, v204, v96
	s_waitcnt lgkmcnt(7)
	v_fmac_f32_e32 v32, v204, v98
	v_fmac_f32_e32 v33, v204, v100
	s_waitcnt lgkmcnt(6)
	v_fmac_f32_e32 v36, v204, v102
	v_fmac_f32_e32 v37, v204, v104
	s_waitcnt lgkmcnt(5)
	v_fmac_f32_e32 v38, v204, v106
	v_fmac_f32_e32 v39, v204, v108
	s_waitcnt lgkmcnt(4)
	v_fmac_f32_e32 v40, v204, v110
	v_fmac_f32_e32 v41, v204, v112
	s_waitcnt lgkmcnt(3)
	v_fmac_f32_e32 v44, v204, v114
	v_fmac_f32_e32 v45, v204, v116
	s_waitcnt lgkmcnt(2)
	v_fmac_f32_e32 v46, v204, v118
	v_fmac_f32_e32 v47, v204, v120
	s_waitcnt lgkmcnt(1)
	v_fmac_f32_e32 v48, v204, v122
	v_fmac_f32_e32 v49, v204, v124
	s_waitcnt lgkmcnt(0)
	v_fmac_f32_e32 v60, v204, v128
	v_fmac_f32_e32 v30, v205, v63
	v_fmac_f32_e32 v43, v205, v65
	v_fmac_f32_e32 v42, v205, v67
	v_fmac_f32_e32 v35, v205, v69
	v_fmac_f32_e32 v34, v205, v71
	v_fmac_f32_e32 v29, v205, v73
	v_fmac_f32_e32 v28, v205, v75
	v_fmac_f32_e32 v27, v205, v77
	v_fmac_f32_e32 v26, v205, v79
	v_fmac_f32_e32 v25, v205, v81
	v_fmac_f32_e32 v24, v205, v83
	v_fmac_f32_e32 v23, v205, v85
	v_fmac_f32_e32 v22, v205, v87
	v_fmac_f32_e32 v21, v205, v89
	v_fmac_f32_e32 v20, v205, v91
	v_fmac_f32_e32 v17, v205, v93
	v_fmac_f32_e32 v16, v205, v95
	v_fmac_f32_e32 v31, v205, v97
	v_fmac_f32_e32 v32, v205, v99
	v_fmac_f32_e32 v33, v205, v101
	v_fmac_f32_e32 v36, v205, v103
	v_fmac_f32_e32 v37, v205, v105
	v_fmac_f32_e32 v38, v205, v107
	v_fmac_f32_e32 v39, v205, v109
	v_fmac_f32_e32 v40, v205, v111
	v_fmac_f32_e32 v41, v205, v113
	v_fmac_f32_e32 v44, v205, v115
	v_fmac_f32_e32 v45, v205, v117
	v_fmac_f32_e32 v46, v205, v119
	v_fmac_f32_e32 v47, v205, v121
	v_fmac_f32_e32 v48, v205, v123
	v_fmac_f32_e32 v49, v205, v125
	v_fmac_f32_e32 v60, v205, v129
	v_add_u32_e32 v61, 168, v57
	v_add_u32_e32 v150, 168, v149
	ds_read2st64_b64 v[62:65], v61 offset1:4
	ds_read2st64_b64 v[66:69], v61 offset0:8 offset1:12
	ds_read2st64_b64 v[70:73], v61 offset0:16 offset1:20
	ds_read2st64_b64 v[74:77], v61 offset0:24 offset1:28
	ds_read2st64_b64 v[78:81], v61 offset0:32 offset1:36
	ds_read2st64_b64 v[82:85], v61 offset0:40 offset1:44
	ds_read2st64_b64 v[86:89], v61 offset0:48 offset1:52
	ds_read2st64_b64 v[90:93], v61 offset0:56 offset1:60
	ds_read2st64_b64 v[94:97], v61 offset0:64 offset1:68
	ds_read2st64_b64 v[98:101], v61 offset0:72 offset1:76
	ds_read2st64_b64 v[102:105], v61 offset0:80 offset1:84
	ds_read2st64_b64 v[106:109], v61 offset0:88 offset1:92
	ds_read2st64_b64 v[110:113], v61 offset0:96 offset1:100
	ds_read2st64_b64 v[114:117], v61 offset0:104 offset1:108
	ds_read2st64_b64 v[118:121], v61 offset0:112 offset1:116
	ds_read2st64_b64 v[122:125], v61 offset0:120 offset1:124
	ds_read_b64 v[128:129], v150
	s_waitcnt vmcnt(20)
	s_waitcnt lgkmcnt(15)
	v_fmac_f32_e32 v30, v206, v62
	v_fmac_f32_e32 v43, v206, v64
	s_waitcnt lgkmcnt(15)
	v_fmac_f32_e32 v42, v206, v66
	v_fmac_f32_e32 v35, v206, v68
	s_waitcnt lgkmcnt(14)
	v_fmac_f32_e32 v34, v206, v70
	v_fmac_f32_e32 v29, v206, v72
	s_waitcnt lgkmcnt(13)
	v_fmac_f32_e32 v28, v206, v74
	v_fmac_f32_e32 v27, v206, v76
	s_waitcnt lgkmcnt(12)
	v_fmac_f32_e32 v26, v206, v78
	v_fmac_f32_e32 v25, v206, v80
	s_waitcnt lgkmcnt(11)
	v_fmac_f32_e32 v24, v206, v82
	v_fmac_f32_e32 v23, v206, v84
	s_waitcnt lgkmcnt(10)
	v_fmac_f32_e32 v22, v206, v86
	v_fmac_f32_e32 v21, v206, v88
	s_waitcnt lgkmcnt(9)
	v_fmac_f32_e32 v20, v206, v90
	v_fmac_f32_e32 v17, v206, v92
	s_waitcnt lgkmcnt(8)
	v_fmac_f32_e32 v16, v206, v94
	v_fmac_f32_e32 v31, v206, v96
	s_waitcnt lgkmcnt(7)
	v_fmac_f32_e32 v32, v206, v98
	v_fmac_f32_e32 v33, v206, v100
	s_waitcnt lgkmcnt(6)
	v_fmac_f32_e32 v36, v206, v102
	v_fmac_f32_e32 v37, v206, v104
	s_waitcnt lgkmcnt(5)
	v_fmac_f32_e32 v38, v206, v106
	v_fmac_f32_e32 v39, v206, v108
	s_waitcnt lgkmcnt(4)
	v_fmac_f32_e32 v40, v206, v110
	v_fmac_f32_e32 v41, v206, v112
	s_waitcnt lgkmcnt(3)
	v_fmac_f32_e32 v44, v206, v114
	v_fmac_f32_e32 v45, v206, v116
	s_waitcnt lgkmcnt(2)
	v_fmac_f32_e32 v46, v206, v118
	v_fmac_f32_e32 v47, v206, v120
	s_waitcnt lgkmcnt(1)
	v_fmac_f32_e32 v48, v206, v122
	v_fmac_f32_e32 v49, v206, v124
	s_waitcnt lgkmcnt(0)
	v_fmac_f32_e32 v60, v206, v128
	v_fmac_f32_e32 v30, v207, v63
	v_fmac_f32_e32 v43, v207, v65
	v_fmac_f32_e32 v42, v207, v67
	v_fmac_f32_e32 v35, v207, v69
	v_fmac_f32_e32 v34, v207, v71
	v_fmac_f32_e32 v29, v207, v73
	v_fmac_f32_e32 v28, v207, v75
	v_fmac_f32_e32 v27, v207, v77
	v_fmac_f32_e32 v26, v207, v79
	v_fmac_f32_e32 v25, v207, v81
	v_fmac_f32_e32 v24, v207, v83
	v_fmac_f32_e32 v23, v207, v85
	v_fmac_f32_e32 v22, v207, v87
	v_fmac_f32_e32 v21, v207, v89
	v_fmac_f32_e32 v20, v207, v91
	v_fmac_f32_e32 v17, v207, v93
	v_fmac_f32_e32 v16, v207, v95
	v_fmac_f32_e32 v31, v207, v97
	v_fmac_f32_e32 v32, v207, v99
	v_fmac_f32_e32 v33, v207, v101
	v_fmac_f32_e32 v36, v207, v103
	v_fmac_f32_e32 v37, v207, v105
	v_fmac_f32_e32 v38, v207, v107
	v_fmac_f32_e32 v39, v207, v109
	v_fmac_f32_e32 v40, v207, v111
	v_fmac_f32_e32 v41, v207, v113
	v_fmac_f32_e32 v44, v207, v115
	v_fmac_f32_e32 v45, v207, v117
	v_fmac_f32_e32 v46, v207, v119
	v_fmac_f32_e32 v47, v207, v121
	v_fmac_f32_e32 v48, v207, v123
	v_fmac_f32_e32 v49, v207, v125
	v_fmac_f32_e32 v60, v207, v129
	v_add_u32_e32 v61, 176, v57
	v_add_u32_e32 v150, 176, v149
	ds_read2st64_b64 v[62:65], v61 offset1:4
	ds_read2st64_b64 v[66:69], v61 offset0:8 offset1:12
	ds_read2st64_b64 v[70:73], v61 offset0:16 offset1:20
	ds_read2st64_b64 v[74:77], v61 offset0:24 offset1:28
	ds_read2st64_b64 v[78:81], v61 offset0:32 offset1:36
	ds_read2st64_b64 v[82:85], v61 offset0:40 offset1:44
	ds_read2st64_b64 v[86:89], v61 offset0:48 offset1:52
	ds_read2st64_b64 v[90:93], v61 offset0:56 offset1:60
	ds_read2st64_b64 v[94:97], v61 offset0:64 offset1:68
	ds_read2st64_b64 v[98:101], v61 offset0:72 offset1:76
	ds_read2st64_b64 v[102:105], v61 offset0:80 offset1:84
	ds_read2st64_b64 v[106:109], v61 offset0:88 offset1:92
	ds_read2st64_b64 v[110:113], v61 offset0:96 offset1:100
	ds_read2st64_b64 v[114:117], v61 offset0:104 offset1:108
	ds_read2st64_b64 v[118:121], v61 offset0:112 offset1:116
	ds_read2st64_b64 v[122:125], v61 offset0:120 offset1:124
	ds_read_b64 v[128:129], v150
	s_waitcnt vmcnt(18)
	s_waitcnt lgkmcnt(15)
	v_fmac_f32_e32 v30, v208, v62
	v_fmac_f32_e32 v43, v208, v64
	s_waitcnt lgkmcnt(15)
	v_fmac_f32_e32 v42, v208, v66
	v_fmac_f32_e32 v35, v208, v68
	s_waitcnt lgkmcnt(14)
	v_fmac_f32_e32 v34, v208, v70
	v_fmac_f32_e32 v29, v208, v72
	s_waitcnt lgkmcnt(13)
	v_fmac_f32_e32 v28, v208, v74
	v_fmac_f32_e32 v27, v208, v76
	s_waitcnt lgkmcnt(12)
	v_fmac_f32_e32 v26, v208, v78
	v_fmac_f32_e32 v25, v208, v80
	s_waitcnt lgkmcnt(11)
	v_fmac_f32_e32 v24, v208, v82
	v_fmac_f32_e32 v23, v208, v84
	s_waitcnt lgkmcnt(10)
	v_fmac_f32_e32 v22, v208, v86
	v_fmac_f32_e32 v21, v208, v88
	s_waitcnt lgkmcnt(9)
	v_fmac_f32_e32 v20, v208, v90
	v_fmac_f32_e32 v17, v208, v92
	s_waitcnt lgkmcnt(8)
	v_fmac_f32_e32 v16, v208, v94
	v_fmac_f32_e32 v31, v208, v96
	s_waitcnt lgkmcnt(7)
	v_fmac_f32_e32 v32, v208, v98
	v_fmac_f32_e32 v33, v208, v100
	s_waitcnt lgkmcnt(6)
	v_fmac_f32_e32 v36, v208, v102
	v_fmac_f32_e32 v37, v208, v104
	s_waitcnt lgkmcnt(5)
	v_fmac_f32_e32 v38, v208, v106
	v_fmac_f32_e32 v39, v208, v108
	s_waitcnt lgkmcnt(4)
	v_fmac_f32_e32 v40, v208, v110
	v_fmac_f32_e32 v41, v208, v112
	s_waitcnt lgkmcnt(3)
	v_fmac_f32_e32 v44, v208, v114
	v_fmac_f32_e32 v45, v208, v116
	s_waitcnt lgkmcnt(2)
	v_fmac_f32_e32 v46, v208, v118
	v_fmac_f32_e32 v47, v208, v120
	s_waitcnt lgkmcnt(1)
	v_fmac_f32_e32 v48, v208, v122
	v_fmac_f32_e32 v49, v208, v124
	s_waitcnt lgkmcnt(0)
	v_fmac_f32_e32 v60, v208, v128
	v_fmac_f32_e32 v30, v209, v63
	v_fmac_f32_e32 v43, v209, v65
	v_fmac_f32_e32 v42, v209, v67
	v_fmac_f32_e32 v35, v209, v69
	v_fmac_f32_e32 v34, v209, v71
	v_fmac_f32_e32 v29, v209, v73
	v_fmac_f32_e32 v28, v209, v75
	v_fmac_f32_e32 v27, v209, v77
	v_fmac_f32_e32 v26, v209, v79
	v_fmac_f32_e32 v25, v209, v81
	v_fmac_f32_e32 v24, v209, v83
	v_fmac_f32_e32 v23, v209, v85
	v_fmac_f32_e32 v22, v209, v87
	v_fmac_f32_e32 v21, v209, v89
	v_fmac_f32_e32 v20, v209, v91
	v_fmac_f32_e32 v17, v209, v93
	v_fmac_f32_e32 v16, v209, v95
	v_fmac_f32_e32 v31, v209, v97
	v_fmac_f32_e32 v32, v209, v99
	v_fmac_f32_e32 v33, v209, v101
	v_fmac_f32_e32 v36, v209, v103
	v_fmac_f32_e32 v37, v209, v105
	v_fmac_f32_e32 v38, v209, v107
	v_fmac_f32_e32 v39, v209, v109
	v_fmac_f32_e32 v40, v209, v111
	v_fmac_f32_e32 v41, v209, v113
	v_fmac_f32_e32 v44, v209, v115
	v_fmac_f32_e32 v45, v209, v117
	v_fmac_f32_e32 v46, v209, v119
	v_fmac_f32_e32 v47, v209, v121
	v_fmac_f32_e32 v48, v209, v123
	v_fmac_f32_e32 v49, v209, v125
	v_fmac_f32_e32 v60, v209, v129
	v_add_u32_e32 v61, 184, v57
	v_add_u32_e32 v150, 184, v149
	ds_read2st64_b64 v[62:65], v61 offset1:4
	ds_read2st64_b64 v[66:69], v61 offset0:8 offset1:12
	ds_read2st64_b64 v[70:73], v61 offset0:16 offset1:20
	ds_read2st64_b64 v[74:77], v61 offset0:24 offset1:28
	ds_read2st64_b64 v[78:81], v61 offset0:32 offset1:36
	ds_read2st64_b64 v[82:85], v61 offset0:40 offset1:44
	ds_read2st64_b64 v[86:89], v61 offset0:48 offset1:52
	ds_read2st64_b64 v[90:93], v61 offset0:56 offset1:60
	ds_read2st64_b64 v[94:97], v61 offset0:64 offset1:68
	ds_read2st64_b64 v[98:101], v61 offset0:72 offset1:76
	ds_read2st64_b64 v[102:105], v61 offset0:80 offset1:84
	ds_read2st64_b64 v[106:109], v61 offset0:88 offset1:92
	ds_read2st64_b64 v[110:113], v61 offset0:96 offset1:100
	ds_read2st64_b64 v[114:117], v61 offset0:104 offset1:108
	ds_read2st64_b64 v[118:121], v61 offset0:112 offset1:116
	ds_read2st64_b64 v[122:125], v61 offset0:120 offset1:124
	ds_read_b64 v[128:129], v150
	s_waitcnt vmcnt(16)
	s_waitcnt lgkmcnt(15)
	v_fmac_f32_e32 v30, v210, v62
	v_fmac_f32_e32 v43, v210, v64
	s_waitcnt lgkmcnt(15)
	v_fmac_f32_e32 v42, v210, v66
	v_fmac_f32_e32 v35, v210, v68
	s_waitcnt lgkmcnt(14)
	v_fmac_f32_e32 v34, v210, v70
	v_fmac_f32_e32 v29, v210, v72
	s_waitcnt lgkmcnt(13)
	v_fmac_f32_e32 v28, v210, v74
	v_fmac_f32_e32 v27, v210, v76
	s_waitcnt lgkmcnt(12)
	v_fmac_f32_e32 v26, v210, v78
	v_fmac_f32_e32 v25, v210, v80
	s_waitcnt lgkmcnt(11)
	v_fmac_f32_e32 v24, v210, v82
	v_fmac_f32_e32 v23, v210, v84
	s_waitcnt lgkmcnt(10)
	v_fmac_f32_e32 v22, v210, v86
	v_fmac_f32_e32 v21, v210, v88
	s_waitcnt lgkmcnt(9)
	v_fmac_f32_e32 v20, v210, v90
	v_fmac_f32_e32 v17, v210, v92
	s_waitcnt lgkmcnt(8)
	v_fmac_f32_e32 v16, v210, v94
	v_fmac_f32_e32 v31, v210, v96
	s_waitcnt lgkmcnt(7)
	v_fmac_f32_e32 v32, v210, v98
	v_fmac_f32_e32 v33, v210, v100
	s_waitcnt lgkmcnt(6)
	v_fmac_f32_e32 v36, v210, v102
	v_fmac_f32_e32 v37, v210, v104
	s_waitcnt lgkmcnt(5)
	v_fmac_f32_e32 v38, v210, v106
	v_fmac_f32_e32 v39, v210, v108
	s_waitcnt lgkmcnt(4)
	v_fmac_f32_e32 v40, v210, v110
	v_fmac_f32_e32 v41, v210, v112
	s_waitcnt lgkmcnt(3)
	v_fmac_f32_e32 v44, v210, v114
	v_fmac_f32_e32 v45, v210, v116
	s_waitcnt lgkmcnt(2)
	v_fmac_f32_e32 v46, v210, v118
	v_fmac_f32_e32 v47, v210, v120
	s_waitcnt lgkmcnt(1)
	v_fmac_f32_e32 v48, v210, v122
	v_fmac_f32_e32 v49, v210, v124
	s_waitcnt lgkmcnt(0)
	v_fmac_f32_e32 v60, v210, v128
	v_fmac_f32_e32 v30, v212, v63
	v_fmac_f32_e32 v43, v212, v65
	v_fmac_f32_e32 v42, v212, v67
	v_fmac_f32_e32 v35, v212, v69
	v_fmac_f32_e32 v34, v212, v71
	v_fmac_f32_e32 v29, v212, v73
	v_fmac_f32_e32 v28, v212, v75
	v_fmac_f32_e32 v27, v212, v77
	v_fmac_f32_e32 v26, v212, v79
	v_fmac_f32_e32 v25, v212, v81
	v_fmac_f32_e32 v24, v212, v83
	v_fmac_f32_e32 v23, v212, v85
	v_fmac_f32_e32 v22, v212, v87
	v_fmac_f32_e32 v21, v212, v89
	v_fmac_f32_e32 v20, v212, v91
	v_fmac_f32_e32 v17, v212, v93
	v_fmac_f32_e32 v16, v212, v95
	v_fmac_f32_e32 v31, v212, v97
	v_fmac_f32_e32 v32, v212, v99
	v_fmac_f32_e32 v33, v212, v101
	v_fmac_f32_e32 v36, v212, v103
	v_fmac_f32_e32 v37, v212, v105
	v_fmac_f32_e32 v38, v212, v107
	v_fmac_f32_e32 v39, v212, v109
	v_fmac_f32_e32 v40, v212, v111
	v_fmac_f32_e32 v41, v212, v113
	v_fmac_f32_e32 v44, v212, v115
	v_fmac_f32_e32 v45, v212, v117
	v_fmac_f32_e32 v46, v212, v119
	v_fmac_f32_e32 v47, v212, v121
	v_fmac_f32_e32 v48, v212, v123
	v_fmac_f32_e32 v49, v212, v125
	v_fmac_f32_e32 v60, v212, v129
	v_add_u32_e32 v61, 192, v57
	v_add_u32_e32 v150, 192, v149
	ds_read2st64_b64 v[62:65], v61 offset1:4
	ds_read2st64_b64 v[66:69], v61 offset0:8 offset1:12
	ds_read2st64_b64 v[70:73], v61 offset0:16 offset1:20
	ds_read2st64_b64 v[74:77], v61 offset0:24 offset1:28
	ds_read2st64_b64 v[78:81], v61 offset0:32 offset1:36
	ds_read2st64_b64 v[82:85], v61 offset0:40 offset1:44
	ds_read2st64_b64 v[86:89], v61 offset0:48 offset1:52
	ds_read2st64_b64 v[90:93], v61 offset0:56 offset1:60
	ds_read2st64_b64 v[94:97], v61 offset0:64 offset1:68
	ds_read2st64_b64 v[98:101], v61 offset0:72 offset1:76
	ds_read2st64_b64 v[102:105], v61 offset0:80 offset1:84
	ds_read2st64_b64 v[106:109], v61 offset0:88 offset1:92
	ds_read2st64_b64 v[110:113], v61 offset0:96 offset1:100
	ds_read2st64_b64 v[114:117], v61 offset0:104 offset1:108
	ds_read2st64_b64 v[118:121], v61 offset0:112 offset1:116
	ds_read2st64_b64 v[122:125], v61 offset0:120 offset1:124
	ds_read_b64 v[128:129], v150
	s_waitcnt vmcnt(14)
	s_waitcnt lgkmcnt(15)
	v_fmac_f32_e32 v30, v213, v62
	v_fmac_f32_e32 v43, v213, v64
	s_waitcnt lgkmcnt(15)
	v_fmac_f32_e32 v42, v213, v66
	v_fmac_f32_e32 v35, v213, v68
	s_waitcnt lgkmcnt(14)
	v_fmac_f32_e32 v34, v213, v70
	v_fmac_f32_e32 v29, v213, v72
	s_waitcnt lgkmcnt(13)
	v_fmac_f32_e32 v28, v213, v74
	v_fmac_f32_e32 v27, v213, v76
	s_waitcnt lgkmcnt(12)
	v_fmac_f32_e32 v26, v213, v78
	v_fmac_f32_e32 v25, v213, v80
	s_waitcnt lgkmcnt(11)
	v_fmac_f32_e32 v24, v213, v82
	v_fmac_f32_e32 v23, v213, v84
	s_waitcnt lgkmcnt(10)
	v_fmac_f32_e32 v22, v213, v86
	v_fmac_f32_e32 v21, v213, v88
	s_waitcnt lgkmcnt(9)
	v_fmac_f32_e32 v20, v213, v90
	v_fmac_f32_e32 v17, v213, v92
	s_waitcnt lgkmcnt(8)
	v_fmac_f32_e32 v16, v213, v94
	v_fmac_f32_e32 v31, v213, v96
	s_waitcnt lgkmcnt(7)
	v_fmac_f32_e32 v32, v213, v98
	v_fmac_f32_e32 v33, v213, v100
	s_waitcnt lgkmcnt(6)
	v_fmac_f32_e32 v36, v213, v102
	v_fmac_f32_e32 v37, v213, v104
	s_waitcnt lgkmcnt(5)
	v_fmac_f32_e32 v38, v213, v106
	v_fmac_f32_e32 v39, v213, v108
	s_waitcnt lgkmcnt(4)
	v_fmac_f32_e32 v40, v213, v110
	v_fmac_f32_e32 v41, v213, v112
	s_waitcnt lgkmcnt(3)
	v_fmac_f32_e32 v44, v213, v114
	v_fmac_f32_e32 v45, v213, v116
	s_waitcnt lgkmcnt(2)
	v_fmac_f32_e32 v46, v213, v118
	v_fmac_f32_e32 v47, v213, v120
	s_waitcnt lgkmcnt(1)
	v_fmac_f32_e32 v48, v213, v122
	v_fmac_f32_e32 v49, v213, v124
	s_waitcnt lgkmcnt(0)
	v_fmac_f32_e32 v60, v213, v128
	v_fmac_f32_e32 v30, v214, v63
	v_fmac_f32_e32 v43, v214, v65
	v_fmac_f32_e32 v42, v214, v67
	v_fmac_f32_e32 v35, v214, v69
	v_fmac_f32_e32 v34, v214, v71
	v_fmac_f32_e32 v29, v214, v73
	v_fmac_f32_e32 v28, v214, v75
	v_fmac_f32_e32 v27, v214, v77
	v_fmac_f32_e32 v26, v214, v79
	v_fmac_f32_e32 v25, v214, v81
	v_fmac_f32_e32 v24, v214, v83
	v_fmac_f32_e32 v23, v214, v85
	v_fmac_f32_e32 v22, v214, v87
	v_fmac_f32_e32 v21, v214, v89
	v_fmac_f32_e32 v20, v214, v91
	v_fmac_f32_e32 v17, v214, v93
	v_fmac_f32_e32 v16, v214, v95
	v_fmac_f32_e32 v31, v214, v97
	v_fmac_f32_e32 v32, v214, v99
	v_fmac_f32_e32 v33, v214, v101
	v_fmac_f32_e32 v36, v214, v103
	v_fmac_f32_e32 v37, v214, v105
	v_fmac_f32_e32 v38, v214, v107
	v_fmac_f32_e32 v39, v214, v109
	v_fmac_f32_e32 v40, v214, v111
	v_fmac_f32_e32 v41, v214, v113
	v_fmac_f32_e32 v44, v214, v115
	v_fmac_f32_e32 v45, v214, v117
	v_fmac_f32_e32 v46, v214, v119
	v_fmac_f32_e32 v47, v214, v121
	v_fmac_f32_e32 v48, v214, v123
	v_fmac_f32_e32 v49, v214, v125
	v_fmac_f32_e32 v60, v214, v129
	v_add_u32_e32 v61, 200, v57
	v_add_u32_e32 v150, 200, v149
	ds_read2st64_b64 v[62:65], v61 offset1:4
	ds_read2st64_b64 v[66:69], v61 offset0:8 offset1:12
	ds_read2st64_b64 v[70:73], v61 offset0:16 offset1:20
	ds_read2st64_b64 v[74:77], v61 offset0:24 offset1:28
	ds_read2st64_b64 v[78:81], v61 offset0:32 offset1:36
	ds_read2st64_b64 v[82:85], v61 offset0:40 offset1:44
	ds_read2st64_b64 v[86:89], v61 offset0:48 offset1:52
	ds_read2st64_b64 v[90:93], v61 offset0:56 offset1:60
	ds_read2st64_b64 v[94:97], v61 offset0:64 offset1:68
	ds_read2st64_b64 v[98:101], v61 offset0:72 offset1:76
	ds_read2st64_b64 v[102:105], v61 offset0:80 offset1:84
	ds_read2st64_b64 v[106:109], v61 offset0:88 offset1:92
	ds_read2st64_b64 v[110:113], v61 offset0:96 offset1:100
	ds_read2st64_b64 v[114:117], v61 offset0:104 offset1:108
	ds_read2st64_b64 v[118:121], v61 offset0:112 offset1:116
	ds_read2st64_b64 v[122:125], v61 offset0:120 offset1:124
	ds_read_b64 v[128:129], v150
	s_waitcnt vmcnt(12)
	s_waitcnt lgkmcnt(15)
	v_fmac_f32_e32 v30, v215, v62
	v_fmac_f32_e32 v43, v215, v64
	s_waitcnt lgkmcnt(15)
	v_fmac_f32_e32 v42, v215, v66
	v_fmac_f32_e32 v35, v215, v68
	s_waitcnt lgkmcnt(14)
	v_fmac_f32_e32 v34, v215, v70
	v_fmac_f32_e32 v29, v215, v72
	s_waitcnt lgkmcnt(13)
	v_fmac_f32_e32 v28, v215, v74
	v_fmac_f32_e32 v27, v215, v76
	s_waitcnt lgkmcnt(12)
	v_fmac_f32_e32 v26, v215, v78
	v_fmac_f32_e32 v25, v215, v80
	s_waitcnt lgkmcnt(11)
	v_fmac_f32_e32 v24, v215, v82
	v_fmac_f32_e32 v23, v215, v84
	s_waitcnt lgkmcnt(10)
	v_fmac_f32_e32 v22, v215, v86
	v_fmac_f32_e32 v21, v215, v88
	s_waitcnt lgkmcnt(9)
	v_fmac_f32_e32 v20, v215, v90
	v_fmac_f32_e32 v17, v215, v92
	s_waitcnt lgkmcnt(8)
	v_fmac_f32_e32 v16, v215, v94
	v_fmac_f32_e32 v31, v215, v96
	s_waitcnt lgkmcnt(7)
	v_fmac_f32_e32 v32, v215, v98
	v_fmac_f32_e32 v33, v215, v100
	s_waitcnt lgkmcnt(6)
	v_fmac_f32_e32 v36, v215, v102
	v_fmac_f32_e32 v37, v215, v104
	s_waitcnt lgkmcnt(5)
	v_fmac_f32_e32 v38, v215, v106
	v_fmac_f32_e32 v39, v215, v108
	s_waitcnt lgkmcnt(4)
	v_fmac_f32_e32 v40, v215, v110
	v_fmac_f32_e32 v41, v215, v112
	s_waitcnt lgkmcnt(3)
	v_fmac_f32_e32 v44, v215, v114
	v_fmac_f32_e32 v45, v215, v116
	s_waitcnt lgkmcnt(2)
	v_fmac_f32_e32 v46, v215, v118
	v_fmac_f32_e32 v47, v215, v120
	s_waitcnt lgkmcnt(1)
	v_fmac_f32_e32 v48, v215, v122
	v_fmac_f32_e32 v49, v215, v124
	s_waitcnt lgkmcnt(0)
	v_fmac_f32_e32 v60, v215, v128
	v_fmac_f32_e32 v30, v216, v63
	v_fmac_f32_e32 v43, v216, v65
	v_fmac_f32_e32 v42, v216, v67
	v_fmac_f32_e32 v35, v216, v69
	v_fmac_f32_e32 v34, v216, v71
	v_fmac_f32_e32 v29, v216, v73
	v_fmac_f32_e32 v28, v216, v75
	v_fmac_f32_e32 v27, v216, v77
	v_fmac_f32_e32 v26, v216, v79
	v_fmac_f32_e32 v25, v216, v81
	v_fmac_f32_e32 v24, v216, v83
	v_fmac_f32_e32 v23, v216, v85
	v_fmac_f32_e32 v22, v216, v87
	v_fmac_f32_e32 v21, v216, v89
	v_fmac_f32_e32 v20, v216, v91
	v_fmac_f32_e32 v17, v216, v93
	v_fmac_f32_e32 v16, v216, v95
	v_fmac_f32_e32 v31, v216, v97
	v_fmac_f32_e32 v32, v216, v99
	v_fmac_f32_e32 v33, v216, v101
	v_fmac_f32_e32 v36, v216, v103
	v_fmac_f32_e32 v37, v216, v105
	v_fmac_f32_e32 v38, v216, v107
	v_fmac_f32_e32 v39, v216, v109
	v_fmac_f32_e32 v40, v216, v111
	v_fmac_f32_e32 v41, v216, v113
	v_fmac_f32_e32 v44, v216, v115
	v_fmac_f32_e32 v45, v216, v117
	v_fmac_f32_e32 v46, v216, v119
	v_fmac_f32_e32 v47, v216, v121
	v_fmac_f32_e32 v48, v216, v123
	v_fmac_f32_e32 v49, v216, v125
	v_fmac_f32_e32 v60, v216, v129
	v_add_u32_e32 v61, 208, v57
	v_add_u32_e32 v150, 208, v149
	ds_read2st64_b64 v[62:65], v61 offset1:4
	ds_read2st64_b64 v[66:69], v61 offset0:8 offset1:12
	ds_read2st64_b64 v[70:73], v61 offset0:16 offset1:20
	ds_read2st64_b64 v[74:77], v61 offset0:24 offset1:28
	ds_read2st64_b64 v[78:81], v61 offset0:32 offset1:36
	ds_read2st64_b64 v[82:85], v61 offset0:40 offset1:44
	ds_read2st64_b64 v[86:89], v61 offset0:48 offset1:52
	ds_read2st64_b64 v[90:93], v61 offset0:56 offset1:60
	ds_read2st64_b64 v[94:97], v61 offset0:64 offset1:68
	ds_read2st64_b64 v[98:101], v61 offset0:72 offset1:76
	ds_read2st64_b64 v[102:105], v61 offset0:80 offset1:84
	ds_read2st64_b64 v[106:109], v61 offset0:88 offset1:92
	ds_read2st64_b64 v[110:113], v61 offset0:96 offset1:100
	ds_read2st64_b64 v[114:117], v61 offset0:104 offset1:108
	ds_read2st64_b64 v[118:121], v61 offset0:112 offset1:116
	ds_read2st64_b64 v[122:125], v61 offset0:120 offset1:124
	ds_read_b64 v[128:129], v150
	s_waitcnt vmcnt(10)
	s_waitcnt lgkmcnt(15)
	v_fmac_f32_e32 v30, v217, v62
	v_fmac_f32_e32 v43, v217, v64
	s_waitcnt lgkmcnt(15)
	v_fmac_f32_e32 v42, v217, v66
	v_fmac_f32_e32 v35, v217, v68
	s_waitcnt lgkmcnt(14)
	v_fmac_f32_e32 v34, v217, v70
	v_fmac_f32_e32 v29, v217, v72
	s_waitcnt lgkmcnt(13)
	v_fmac_f32_e32 v28, v217, v74
	v_fmac_f32_e32 v27, v217, v76
	s_waitcnt lgkmcnt(12)
	v_fmac_f32_e32 v26, v217, v78
	v_fmac_f32_e32 v25, v217, v80
	s_waitcnt lgkmcnt(11)
	v_fmac_f32_e32 v24, v217, v82
	v_fmac_f32_e32 v23, v217, v84
	s_waitcnt lgkmcnt(10)
	v_fmac_f32_e32 v22, v217, v86
	v_fmac_f32_e32 v21, v217, v88
	s_waitcnt lgkmcnt(9)
	v_fmac_f32_e32 v20, v217, v90
	v_fmac_f32_e32 v17, v217, v92
	s_waitcnt lgkmcnt(8)
	v_fmac_f32_e32 v16, v217, v94
	v_fmac_f32_e32 v31, v217, v96
	s_waitcnt lgkmcnt(7)
	v_fmac_f32_e32 v32, v217, v98
	v_fmac_f32_e32 v33, v217, v100
	s_waitcnt lgkmcnt(6)
	v_fmac_f32_e32 v36, v217, v102
	v_fmac_f32_e32 v37, v217, v104
	s_waitcnt lgkmcnt(5)
	v_fmac_f32_e32 v38, v217, v106
	v_fmac_f32_e32 v39, v217, v108
	s_waitcnt lgkmcnt(4)
	v_fmac_f32_e32 v40, v217, v110
	v_fmac_f32_e32 v41, v217, v112
	s_waitcnt lgkmcnt(3)
	v_fmac_f32_e32 v44, v217, v114
	v_fmac_f32_e32 v45, v217, v116
	s_waitcnt lgkmcnt(2)
	v_fmac_f32_e32 v46, v217, v118
	v_fmac_f32_e32 v47, v217, v120
	s_waitcnt lgkmcnt(1)
	v_fmac_f32_e32 v48, v217, v122
	v_fmac_f32_e32 v49, v217, v124
	s_waitcnt lgkmcnt(0)
	v_fmac_f32_e32 v60, v217, v128
	v_fmac_f32_e32 v30, v218, v63
	v_fmac_f32_e32 v43, v218, v65
	v_fmac_f32_e32 v42, v218, v67
	v_fmac_f32_e32 v35, v218, v69
	v_fmac_f32_e32 v34, v218, v71
	v_fmac_f32_e32 v29, v218, v73
	v_fmac_f32_e32 v28, v218, v75
	v_fmac_f32_e32 v27, v218, v77
	v_fmac_f32_e32 v26, v218, v79
	v_fmac_f32_e32 v25, v218, v81
	v_fmac_f32_e32 v24, v218, v83
	v_fmac_f32_e32 v23, v218, v85
	v_fmac_f32_e32 v22, v218, v87
	v_fmac_f32_e32 v21, v218, v89
	v_fmac_f32_e32 v20, v218, v91
	v_fmac_f32_e32 v17, v218, v93
	v_fmac_f32_e32 v16, v218, v95
	v_fmac_f32_e32 v31, v218, v97
	v_fmac_f32_e32 v32, v218, v99
	v_fmac_f32_e32 v33, v218, v101
	v_fmac_f32_e32 v36, v218, v103
	v_fmac_f32_e32 v37, v218, v105
	v_fmac_f32_e32 v38, v218, v107
	v_fmac_f32_e32 v39, v218, v109
	v_fmac_f32_e32 v40, v218, v111
	v_fmac_f32_e32 v41, v218, v113
	v_fmac_f32_e32 v44, v218, v115
	v_fmac_f32_e32 v45, v218, v117
	v_fmac_f32_e32 v46, v218, v119
	v_fmac_f32_e32 v47, v218, v121
	v_fmac_f32_e32 v48, v218, v123
	v_fmac_f32_e32 v49, v218, v125
	v_fmac_f32_e32 v60, v218, v129
	v_add_u32_e32 v61, 216, v57
	v_add_u32_e32 v150, 216, v149
	ds_read2st64_b64 v[62:65], v61 offset1:4
	ds_read2st64_b64 v[66:69], v61 offset0:8 offset1:12
	ds_read2st64_b64 v[70:73], v61 offset0:16 offset1:20
	ds_read2st64_b64 v[74:77], v61 offset0:24 offset1:28
	ds_read2st64_b64 v[78:81], v61 offset0:32 offset1:36
	ds_read2st64_b64 v[82:85], v61 offset0:40 offset1:44
	ds_read2st64_b64 v[86:89], v61 offset0:48 offset1:52
	ds_read2st64_b64 v[90:93], v61 offset0:56 offset1:60
	ds_read2st64_b64 v[94:97], v61 offset0:64 offset1:68
	ds_read2st64_b64 v[98:101], v61 offset0:72 offset1:76
	ds_read2st64_b64 v[102:105], v61 offset0:80 offset1:84
	ds_read2st64_b64 v[106:109], v61 offset0:88 offset1:92
	ds_read2st64_b64 v[110:113], v61 offset0:96 offset1:100
	ds_read2st64_b64 v[114:117], v61 offset0:104 offset1:108
	ds_read2st64_b64 v[118:121], v61 offset0:112 offset1:116
	ds_read2st64_b64 v[122:125], v61 offset0:120 offset1:124
	ds_read_b64 v[128:129], v150
	s_waitcnt vmcnt(8)
	s_waitcnt lgkmcnt(15)
	v_fmac_f32_e32 v30, v219, v62
	v_fmac_f32_e32 v43, v219, v64
	s_waitcnt lgkmcnt(15)
	v_fmac_f32_e32 v42, v219, v66
	v_fmac_f32_e32 v35, v219, v68
	s_waitcnt lgkmcnt(14)
	v_fmac_f32_e32 v34, v219, v70
	v_fmac_f32_e32 v29, v219, v72
	s_waitcnt lgkmcnt(13)
	v_fmac_f32_e32 v28, v219, v74
	v_fmac_f32_e32 v27, v219, v76
	s_waitcnt lgkmcnt(12)
	v_fmac_f32_e32 v26, v219, v78
	v_fmac_f32_e32 v25, v219, v80
	s_waitcnt lgkmcnt(11)
	v_fmac_f32_e32 v24, v219, v82
	v_fmac_f32_e32 v23, v219, v84
	s_waitcnt lgkmcnt(10)
	v_fmac_f32_e32 v22, v219, v86
	v_fmac_f32_e32 v21, v219, v88
	s_waitcnt lgkmcnt(9)
	v_fmac_f32_e32 v20, v219, v90
	v_fmac_f32_e32 v17, v219, v92
	s_waitcnt lgkmcnt(8)
	v_fmac_f32_e32 v16, v219, v94
	v_fmac_f32_e32 v31, v219, v96
	s_waitcnt lgkmcnt(7)
	v_fmac_f32_e32 v32, v219, v98
	v_fmac_f32_e32 v33, v219, v100
	s_waitcnt lgkmcnt(6)
	v_fmac_f32_e32 v36, v219, v102
	v_fmac_f32_e32 v37, v219, v104
	s_waitcnt lgkmcnt(5)
	v_fmac_f32_e32 v38, v219, v106
	v_fmac_f32_e32 v39, v219, v108
	s_waitcnt lgkmcnt(4)
	v_fmac_f32_e32 v40, v219, v110
	v_fmac_f32_e32 v41, v219, v112
	s_waitcnt lgkmcnt(3)
	v_fmac_f32_e32 v44, v219, v114
	v_fmac_f32_e32 v45, v219, v116
	s_waitcnt lgkmcnt(2)
	v_fmac_f32_e32 v46, v219, v118
	v_fmac_f32_e32 v47, v219, v120
	s_waitcnt lgkmcnt(1)
	v_fmac_f32_e32 v48, v219, v122
	v_fmac_f32_e32 v49, v219, v124
	s_waitcnt lgkmcnt(0)
	v_fmac_f32_e32 v60, v219, v128
	v_fmac_f32_e32 v30, v220, v63
	v_fmac_f32_e32 v43, v220, v65
	v_fmac_f32_e32 v42, v220, v67
	v_fmac_f32_e32 v35, v220, v69
	v_fmac_f32_e32 v34, v220, v71
	v_fmac_f32_e32 v29, v220, v73
	v_fmac_f32_e32 v28, v220, v75
	v_fmac_f32_e32 v27, v220, v77
	v_fmac_f32_e32 v26, v220, v79
	v_fmac_f32_e32 v25, v220, v81
	v_fmac_f32_e32 v24, v220, v83
	v_fmac_f32_e32 v23, v220, v85
	v_fmac_f32_e32 v22, v220, v87
	v_fmac_f32_e32 v21, v220, v89
	v_fmac_f32_e32 v20, v220, v91
	v_fmac_f32_e32 v17, v220, v93
	v_fmac_f32_e32 v16, v220, v95
	v_fmac_f32_e32 v31, v220, v97
	v_fmac_f32_e32 v32, v220, v99
	v_fmac_f32_e32 v33, v220, v101
	v_fmac_f32_e32 v36, v220, v103
	v_fmac_f32_e32 v37, v220, v105
	v_fmac_f32_e32 v38, v220, v107
	v_fmac_f32_e32 v39, v220, v109
	v_fmac_f32_e32 v40, v220, v111
	v_fmac_f32_e32 v41, v220, v113
	v_fmac_f32_e32 v44, v220, v115
	v_fmac_f32_e32 v45, v220, v117
	v_fmac_f32_e32 v46, v220, v119
	v_fmac_f32_e32 v47, v220, v121
	v_fmac_f32_e32 v48, v220, v123
	v_fmac_f32_e32 v49, v220, v125
	v_fmac_f32_e32 v60, v220, v129
	v_add_u32_e32 v61, 224, v57
	v_add_u32_e32 v150, 224, v149
	ds_read2st64_b64 v[62:65], v61 offset1:4
	ds_read2st64_b64 v[66:69], v61 offset0:8 offset1:12
	ds_read2st64_b64 v[70:73], v61 offset0:16 offset1:20
	ds_read2st64_b64 v[74:77], v61 offset0:24 offset1:28
	ds_read2st64_b64 v[78:81], v61 offset0:32 offset1:36
	ds_read2st64_b64 v[82:85], v61 offset0:40 offset1:44
	ds_read2st64_b64 v[86:89], v61 offset0:48 offset1:52
	ds_read2st64_b64 v[90:93], v61 offset0:56 offset1:60
	ds_read2st64_b64 v[94:97], v61 offset0:64 offset1:68
	ds_read2st64_b64 v[98:101], v61 offset0:72 offset1:76
	ds_read2st64_b64 v[102:105], v61 offset0:80 offset1:84
	ds_read2st64_b64 v[106:109], v61 offset0:88 offset1:92
	ds_read2st64_b64 v[110:113], v61 offset0:96 offset1:100
	ds_read2st64_b64 v[114:117], v61 offset0:104 offset1:108
	ds_read2st64_b64 v[118:121], v61 offset0:112 offset1:116
	ds_read2st64_b64 v[122:125], v61 offset0:120 offset1:124
	ds_read_b64 v[128:129], v150
	s_waitcnt vmcnt(6)
	s_waitcnt lgkmcnt(15)
	v_fmac_f32_e32 v30, v221, v62
	v_fmac_f32_e32 v43, v221, v64
	s_waitcnt lgkmcnt(15)
	v_fmac_f32_e32 v42, v221, v66
	v_fmac_f32_e32 v35, v221, v68
	s_waitcnt lgkmcnt(14)
	v_fmac_f32_e32 v34, v221, v70
	v_fmac_f32_e32 v29, v221, v72
	s_waitcnt lgkmcnt(13)
	v_fmac_f32_e32 v28, v221, v74
	v_fmac_f32_e32 v27, v221, v76
	s_waitcnt lgkmcnt(12)
	v_fmac_f32_e32 v26, v221, v78
	v_fmac_f32_e32 v25, v221, v80
	s_waitcnt lgkmcnt(11)
	v_fmac_f32_e32 v24, v221, v82
	v_fmac_f32_e32 v23, v221, v84
	s_waitcnt lgkmcnt(10)
	v_fmac_f32_e32 v22, v221, v86
	v_fmac_f32_e32 v21, v221, v88
	s_waitcnt lgkmcnt(9)
	v_fmac_f32_e32 v20, v221, v90
	v_fmac_f32_e32 v17, v221, v92
	s_waitcnt lgkmcnt(8)
	v_fmac_f32_e32 v16, v221, v94
	v_fmac_f32_e32 v31, v221, v96
	s_waitcnt lgkmcnt(7)
	v_fmac_f32_e32 v32, v221, v98
	v_fmac_f32_e32 v33, v221, v100
	s_waitcnt lgkmcnt(6)
	v_fmac_f32_e32 v36, v221, v102
	v_fmac_f32_e32 v37, v221, v104
	s_waitcnt lgkmcnt(5)
	v_fmac_f32_e32 v38, v221, v106
	v_fmac_f32_e32 v39, v221, v108
	s_waitcnt lgkmcnt(4)
	v_fmac_f32_e32 v40, v221, v110
	v_fmac_f32_e32 v41, v221, v112
	s_waitcnt lgkmcnt(3)
	v_fmac_f32_e32 v44, v221, v114
	v_fmac_f32_e32 v45, v221, v116
	s_waitcnt lgkmcnt(2)
	v_fmac_f32_e32 v46, v221, v118
	v_fmac_f32_e32 v47, v221, v120
	s_waitcnt lgkmcnt(1)
	v_fmac_f32_e32 v48, v221, v122
	v_fmac_f32_e32 v49, v221, v124
	s_waitcnt lgkmcnt(0)
	v_fmac_f32_e32 v60, v221, v128
	v_fmac_f32_e32 v30, v222, v63
	v_fmac_f32_e32 v43, v222, v65
	v_fmac_f32_e32 v42, v222, v67
	v_fmac_f32_e32 v35, v222, v69
	v_fmac_f32_e32 v34, v222, v71
	v_fmac_f32_e32 v29, v222, v73
	v_fmac_f32_e32 v28, v222, v75
	v_fmac_f32_e32 v27, v222, v77
	v_fmac_f32_e32 v26, v222, v79
	v_fmac_f32_e32 v25, v222, v81
	v_fmac_f32_e32 v24, v222, v83
	v_fmac_f32_e32 v23, v222, v85
	v_fmac_f32_e32 v22, v222, v87
	v_fmac_f32_e32 v21, v222, v89
	v_fmac_f32_e32 v20, v222, v91
	v_fmac_f32_e32 v17, v222, v93
	v_fmac_f32_e32 v16, v222, v95
	v_fmac_f32_e32 v31, v222, v97
	v_fmac_f32_e32 v32, v222, v99
	v_fmac_f32_e32 v33, v222, v101
	v_fmac_f32_e32 v36, v222, v103
	v_fmac_f32_e32 v37, v222, v105
	v_fmac_f32_e32 v38, v222, v107
	v_fmac_f32_e32 v39, v222, v109
	v_fmac_f32_e32 v40, v222, v111
	v_fmac_f32_e32 v41, v222, v113
	v_fmac_f32_e32 v44, v222, v115
	v_fmac_f32_e32 v45, v222, v117
	v_fmac_f32_e32 v46, v222, v119
	v_fmac_f32_e32 v47, v222, v121
	v_fmac_f32_e32 v48, v222, v123
	v_fmac_f32_e32 v49, v222, v125
	v_fmac_f32_e32 v60, v222, v129
	v_add_u32_e32 v61, 232, v57
	v_add_u32_e32 v150, 232, v149
	ds_read2st64_b64 v[62:65], v61 offset1:4
	ds_read2st64_b64 v[66:69], v61 offset0:8 offset1:12
	ds_read2st64_b64 v[70:73], v61 offset0:16 offset1:20
	ds_read2st64_b64 v[74:77], v61 offset0:24 offset1:28
	ds_read2st64_b64 v[78:81], v61 offset0:32 offset1:36
	ds_read2st64_b64 v[82:85], v61 offset0:40 offset1:44
	ds_read2st64_b64 v[86:89], v61 offset0:48 offset1:52
	ds_read2st64_b64 v[90:93], v61 offset0:56 offset1:60
	ds_read2st64_b64 v[94:97], v61 offset0:64 offset1:68
	ds_read2st64_b64 v[98:101], v61 offset0:72 offset1:76
	ds_read2st64_b64 v[102:105], v61 offset0:80 offset1:84
	ds_read2st64_b64 v[106:109], v61 offset0:88 offset1:92
	ds_read2st64_b64 v[110:113], v61 offset0:96 offset1:100
	ds_read2st64_b64 v[114:117], v61 offset0:104 offset1:108
	ds_read2st64_b64 v[118:121], v61 offset0:112 offset1:116
	ds_read2st64_b64 v[122:125], v61 offset0:120 offset1:124
	ds_read_b64 v[128:129], v150
	s_waitcnt vmcnt(4)
	s_waitcnt lgkmcnt(15)
	v_fmac_f32_e32 v30, v223, v62
	v_fmac_f32_e32 v43, v223, v64
	s_waitcnt lgkmcnt(15)
	v_fmac_f32_e32 v42, v223, v66
	v_fmac_f32_e32 v35, v223, v68
	s_waitcnt lgkmcnt(14)
	v_fmac_f32_e32 v34, v223, v70
	v_fmac_f32_e32 v29, v223, v72
	s_waitcnt lgkmcnt(13)
	v_fmac_f32_e32 v28, v223, v74
	v_fmac_f32_e32 v27, v223, v76
	s_waitcnt lgkmcnt(12)
	v_fmac_f32_e32 v26, v223, v78
	v_fmac_f32_e32 v25, v223, v80
	s_waitcnt lgkmcnt(11)
	v_fmac_f32_e32 v24, v223, v82
	v_fmac_f32_e32 v23, v223, v84
	s_waitcnt lgkmcnt(10)
	v_fmac_f32_e32 v22, v223, v86
	v_fmac_f32_e32 v21, v223, v88
	s_waitcnt lgkmcnt(9)
	v_fmac_f32_e32 v20, v223, v90
	v_fmac_f32_e32 v17, v223, v92
	s_waitcnt lgkmcnt(8)
	v_fmac_f32_e32 v16, v223, v94
	v_fmac_f32_e32 v31, v223, v96
	s_waitcnt lgkmcnt(7)
	v_fmac_f32_e32 v32, v223, v98
	v_fmac_f32_e32 v33, v223, v100
	s_waitcnt lgkmcnt(6)
	v_fmac_f32_e32 v36, v223, v102
	v_fmac_f32_e32 v37, v223, v104
	s_waitcnt lgkmcnt(5)
	v_fmac_f32_e32 v38, v223, v106
	v_fmac_f32_e32 v39, v223, v108
	s_waitcnt lgkmcnt(4)
	v_fmac_f32_e32 v40, v223, v110
	v_fmac_f32_e32 v41, v223, v112
	s_waitcnt lgkmcnt(3)
	v_fmac_f32_e32 v44, v223, v114
	v_fmac_f32_e32 v45, v223, v116
	s_waitcnt lgkmcnt(2)
	v_fmac_f32_e32 v46, v223, v118
	v_fmac_f32_e32 v47, v223, v120
	s_waitcnt lgkmcnt(1)
	v_fmac_f32_e32 v48, v223, v122
	v_fmac_f32_e32 v49, v223, v124
	s_waitcnt lgkmcnt(0)
	v_fmac_f32_e32 v60, v223, v128
	v_fmac_f32_e32 v30, v224, v63
	v_fmac_f32_e32 v43, v224, v65
	v_fmac_f32_e32 v42, v224, v67
	v_fmac_f32_e32 v35, v224, v69
	v_fmac_f32_e32 v34, v224, v71
	v_fmac_f32_e32 v29, v224, v73
	v_fmac_f32_e32 v28, v224, v75
	v_fmac_f32_e32 v27, v224, v77
	v_fmac_f32_e32 v26, v224, v79
	v_fmac_f32_e32 v25, v224, v81
	v_fmac_f32_e32 v24, v224, v83
	v_fmac_f32_e32 v23, v224, v85
	v_fmac_f32_e32 v22, v224, v87
	v_fmac_f32_e32 v21, v224, v89
	v_fmac_f32_e32 v20, v224, v91
	v_fmac_f32_e32 v17, v224, v93
	v_fmac_f32_e32 v16, v224, v95
	v_fmac_f32_e32 v31, v224, v97
	v_fmac_f32_e32 v32, v224, v99
	v_fmac_f32_e32 v33, v224, v101
	v_fmac_f32_e32 v36, v224, v103
	v_fmac_f32_e32 v37, v224, v105
	v_fmac_f32_e32 v38, v224, v107
	v_fmac_f32_e32 v39, v224, v109
	v_fmac_f32_e32 v40, v224, v111
	v_fmac_f32_e32 v41, v224, v113
	v_fmac_f32_e32 v44, v224, v115
	v_fmac_f32_e32 v45, v224, v117
	v_fmac_f32_e32 v46, v224, v119
	v_fmac_f32_e32 v47, v224, v121
	v_fmac_f32_e32 v48, v224, v123
	v_fmac_f32_e32 v49, v224, v125
	v_fmac_f32_e32 v60, v224, v129
	v_add_u32_e32 v61, 240, v57
	v_add_u32_e32 v150, 240, v149
	ds_read2st64_b64 v[62:65], v61 offset1:4
	ds_read2st64_b64 v[66:69], v61 offset0:8 offset1:12
	ds_read2st64_b64 v[70:73], v61 offset0:16 offset1:20
	ds_read2st64_b64 v[74:77], v61 offset0:24 offset1:28
	ds_read2st64_b64 v[78:81], v61 offset0:32 offset1:36
	ds_read2st64_b64 v[82:85], v61 offset0:40 offset1:44
	ds_read2st64_b64 v[86:89], v61 offset0:48 offset1:52
	ds_read2st64_b64 v[90:93], v61 offset0:56 offset1:60
	ds_read2st64_b64 v[94:97], v61 offset0:64 offset1:68
	ds_read2st64_b64 v[98:101], v61 offset0:72 offset1:76
	ds_read2st64_b64 v[102:105], v61 offset0:80 offset1:84
	ds_read2st64_b64 v[106:109], v61 offset0:88 offset1:92
	ds_read2st64_b64 v[110:113], v61 offset0:96 offset1:100
	ds_read2st64_b64 v[114:117], v61 offset0:104 offset1:108
	ds_read2st64_b64 v[118:121], v61 offset0:112 offset1:116
	ds_read2st64_b64 v[122:125], v61 offset0:120 offset1:124
	ds_read_b64 v[128:129], v150
	s_waitcnt vmcnt(2)
	s_waitcnt lgkmcnt(15)
	v_fmac_f32_e32 v30, v225, v62
	v_fmac_f32_e32 v43, v225, v64
	s_waitcnt lgkmcnt(15)
	v_fmac_f32_e32 v42, v225, v66
	v_fmac_f32_e32 v35, v225, v68
	s_waitcnt lgkmcnt(14)
	v_fmac_f32_e32 v34, v225, v70
	v_fmac_f32_e32 v29, v225, v72
	s_waitcnt lgkmcnt(13)
	v_fmac_f32_e32 v28, v225, v74
	v_fmac_f32_e32 v27, v225, v76
	s_waitcnt lgkmcnt(12)
	v_fmac_f32_e32 v26, v225, v78
	v_fmac_f32_e32 v25, v225, v80
	s_waitcnt lgkmcnt(11)
	v_fmac_f32_e32 v24, v225, v82
	v_fmac_f32_e32 v23, v225, v84
	s_waitcnt lgkmcnt(10)
	v_fmac_f32_e32 v22, v225, v86
	v_fmac_f32_e32 v21, v225, v88
	s_waitcnt lgkmcnt(9)
	v_fmac_f32_e32 v20, v225, v90
	v_fmac_f32_e32 v17, v225, v92
	s_waitcnt lgkmcnt(8)
	v_fmac_f32_e32 v16, v225, v94
	v_fmac_f32_e32 v31, v225, v96
	s_waitcnt lgkmcnt(7)
	v_fmac_f32_e32 v32, v225, v98
	v_fmac_f32_e32 v33, v225, v100
	s_waitcnt lgkmcnt(6)
	v_fmac_f32_e32 v36, v225, v102
	v_fmac_f32_e32 v37, v225, v104
	s_waitcnt lgkmcnt(5)
	v_fmac_f32_e32 v38, v225, v106
	v_fmac_f32_e32 v39, v225, v108
	s_waitcnt lgkmcnt(4)
	v_fmac_f32_e32 v40, v225, v110
	v_fmac_f32_e32 v41, v225, v112
	s_waitcnt lgkmcnt(3)
	v_fmac_f32_e32 v44, v225, v114
	v_fmac_f32_e32 v45, v225, v116
	s_waitcnt lgkmcnt(2)
	v_fmac_f32_e32 v46, v225, v118
	v_fmac_f32_e32 v47, v225, v120
	s_waitcnt lgkmcnt(1)
	v_fmac_f32_e32 v48, v225, v122
	v_fmac_f32_e32 v49, v225, v124
	s_waitcnt lgkmcnt(0)
	v_fmac_f32_e32 v60, v225, v128
	v_fmac_f32_e32 v30, v226, v63
	v_fmac_f32_e32 v43, v226, v65
	v_fmac_f32_e32 v42, v226, v67
	v_fmac_f32_e32 v35, v226, v69
	v_fmac_f32_e32 v34, v226, v71
	v_fmac_f32_e32 v29, v226, v73
	v_fmac_f32_e32 v28, v226, v75
	v_fmac_f32_e32 v27, v226, v77
	v_fmac_f32_e32 v26, v226, v79
	v_fmac_f32_e32 v25, v226, v81
	v_fmac_f32_e32 v24, v226, v83
	v_fmac_f32_e32 v23, v226, v85
	v_fmac_f32_e32 v22, v226, v87
	v_fmac_f32_e32 v21, v226, v89
	v_fmac_f32_e32 v20, v226, v91
	v_fmac_f32_e32 v17, v226, v93
	v_fmac_f32_e32 v16, v226, v95
	v_fmac_f32_e32 v31, v226, v97
	v_fmac_f32_e32 v32, v226, v99
	v_fmac_f32_e32 v33, v226, v101
	v_fmac_f32_e32 v36, v226, v103
	v_fmac_f32_e32 v37, v226, v105
	v_fmac_f32_e32 v38, v226, v107
	v_fmac_f32_e32 v39, v226, v109
	v_fmac_f32_e32 v40, v226, v111
	v_fmac_f32_e32 v41, v226, v113
	v_fmac_f32_e32 v44, v226, v115
	v_fmac_f32_e32 v45, v226, v117
	v_fmac_f32_e32 v46, v226, v119
	v_fmac_f32_e32 v47, v226, v121
	v_fmac_f32_e32 v48, v226, v123
	v_fmac_f32_e32 v49, v226, v125
	v_fmac_f32_e32 v60, v226, v129
	v_add_u32_e32 v61, 248, v57
	v_add_u32_e32 v150, 248, v149
	ds_read2st64_b64 v[62:65], v61 offset1:4
	ds_read2st64_b64 v[66:69], v61 offset0:8 offset1:12
	ds_read2st64_b64 v[70:73], v61 offset0:16 offset1:20
	ds_read2st64_b64 v[74:77], v61 offset0:24 offset1:28
	ds_read2st64_b64 v[78:81], v61 offset0:32 offset1:36
	ds_read2st64_b64 v[82:85], v61 offset0:40 offset1:44
	ds_read2st64_b64 v[86:89], v61 offset0:48 offset1:52
	ds_read2st64_b64 v[90:93], v61 offset0:56 offset1:60
	ds_read2st64_b64 v[94:97], v61 offset0:64 offset1:68
	ds_read2st64_b64 v[98:101], v61 offset0:72 offset1:76
	ds_read2st64_b64 v[102:105], v61 offset0:80 offset1:84
	ds_read2st64_b64 v[106:109], v61 offset0:88 offset1:92
	ds_read2st64_b64 v[110:113], v61 offset0:96 offset1:100
	ds_read2st64_b64 v[114:117], v61 offset0:104 offset1:108
	ds_read2st64_b64 v[118:121], v61 offset0:112 offset1:116
	ds_read2st64_b64 v[122:125], v61 offset0:120 offset1:124
	ds_read_b64 v[128:129], v150
	s_waitcnt vmcnt(0)
	s_waitcnt lgkmcnt(15)
	v_fmac_f32_e32 v30, v227, v62
	v_fmac_f32_e32 v43, v227, v64
	s_waitcnt lgkmcnt(15)
	v_fmac_f32_e32 v42, v227, v66
	v_fmac_f32_e32 v35, v227, v68
	s_waitcnt lgkmcnt(14)
	v_fmac_f32_e32 v34, v227, v70
	v_fmac_f32_e32 v29, v227, v72
	s_waitcnt lgkmcnt(13)
	v_fmac_f32_e32 v28, v227, v74
	v_fmac_f32_e32 v27, v227, v76
	s_waitcnt lgkmcnt(12)
	v_fmac_f32_e32 v26, v227, v78
	v_fmac_f32_e32 v25, v227, v80
	s_waitcnt lgkmcnt(11)
	v_fmac_f32_e32 v24, v227, v82
	v_fmac_f32_e32 v23, v227, v84
	s_waitcnt lgkmcnt(10)
	v_fmac_f32_e32 v22, v227, v86
	v_fmac_f32_e32 v21, v227, v88
	s_waitcnt lgkmcnt(9)
	v_fmac_f32_e32 v20, v227, v90
	v_fmac_f32_e32 v17, v227, v92
	s_waitcnt lgkmcnt(8)
	v_fmac_f32_e32 v16, v227, v94
	v_fmac_f32_e32 v31, v227, v96
	s_waitcnt lgkmcnt(7)
	v_fmac_f32_e32 v32, v227, v98
	v_fmac_f32_e32 v33, v227, v100
	s_waitcnt lgkmcnt(6)
	v_fmac_f32_e32 v36, v227, v102
	v_fmac_f32_e32 v37, v227, v104
	s_waitcnt lgkmcnt(5)
	v_fmac_f32_e32 v38, v227, v106
	v_fmac_f32_e32 v39, v227, v108
	s_waitcnt lgkmcnt(4)
	v_fmac_f32_e32 v40, v227, v110
	v_fmac_f32_e32 v41, v227, v112
	s_waitcnt lgkmcnt(3)
	v_fmac_f32_e32 v44, v227, v114
	v_fmac_f32_e32 v45, v227, v116
	s_waitcnt lgkmcnt(2)
	v_fmac_f32_e32 v46, v227, v118
	v_fmac_f32_e32 v47, v227, v120
	s_waitcnt lgkmcnt(1)
	v_fmac_f32_e32 v48, v227, v122
	v_fmac_f32_e32 v49, v227, v124
	s_waitcnt lgkmcnt(0)
	v_fmac_f32_e32 v60, v227, v128
	v_fmac_f32_e32 v30, v228, v63
	v_fmac_f32_e32 v43, v228, v65
	v_fmac_f32_e32 v42, v228, v67
	v_fmac_f32_e32 v35, v228, v69
	v_fmac_f32_e32 v34, v228, v71
	v_fmac_f32_e32 v29, v228, v73
	v_fmac_f32_e32 v28, v228, v75
	v_fmac_f32_e32 v27, v228, v77
	v_fmac_f32_e32 v26, v228, v79
	v_fmac_f32_e32 v25, v228, v81
	v_fmac_f32_e32 v24, v228, v83
	v_fmac_f32_e32 v23, v228, v85
	v_fmac_f32_e32 v22, v228, v87
	v_fmac_f32_e32 v21, v228, v89
	v_fmac_f32_e32 v20, v228, v91
	v_fmac_f32_e32 v17, v228, v93
	v_fmac_f32_e32 v16, v228, v95
	v_fmac_f32_e32 v31, v228, v97
	v_fmac_f32_e32 v32, v228, v99
	v_fmac_f32_e32 v33, v228, v101
	v_fmac_f32_e32 v36, v228, v103
	v_fmac_f32_e32 v37, v228, v105
	v_fmac_f32_e32 v38, v228, v107
	v_fmac_f32_e32 v39, v228, v109
	v_fmac_f32_e32 v40, v228, v111
	v_fmac_f32_e32 v41, v228, v113
	v_fmac_f32_e32 v44, v228, v115
	v_fmac_f32_e32 v45, v228, v117
	v_fmac_f32_e32 v46, v228, v119
	v_fmac_f32_e32 v47, v228, v121
	v_fmac_f32_e32 v48, v228, v123
	v_fmac_f32_e32 v49, v228, v125
	v_fmac_f32_e32 v60, v228, v129
	s_barrier
	s_and_saveexec_b64 s[30:31], s[4:5]
	s_cbranch_execz .LBB0_38
	s_mov_b64 s[18:19], -1
	v_mov_b32_e32 v50, v18
	v_mov_b32_e32 v51, v55
	s_and_saveexec_b64 s[34:35], s[10:11]
	s_cbranch_execz .LBB0_35
	v_mov_b32_e32 v52, 0
	v_mov_b64_e32 v[50:51], v[18:19]
	s_and_saveexec_b64 s[42:43], s[12:13]
	s_cbranch_execz .LBB0_30
	s_mov_b32 s67, 0
	s_mov_b64 s[44:45], 0
	v_mov_b32_e32 v52, v54
	v_mov_b32_e32 v61, v56
	v_mov_b64_e32 v[50:51], v[18:19]

.LBB0_38:
	s_or_b64 exec, exec, s[30:31]
	v_lshl_add_u64 v[50:51], v[14:15], 0, s[28:29]
	s_mov_b32 s18, 0
	s_waitcnt lgkmcnt(0)
	s_barrier
	global_load_dword v164, v[50:51], off
	v_add_co_u32_e32 v62, vcc, s60, v50
	s_nop 1
	v_addc_co_u32_e32 v63, vcc, 0, v51, vcc
	v_lshl_add_u64 v[50:51], v[50:51], 0, s[24:25]
	global_load_dword v165, v[62:63], off
	global_load_dword v166, v[50:51], off
	v_add_co_u32_e32 v62, vcc, s60, v50
	s_nop 1
	v_addc_co_u32_e32 v63, vcc, 0, v51, vcc
	v_lshl_add_u64 v[50:51], v[50:51], 0, s[24:25]
	global_load_dword v167, v[62:63], off
	global_load_dword v168, v[50:51], off
	v_add_co_u32_e32 v62, vcc, s60, v50
	s_nop 1
	v_addc_co_u32_e32 v63, vcc, 0, v51, vcc
	v_lshl_add_u64 v[50:51], v[50:51], 0, s[24:25]
	global_load_dword v169, v[62:63], off
	global_load_dword v170, v[50:51], off
	v_add_co_u32_e32 v62, vcc, s60, v50
	s_nop 1
	v_addc_co_u32_e32 v63, vcc, 0, v51, vcc
	v_lshl_add_u64 v[50:51], v[50:51], 0, s[24:25]
	global_load_dword v171, v[62:63], off
	global_load_dword v172, v[50:51], off
	v_add_co_u32_e32 v62, vcc, s60, v50
	s_nop 1
	v_addc_co_u32_e32 v63, vcc, 0, v51, vcc
	v_lshl_add_u64 v[50:51], v[50:51], 0, s[24:25]
	global_load_dword v173, v[62:63], off
	global_load_dword v174, v[50:51], off
	v_add_co_u32_e32 v62, vcc, s60, v50
	s_nop 1
	v_addc_co_u32_e32 v63, vcc, 0, v51, vcc
	v_lshl_add_u64 v[50:51], v[50:51], 0, s[24:25]
	global_load_dword v175, v[62:63], off
	global_load_dword v176, v[50:51], off
	v_add_co_u32_e32 v62, vcc, s60, v50
	s_nop 1
	v_addc_co_u32_e32 v63, vcc, 0, v51, vcc
	v_lshl_add_u64 v[50:51], v[50:51], 0, s[24:25]
	global_load_dword v177, v[62:63], off
	global_load_dword v178, v[50:51], off
	v_add_co_u32_e32 v62, vcc, s60, v50
	s_nop 1
	v_addc_co_u32_e32 v63, vcc, 0, v51, vcc
	v_lshl_add_u64 v[50:51], v[50:51], 0, s[24:25]
	global_load_dword v179, v[62:63], off
	global_load_dword v180, v[50:51], off
	v_add_co_u32_e32 v62, vcc, s60, v50
	s_nop 1
	v_addc_co_u32_e32 v63, vcc, 0, v51, vcc
	v_lshl_add_u64 v[50:51], v[50:51], 0, s[24:25]
	global_load_dword v181, v[62:63], off
	global_load_dword v182, v[50:51], off
	v_add_co_u32_e32 v62, vcc, s60, v50
	s_nop 1
	v_addc_co_u32_e32 v63, vcc, 0, v51, vcc
	v_lshl_add_u64 v[50:51], v[50:51], 0, s[24:25]
	global_load_dword v183, v[62:63], off
	global_load_dword v184, v[50:51], off
	v_add_co_u32_e32 v62, vcc, s60, v50
	s_nop 1
	v_addc_co_u32_e32 v63, vcc, 0, v51, vcc
	v_lshl_add_u64 v[50:51], v[50:51], 0, s[24:25]
	global_load_dword v185, v[62:63], off
	global_load_dword v186, v[50:51], off
	v_add_co_u32_e32 v62, vcc, s60, v50
	s_nop 1
	v_addc_co_u32_e32 v63, vcc, 0, v51, vcc
	v_lshl_add_u64 v[50:51], v[50:51], 0, s[24:25]
	global_load_dword v187, v[62:63], off
	global_load_dword v188, v[50:51], off
	v_add_co_u32_e32 v62, vcc, s60, v50
	s_nop 1
	v_addc_co_u32_e32 v63, vcc, 0, v51, vcc
	v_lshl_add_u64 v[50:51], v[50:51], 0, s[24:25]
	global_load_dword v189, v[62:63], off
	global_load_dword v190, v[50:51], off
	v_add_co_u32_e32 v62, vcc, s60, v50
	s_nop 1
	v_addc_co_u32_e32 v63, vcc, 0, v51, vcc
	v_lshl_add_u64 v[50:51], v[50:51], 0, s[24:25]
	global_load_dword v191, v[62:63], off
	global_load_dword v192, v[50:51], off
	v_add_co_u32_e32 v62, vcc, s60, v50
	s_nop 1
	v_addc_co_u32_e32 v63, vcc, 0, v51, vcc
	v_lshl_add_u64 v[50:51], v[50:51], 0, s[24:25]
	global_load_dword v193, v[62:63], off
	global_load_dword v194, v[50:51], off
	v_add_co_u32_e32 v62, vcc, s60, v50
	s_nop 1
	v_addc_co_u32_e32 v63, vcc, 0, v51, vcc
	v_lshl_add_u64 v[50:51], v[50:51], 0, s[24:25]
	global_load_dword v195, v[62:63], off
	v_add_u32_e32 v149, 0x10000, v57
	v_mov_b32_e32 v61, v57
	v_mov_b32_e32 v150, v149
	ds_read2st64_b64 v[62:65], v61 offset1:4
	ds_read2st64_b64 v[66:69], v61 offset0:8 offset1:12
	ds_read2st64_b64 v[70:73], v61 offset0:16 offset1:20
	ds_read2st64_b64 v[74:77], v61 offset0:24 offset1:28
	ds_read2st64_b64 v[78:81], v61 offset0:32 offset1:36
	ds_read2st64_b64 v[82:85], v61 offset0:40 offset1:44
	ds_read2st64_b64 v[86:89], v61 offset0:48 offset1:52
	ds_read2st64_b64 v[90:93], v61 offset0:56 offset1:60
	ds_read2st64_b64 v[94:97], v61 offset0:64 offset1:68
	ds_read2st64_b64 v[98:101], v61 offset0:72 offset1:76
	ds_read2st64_b64 v[102:105], v61 offset0:80 offset1:84
	ds_read2st64_b64 v[106:109], v61 offset0:88 offset1:92
	ds_read2st64_b64 v[110:113], v61 offset0:96 offset1:100
	ds_read2st64_b64 v[114:117], v61 offset0:104 offset1:108
	ds_read2st64_b64 v[118:121], v61 offset0:112 offset1:116
	ds_read2st64_b64 v[122:125], v61 offset0:120 offset1:124
	ds_read_b64 v[128:129], v150
	s_waitcnt vmcnt(30)
	s_waitcnt lgkmcnt(15)
	v_fmac_f32_e32 v30, v164, v62
	v_fmac_f32_e32 v43, v164, v64
	s_waitcnt lgkmcnt(15)
	v_fmac_f32_e32 v42, v164, v66
	v_fmac_f32_e32 v35, v164, v68
	s_waitcnt lgkmcnt(14)
	v_fmac_f32_e32 v34, v164, v70
	v_fmac_f32_e32 v29, v164, v72
	s_waitcnt lgkmcnt(13)
	v_fmac_f32_e32 v28, v164, v74
	v_fmac_f32_e32 v27, v164, v76
	s_waitcnt lgkmcnt(12)
	v_fmac_f32_e32 v26, v164, v78
	v_fmac_f32_e32 v25, v164, v80
	s_waitcnt lgkmcnt(11)
	v_fmac_f32_e32 v24, v164, v82
	v_fmac_f32_e32 v23, v164, v84
	s_waitcnt lgkmcnt(10)
	v_fmac_f32_e32 v22, v164, v86
	v_fmac_f32_e32 v21, v164, v88
	s_waitcnt lgkmcnt(9)
	v_fmac_f32_e32 v20, v164, v90
	v_fmac_f32_e32 v17, v164, v92
	s_waitcnt lgkmcnt(8)
	v_fmac_f32_e32 v16, v164, v94
	v_fmac_f32_e32 v31, v164, v96
	s_waitcnt lgkmcnt(7)
	v_fmac_f32_e32 v32, v164, v98
	v_fmac_f32_e32 v33, v164, v100
	s_waitcnt lgkmcnt(6)
	v_fmac_f32_e32 v36, v164, v102
	v_fmac_f32_e32 v37, v164, v104
	s_waitcnt lgkmcnt(5)
	v_fmac_f32_e32 v38, v164, v106
	v_fmac_f32_e32 v39, v164, v108
	s_waitcnt lgkmcnt(4)
	v_fmac_f32_e32 v40, v164, v110
	v_fmac_f32_e32 v41, v164, v112
	s_waitcnt lgkmcnt(3)
	v_fmac_f32_e32 v44, v164, v114
	v_fmac_f32_e32 v45, v164, v116
	s_waitcnt lgkmcnt(2)
	v_fmac_f32_e32 v46, v164, v118
	v_fmac_f32_e32 v47, v164, v120
	s_waitcnt lgkmcnt(1)
	v_fmac_f32_e32 v48, v164, v122
	v_fmac_f32_e32 v49, v164, v124
	s_waitcnt lgkmcnt(0)
	v_fmac_f32_e32 v60, v164, v128
	v_fmac_f32_e32 v30, v165, v63
	v_fmac_f32_e32 v43, v165, v65
	v_fmac_f32_e32 v42, v165, v67
	v_fmac_f32_e32 v35, v165, v69
	v_fmac_f32_e32 v34, v165, v71
	v_fmac_f32_e32 v29, v165, v73
	v_fmac_f32_e32 v28, v165, v75
	v_fmac_f32_e32 v27, v165, v77
	v_fmac_f32_e32 v26, v165, v79
	v_fmac_f32_e32 v25, v165, v81
	v_fmac_f32_e32 v24, v165, v83
	v_fmac_f32_e32 v23, v165, v85
	v_fmac_f32_e32 v22, v165, v87
	v_fmac_f32_e32 v21, v165, v89
	v_fmac_f32_e32 v20, v165, v91
	v_fmac_f32_e32 v17, v165, v93
	v_fmac_f32_e32 v16, v165, v95
	v_fmac_f32_e32 v31, v165, v97
	v_fmac_f32_e32 v32, v165, v99
	v_fmac_f32_e32 v33, v165, v101
	v_fmac_f32_e32 v36, v165, v103
	v_fmac_f32_e32 v37, v165, v105
	v_fmac_f32_e32 v38, v165, v107
	v_fmac_f32_e32 v39, v165, v109
	v_fmac_f32_e32 v40, v165, v111
	v_fmac_f32_e32 v41, v165, v113
	v_fmac_f32_e32 v44, v165, v115
	v_fmac_f32_e32 v45, v165, v117
	v_fmac_f32_e32 v46, v165, v119
	v_fmac_f32_e32 v47, v165, v121
	v_fmac_f32_e32 v48, v165, v123
	v_fmac_f32_e32 v49, v165, v125
	v_fmac_f32_e32 v60, v165, v129
	global_load_dword v196, v[50:51], off
	v_add_co_u32_e32 v62, vcc, s60, v50
	s_nop 1
	v_addc_co_u32_e32 v63, vcc, 0, v51, vcc
	v_lshl_add_u64 v[50:51], v[50:51], 0, s[24:25]
	global_load_dword v197, v[62:63], off
	v_add_u32_e32 v61, 8, v57
	v_add_u32_e32 v150, 8, v149
	ds_read2st64_b64 v[62:65], v61 offset1:4
	ds_read2st64_b64 v[66:69], v61 offset0:8 offset1:12
	ds_read2st64_b64 v[70:73], v61 offset0:16 offset1:20
	ds_read2st64_b64 v[74:77], v61 offset0:24 offset1:28
	ds_read2st64_b64 v[78:81], v61 offset0:32 offset1:36
	ds_read2st64_b64 v[82:85], v61 offset0:40 offset1:44
	ds_read2st64_b64 v[86:89], v61 offset0:48 offset1:52
	ds_read2st64_b64 v[90:93], v61 offset0:56 offset1:60
	ds_read2st64_b64 v[94:97], v61 offset0:64 offset1:68
	ds_read2st64_b64 v[98:101], v61 offset0:72 offset1:76
	ds_read2st64_b64 v[102:105], v61 offset0:80 offset1:84
	ds_read2st64_b64 v[106:109], v61 offset0:88 offset1:92
	ds_read2st64_b64 v[110:113], v61 offset0:96 offset1:100
	ds_read2st64_b64 v[114:117], v61 offset0:104 offset1:108
	ds_read2st64_b64 v[118:121], v61 offset0:112 offset1:116
	ds_read2st64_b64 v[122:125], v61 offset0:120 offset1:124
	ds_read_b64 v[128:129], v150
	s_waitcnt vmcnt(30)
	s_waitcnt lgkmcnt(15)
	v_fmac_f32_e32 v30, v166, v62
	v_fmac_f32_e32 v43, v166, v64
	s_waitcnt lgkmcnt(15)
	v_fmac_f32_e32 v42, v166, v66
	v_fmac_f32_e32 v35, v166, v68
	s_waitcnt lgkmcnt(14)
	v_fmac_f32_e32 v34, v166, v70
	v_fmac_f32_e32 v29, v166, v72
	s_waitcnt lgkmcnt(13)
	v_fmac_f32_e32 v28, v166, v74
	v_fmac_f32_e32 v27, v166, v76
	s_waitcnt lgkmcnt(12)
	v_fmac_f32_e32 v26, v166, v78
	v_fmac_f32_e32 v25, v166, v80
	s_waitcnt lgkmcnt(11)
	v_fmac_f32_e32 v24, v166, v82
	v_fmac_f32_e32 v23, v166, v84
	s_waitcnt lgkmcnt(10)
	v_fmac_f32_e32 v22, v166, v86
	v_fmac_f32_e32 v21, v166, v88
	s_waitcnt lgkmcnt(9)
	v_fmac_f32_e32 v20, v166, v90
	v_fmac_f32_e32 v17, v166, v92
	s_waitcnt lgkmcnt(8)
	v_fmac_f32_e32 v16, v166, v94
	v_fmac_f32_e32 v31, v166, v96
	s_waitcnt lgkmcnt(7)
	v_fmac_f32_e32 v32, v166, v98
	v_fmac_f32_e32 v33, v166, v100
	s_waitcnt lgkmcnt(6)
	v_fmac_f32_e32 v36, v166, v102
	v_fmac_f32_e32 v37, v166, v104
	s_waitcnt lgkmcnt(5)
	v_fmac_f32_e32 v38, v166, v106
	v_fmac_f32_e32 v39, v166, v108
	s_waitcnt lgkmcnt(4)
	v_fmac_f32_e32 v40, v166, v110
	v_fmac_f32_e32 v41, v166, v112
	s_waitcnt lgkmcnt(3)
	v_fmac_f32_e32 v44, v166, v114
	v_fmac_f32_e32 v45, v166, v116
	s_waitcnt lgkmcnt(2)
	v_fmac_f32_e32 v46, v166, v118
	v_fmac_f32_e32 v47, v166, v120
	s_waitcnt lgkmcnt(1)
	v_fmac_f32_e32 v48, v166, v122
	v_fmac_f32_e32 v49, v166, v124
	s_waitcnt lgkmcnt(0)
	v_fmac_f32_e32 v60, v166, v128
	v_fmac_f32_e32 v30, v167, v63
	v_fmac_f32_e32 v43, v167, v65
	v_fmac_f32_e32 v42, v167, v67
	v_fmac_f32_e32 v35, v167, v69
	v_fmac_f32_e32 v34, v167, v71
	v_fmac_f32_e32 v29, v167, v73
	v_fmac_f32_e32 v28, v167, v75
	v_fmac_f32_e32 v27, v167, v77
	v_fmac_f32_e32 v26, v167, v79
	v_fmac_f32_e32 v25, v167, v81
	v_fmac_f32_e32 v24, v167, v83
	v_fmac_f32_e32 v23, v167, v85
	v_fmac_f32_e32 v22, v167, v87
	v_fmac_f32_e32 v21, v167, v89
	v_fmac_f32_e32 v20, v167, v91
	v_fmac_f32_e32 v17, v167, v93
	v_fmac_f32_e32 v16, v167, v95
	v_fmac_f32_e32 v31, v167, v97
	v_fmac_f32_e32 v32, v167, v99
	v_fmac_f32_e32 v33, v167, v101
	v_fmac_f32_e32 v36, v167, v103
	v_fmac_f32_e32 v37, v167, v105
	v_fmac_f32_e32 v38, v167, v107
	v_fmac_f32_e32 v39, v167, v109
	v_fmac_f32_e32 v40, v167, v111
	v_fmac_f32_e32 v41, v167, v113
	v_fmac_f32_e32 v44, v167, v115
	v_fmac_f32_e32 v45, v167, v117
	v_fmac_f32_e32 v46, v167, v119
	v_fmac_f32_e32 v47, v167, v121
	v_fmac_f32_e32 v48, v167, v123
	v_fmac_f32_e32 v49, v167, v125
	v_fmac_f32_e32 v60, v167, v129
	global_load_dword v198, v[50:51], off
	v_add_co_u32_e32 v62, vcc, s60, v50
	s_nop 1
	v_addc_co_u32_e32 v63, vcc, 0, v51, vcc
	v_lshl_add_u64 v[50:51], v[50:51], 0, s[24:25]
	global_load_dword v199, v[62:63], off
	v_add_u32_e32 v61, 16, v57
	v_add_u32_e32 v150, 16, v149
	ds_read2st64_b64 v[62:65], v61 offset1:4
	ds_read2st64_b64 v[66:69], v61 offset0:8 offset1:12
	ds_read2st64_b64 v[70:73], v61 offset0:16 offset1:20
	ds_read2st64_b64 v[74:77], v61 offset0:24 offset1:28
	ds_read2st64_b64 v[78:81], v61 offset0:32 offset1:36
	ds_read2st64_b64 v[82:85], v61 offset0:40 offset1:44
	ds_read2st64_b64 v[86:89], v61 offset0:48 offset1:52
	ds_read2st64_b64 v[90:93], v61 offset0:56 offset1:60
	ds_read2st64_b64 v[94:97], v61 offset0:64 offset1:68
	ds_read2st64_b64 v[98:101], v61 offset0:72 offset1:76
	ds_read2st64_b64 v[102:105], v61 offset0:80 offset1:84
	ds_read2st64_b64 v[106:109], v61 offset0:88 offset1:92
	ds_read2st64_b64 v[110:113], v61 offset0:96 offset1:100
	ds_read2st64_b64 v[114:117], v61 offset0:104 offset1:108
	ds_read2st64_b64 v[118:121], v61 offset0:112 offset1:116
	ds_read2st64_b64 v[122:125], v61 offset0:120 offset1:124
	ds_read_b64 v[128:129], v150
	s_waitcnt vmcnt(30)
	s_waitcnt lgkmcnt(15)
	v_fmac_f32_e32 v30, v168, v62
	v_fmac_f32_e32 v43, v168, v64
	s_waitcnt lgkmcnt(15)
	v_fmac_f32_e32 v42, v168, v66
	v_fmac_f32_e32 v35, v168, v68
	s_waitcnt lgkmcnt(14)
	v_fmac_f32_e32 v34, v168, v70
	v_fmac_f32_e32 v29, v168, v72
	s_waitcnt lgkmcnt(13)
	v_fmac_f32_e32 v28, v168, v74
	v_fmac_f32_e32 v27, v168, v76
	s_waitcnt lgkmcnt(12)
	v_fmac_f32_e32 v26, v168, v78
	v_fmac_f32_e32 v25, v168, v80
	s_waitcnt lgkmcnt(11)
	v_fmac_f32_e32 v24, v168, v82
	v_fmac_f32_e32 v23, v168, v84
	s_waitcnt lgkmcnt(10)
	v_fmac_f32_e32 v22, v168, v86
	v_fmac_f32_e32 v21, v168, v88
	s_waitcnt lgkmcnt(9)
	v_fmac_f32_e32 v20, v168, v90
	v_fmac_f32_e32 v17, v168, v92
	s_waitcnt lgkmcnt(8)
	v_fmac_f32_e32 v16, v168, v94
	v_fmac_f32_e32 v31, v168, v96
	s_waitcnt lgkmcnt(7)
	v_fmac_f32_e32 v32, v168, v98
	v_fmac_f32_e32 v33, v168, v100
	s_waitcnt lgkmcnt(6)
	v_fmac_f32_e32 v36, v168, v102
	v_fmac_f32_e32 v37, v168, v104
	s_waitcnt lgkmcnt(5)
	v_fmac_f32_e32 v38, v168, v106
	v_fmac_f32_e32 v39, v168, v108
	s_waitcnt lgkmcnt(4)
	v_fmac_f32_e32 v40, v168, v110
	v_fmac_f32_e32 v41, v168, v112
	s_waitcnt lgkmcnt(3)
	v_fmac_f32_e32 v44, v168, v114
	v_fmac_f32_e32 v45, v168, v116
	s_waitcnt lgkmcnt(2)
	v_fmac_f32_e32 v46, v168, v118
	v_fmac_f32_e32 v47, v168, v120
	s_waitcnt lgkmcnt(1)
	v_fmac_f32_e32 v48, v168, v122
	v_fmac_f32_e32 v49, v168, v124
	s_waitcnt lgkmcnt(0)
	v_fmac_f32_e32 v60, v168, v128
	v_fmac_f32_e32 v30, v169, v63
	v_fmac_f32_e32 v43, v169, v65
	v_fmac_f32_e32 v42, v169, v67
	v_fmac_f32_e32 v35, v169, v69
	v_fmac_f32_e32 v34, v169, v71
	v_fmac_f32_e32 v29, v169, v73
	v_fmac_f32_e32 v28, v169, v75
	v_fmac_f32_e32 v27, v169, v77
	v_fmac_f32_e32 v26, v169, v79
	v_fmac_f32_e32 v25, v169, v81
	v_fmac_f32_e32 v24, v169, v83
	v_fmac_f32_e32 v23, v169, v85
	v_fmac_f32_e32 v22, v169, v87
	v_fmac_f32_e32 v21, v169, v89
	v_fmac_f32_e32 v20, v169, v91
	v_fmac_f32_e32 v17, v169, v93
	v_fmac_f32_e32 v16, v169, v95
	v_fmac_f32_e32 v31, v169, v97
	v_fmac_f32_e32 v32, v169, v99
	v_fmac_f32_e32 v33, v169, v101
	v_fmac_f32_e32 v36, v169, v103
	v_fmac_f32_e32 v37, v169, v105
	v_fmac_f32_e32 v38, v169, v107
	v_fmac_f32_e32 v39, v169, v109
	v_fmac_f32_e32 v40, v169, v111
	v_fmac_f32_e32 v41, v169, v113
	v_fmac_f32_e32 v44, v169, v115
	v_fmac_f32_e32 v45, v169, v117
	v_fmac_f32_e32 v46, v169, v119
	v_fmac_f32_e32 v47, v169, v121
	v_fmac_f32_e32 v48, v169, v123
	v_fmac_f32_e32 v49, v169, v125
	v_fmac_f32_e32 v60, v169, v129
	global_load_dword v200, v[50:51], off
	v_add_co_u32_e32 v62, vcc, s60, v50
	s_nop 1
	v_addc_co_u32_e32 v63, vcc, 0, v51, vcc
	v_lshl_add_u64 v[50:51], v[50:51], 0, s[24:25]
	global_load_dword v201, v[62:63], off
	v_add_u32_e32 v61, 24, v57
	v_add_u32_e32 v150, 24, v149
	ds_read2st64_b64 v[62:65], v61 offset1:4
	ds_read2st64_b64 v[66:69], v61 offset0:8 offset1:12
	ds_read2st64_b64 v[70:73], v61 offset0:16 offset1:20
	ds_read2st64_b64 v[74:77], v61 offset0:24 offset1:28
	ds_read2st64_b64 v[78:81], v61 offset0:32 offset1:36
	ds_read2st64_b64 v[82:85], v61 offset0:40 offset1:44
	ds_read2st64_b64 v[86:89], v61 offset0:48 offset1:52
	ds_read2st64_b64 v[90:93], v61 offset0:56 offset1:60
	ds_read2st64_b64 v[94:97], v61 offset0:64 offset1:68
	ds_read2st64_b64 v[98:101], v61 offset0:72 offset1:76
	ds_read2st64_b64 v[102:105], v61 offset0:80 offset1:84
	ds_read2st64_b64 v[106:109], v61 offset0:88 offset1:92
	ds_read2st64_b64 v[110:113], v61 offset0:96 offset1:100
	ds_read2st64_b64 v[114:117], v61 offset0:104 offset1:108
	ds_read2st64_b64 v[118:121], v61 offset0:112 offset1:116
	ds_read2st64_b64 v[122:125], v61 offset0:120 offset1:124
	ds_read_b64 v[128:129], v150
	s_waitcnt vmcnt(30)
	s_waitcnt lgkmcnt(15)
	v_fmac_f32_e32 v30, v170, v62
	v_fmac_f32_e32 v43, v170, v64
	s_waitcnt lgkmcnt(15)
	v_fmac_f32_e32 v42, v170, v66
	v_fmac_f32_e32 v35, v170, v68
	s_waitcnt lgkmcnt(14)
	v_fmac_f32_e32 v34, v170, v70
	v_fmac_f32_e32 v29, v170, v72
	s_waitcnt lgkmcnt(13)
	v_fmac_f32_e32 v28, v170, v74
	v_fmac_f32_e32 v27, v170, v76
	s_waitcnt lgkmcnt(12)
	v_fmac_f32_e32 v26, v170, v78
	v_fmac_f32_e32 v25, v170, v80
	s_waitcnt lgkmcnt(11)
	v_fmac_f32_e32 v24, v170, v82
	v_fmac_f32_e32 v23, v170, v84
	s_waitcnt lgkmcnt(10)
	v_fmac_f32_e32 v22, v170, v86
	v_fmac_f32_e32 v21, v170, v88
	s_waitcnt lgkmcnt(9)
	v_fmac_f32_e32 v20, v170, v90
	v_fmac_f32_e32 v17, v170, v92
	s_waitcnt lgkmcnt(8)
	v_fmac_f32_e32 v16, v170, v94
	v_fmac_f32_e32 v31, v170, v96
	s_waitcnt lgkmcnt(7)
	v_fmac_f32_e32 v32, v170, v98
	v_fmac_f32_e32 v33, v170, v100
	s_waitcnt lgkmcnt(6)
	v_fmac_f32_e32 v36, v170, v102
	v_fmac_f32_e32 v37, v170, v104
	s_waitcnt lgkmcnt(5)
	v_fmac_f32_e32 v38, v170, v106
	v_fmac_f32_e32 v39, v170, v108
	s_waitcnt lgkmcnt(4)
	v_fmac_f32_e32 v40, v170, v110
	v_fmac_f32_e32 v41, v170, v112
	s_waitcnt lgkmcnt(3)
	v_fmac_f32_e32 v44, v170, v114
	v_fmac_f32_e32 v45, v170, v116
	s_waitcnt lgkmcnt(2)
	v_fmac_f32_e32 v46, v170, v118
	v_fmac_f32_e32 v47, v170, v120
	s_waitcnt lgkmcnt(1)
	v_fmac_f32_e32 v48, v170, v122
	v_fmac_f32_e32 v49, v170, v124
	s_waitcnt lgkmcnt(0)
	v_fmac_f32_e32 v60, v170, v128
	v_fmac_f32_e32 v30, v171, v63
	v_fmac_f32_e32 v43, v171, v65
	v_fmac_f32_e32 v42, v171, v67
	v_fmac_f32_e32 v35, v171, v69
	v_fmac_f32_e32 v34, v171, v71
	v_fmac_f32_e32 v29, v171, v73
	v_fmac_f32_e32 v28, v171, v75
	v_fmac_f32_e32 v27, v171, v77
	v_fmac_f32_e32 v26, v171, v79
	v_fmac_f32_e32 v25, v171, v81
	v_fmac_f32_e32 v24, v171, v83
	v_fmac_f32_e32 v23, v171, v85
	v_fmac_f32_e32 v22, v171, v87
	v_fmac_f32_e32 v21, v171, v89
	v_fmac_f32_e32 v20, v171, v91
	v_fmac_f32_e32 v17, v171, v93
	v_fmac_f32_e32 v16, v171, v95
	v_fmac_f32_e32 v31, v171, v97
	v_fmac_f32_e32 v32, v171, v99
	v_fmac_f32_e32 v33, v171, v101
	v_fmac_f32_e32 v36, v171, v103
	v_fmac_f32_e32 v37, v171, v105
	v_fmac_f32_e32 v38, v171, v107
	v_fmac_f32_e32 v39, v171, v109
	v_fmac_f32_e32 v40, v171, v111
	v_fmac_f32_e32 v41, v171, v113
	v_fmac_f32_e32 v44, v171, v115
	v_fmac_f32_e32 v45, v171, v117
	v_fmac_f32_e32 v46, v171, v119
	v_fmac_f32_e32 v47, v171, v121
	v_fmac_f32_e32 v48, v171, v123
	v_fmac_f32_e32 v49, v171, v125
	v_fmac_f32_e32 v60, v171, v129
	global_load_dword v202, v[50:51], off
	v_add_co_u32_e32 v62, vcc, s60, v50
	s_nop 1
	v_addc_co_u32_e32 v63, vcc, 0, v51, vcc
	v_lshl_add_u64 v[50:51], v[50:51], 0, s[24:25]
	global_load_dword v203, v[62:63], off
	v_add_u32_e32 v61, 32, v57
	v_add_u32_e32 v150, 32, v149
	ds_read2st64_b64 v[62:65], v61 offset1:4
	ds_read2st64_b64 v[66:69], v61 offset0:8 offset1:12
	ds_read2st64_b64 v[70:73], v61 offset0:16 offset1:20
	ds_read2st64_b64 v[74:77], v61 offset0:24 offset1:28
	ds_read2st64_b64 v[78:81], v61 offset0:32 offset1:36
	ds_read2st64_b64 v[82:85], v61 offset0:40 offset1:44
	ds_read2st64_b64 v[86:89], v61 offset0:48 offset1:52
	ds_read2st64_b64 v[90:93], v61 offset0:56 offset1:60
	ds_read2st64_b64 v[94:97], v61 offset0:64 offset1:68
	ds_read2st64_b64 v[98:101], v61 offset0:72 offset1:76
	ds_read2st64_b64 v[102:105], v61 offset0:80 offset1:84
	ds_read2st64_b64 v[106:109], v61 offset0:88 offset1:92
	ds_read2st64_b64 v[110:113], v61 offset0:96 offset1:100
	ds_read2st64_b64 v[114:117], v61 offset0:104 offset1:108
	ds_read2st64_b64 v[118:121], v61 offset0:112 offset1:116
	ds_read2st64_b64 v[122:125], v61 offset0:120 offset1:124
	ds_read_b64 v[128:129], v150
	s_waitcnt vmcnt(30)
	s_waitcnt lgkmcnt(15)
	v_fmac_f32_e32 v30, v172, v62
	v_fmac_f32_e32 v43, v172, v64
	s_waitcnt lgkmcnt(15)
	v_fmac_f32_e32 v42, v172, v66
	v_fmac_f32_e32 v35, v172, v68
	s_waitcnt lgkmcnt(14)
	v_fmac_f32_e32 v34, v172, v70
	v_fmac_f32_e32 v29, v172, v72
	s_waitcnt lgkmcnt(13)
	v_fmac_f32_e32 v28, v172, v74
	v_fmac_f32_e32 v27, v172, v76
	s_waitcnt lgkmcnt(12)
	v_fmac_f32_e32 v26, v172, v78
	v_fmac_f32_e32 v25, v172, v80
	s_waitcnt lgkmcnt(11)
	v_fmac_f32_e32 v24, v172, v82
	v_fmac_f32_e32 v23, v172, v84
	s_waitcnt lgkmcnt(10)
	v_fmac_f32_e32 v22, v172, v86
	v_fmac_f32_e32 v21, v172, v88
	s_waitcnt lgkmcnt(9)
	v_fmac_f32_e32 v20, v172, v90
	v_fmac_f32_e32 v17, v172, v92
	s_waitcnt lgkmcnt(8)
	v_fmac_f32_e32 v16, v172, v94
	v_fmac_f32_e32 v31, v172, v96
	s_waitcnt lgkmcnt(7)
	v_fmac_f32_e32 v32, v172, v98
	v_fmac_f32_e32 v33, v172, v100
	s_waitcnt lgkmcnt(6)
	v_fmac_f32_e32 v36, v172, v102
	v_fmac_f32_e32 v37, v172, v104
	s_waitcnt lgkmcnt(5)
	v_fmac_f32_e32 v38, v172, v106
	v_fmac_f32_e32 v39, v172, v108
	s_waitcnt lgkmcnt(4)
	v_fmac_f32_e32 v40, v172, v110
	v_fmac_f32_e32 v41, v172, v112
	s_waitcnt lgkmcnt(3)
	v_fmac_f32_e32 v44, v172, v114
	v_fmac_f32_e32 v45, v172, v116
	s_waitcnt lgkmcnt(2)
	v_fmac_f32_e32 v46, v172, v118
	v_fmac_f32_e32 v47, v172, v120
	s_waitcnt lgkmcnt(1)
	v_fmac_f32_e32 v48, v172, v122
	v_fmac_f32_e32 v49, v172, v124
	s_waitcnt lgkmcnt(0)
	v_fmac_f32_e32 v60, v172, v128
	v_fmac_f32_e32 v30, v173, v63
	v_fmac_f32_e32 v43, v173, v65
	v_fmac_f32_e32 v42, v173, v67
	v_fmac_f32_e32 v35, v173, v69
	v_fmac_f32_e32 v34, v173, v71
	v_fmac_f32_e32 v29, v173, v73
	v_fmac_f32_e32 v28, v173, v75
	v_fmac_f32_e32 v27, v173, v77
	v_fmac_f32_e32 v26, v173, v79
	v_fmac_f32_e32 v25, v173, v81
	v_fmac_f32_e32 v24, v173, v83
	v_fmac_f32_e32 v23, v173, v85
	v_fmac_f32_e32 v22, v173, v87
	v_fmac_f32_e32 v21, v173, v89
	v_fmac_f32_e32 v20, v173, v91
	v_fmac_f32_e32 v17, v173, v93
	v_fmac_f32_e32 v16, v173, v95
	v_fmac_f32_e32 v31, v173, v97
	v_fmac_f32_e32 v32, v173, v99
	v_fmac_f32_e32 v33, v173, v101
	v_fmac_f32_e32 v36, v173, v103
	v_fmac_f32_e32 v37, v173, v105
	v_fmac_f32_e32 v38, v173, v107
	v_fmac_f32_e32 v39, v173, v109
	v_fmac_f32_e32 v40, v173, v111
	v_fmac_f32_e32 v41, v173, v113
	v_fmac_f32_e32 v44, v173, v115
	v_fmac_f32_e32 v45, v173, v117
	v_fmac_f32_e32 v46, v173, v119
	v_fmac_f32_e32 v47, v173, v121
	v_fmac_f32_e32 v48, v173, v123
	v_fmac_f32_e32 v49, v173, v125
	v_fmac_f32_e32 v60, v173, v129
	global_load_dword v204, v[50:51], off
	v_add_co_u32_e32 v62, vcc, s60, v50
	s_nop 1
	v_addc_co_u32_e32 v63, vcc, 0, v51, vcc
	v_lshl_add_u64 v[50:51], v[50:51], 0, s[24:25]
	global_load_dword v205, v[62:63], off
	v_add_u32_e32 v61, 40, v57
	v_add_u32_e32 v150, 40, v149
	ds_read2st64_b64 v[62:65], v61 offset1:4
	ds_read2st64_b64 v[66:69], v61 offset0:8 offset1:12
	ds_read2st64_b64 v[70:73], v61 offset0:16 offset1:20
	ds_read2st64_b64 v[74:77], v61 offset0:24 offset1:28
	ds_read2st64_b64 v[78:81], v61 offset0:32 offset1:36
	ds_read2st64_b64 v[82:85], v61 offset0:40 offset1:44
	ds_read2st64_b64 v[86:89], v61 offset0:48 offset1:52
	ds_read2st64_b64 v[90:93], v61 offset0:56 offset1:60
	ds_read2st64_b64 v[94:97], v61 offset0:64 offset1:68
	ds_read2st64_b64 v[98:101], v61 offset0:72 offset1:76
	ds_read2st64_b64 v[102:105], v61 offset0:80 offset1:84
	ds_read2st64_b64 v[106:109], v61 offset0:88 offset1:92
	ds_read2st64_b64 v[110:113], v61 offset0:96 offset1:100
	ds_read2st64_b64 v[114:117], v61 offset0:104 offset1:108
	ds_read2st64_b64 v[118:121], v61 offset0:112 offset1:116
	ds_read2st64_b64 v[122:125], v61 offset0:120 offset1:124
	ds_read_b64 v[128:129], v150
	s_waitcnt vmcnt(30)
	s_waitcnt lgkmcnt(15)
	v_fmac_f32_e32 v30, v174, v62
	v_fmac_f32_e32 v43, v174, v64
	s_waitcnt lgkmcnt(15)
	v_fmac_f32_e32 v42, v174, v66
	v_fmac_f32_e32 v35, v174, v68
	s_waitcnt lgkmcnt(14)
	v_fmac_f32_e32 v34, v174, v70
	v_fmac_f32_e32 v29, v174, v72
	s_waitcnt lgkmcnt(13)
	v_fmac_f32_e32 v28, v174, v74
	v_fmac_f32_e32 v27, v174, v76
	s_waitcnt lgkmcnt(12)
	v_fmac_f32_e32 v26, v174, v78
	v_fmac_f32_e32 v25, v174, v80
	s_waitcnt lgkmcnt(11)
	v_fmac_f32_e32 v24, v174, v82
	v_fmac_f32_e32 v23, v174, v84
	s_waitcnt lgkmcnt(10)
	v_fmac_f32_e32 v22, v174, v86
	v_fmac_f32_e32 v21, v174, v88
	s_waitcnt lgkmcnt(9)
	v_fmac_f32_e32 v20, v174, v90
	v_fmac_f32_e32 v17, v174, v92
	s_waitcnt lgkmcnt(8)
	v_fmac_f32_e32 v16, v174, v94
	v_fmac_f32_e32 v31, v174, v96
	s_waitcnt lgkmcnt(7)
	v_fmac_f32_e32 v32, v174, v98
	v_fmac_f32_e32 v33, v174, v100
	s_waitcnt lgkmcnt(6)
	v_fmac_f32_e32 v36, v174, v102
	v_fmac_f32_e32 v37, v174, v104
	s_waitcnt lgkmcnt(5)
	v_fmac_f32_e32 v38, v174, v106
	v_fmac_f32_e32 v39, v174, v108
	s_waitcnt lgkmcnt(4)
	v_fmac_f32_e32 v40, v174, v110
	v_fmac_f32_e32 v41, v174, v112
	s_waitcnt lgkmcnt(3)
	v_fmac_f32_e32 v44, v174, v114
	v_fmac_f32_e32 v45, v174, v116
	s_waitcnt lgkmcnt(2)
	v_fmac_f32_e32 v46, v174, v118
	v_fmac_f32_e32 v47, v174, v120
	s_waitcnt lgkmcnt(1)
	v_fmac_f32_e32 v48, v174, v122
	v_fmac_f32_e32 v49, v174, v124
	s_waitcnt lgkmcnt(0)
	v_fmac_f32_e32 v60, v174, v128
	v_fmac_f32_e32 v30, v175, v63
	v_fmac_f32_e32 v43, v175, v65
	v_fmac_f32_e32 v42, v175, v67
	v_fmac_f32_e32 v35, v175, v69
	v_fmac_f32_e32 v34, v175, v71
	v_fmac_f32_e32 v29, v175, v73
	v_fmac_f32_e32 v28, v175, v75
	v_fmac_f32_e32 v27, v175, v77
	v_fmac_f32_e32 v26, v175, v79
	v_fmac_f32_e32 v25, v175, v81
	v_fmac_f32_e32 v24, v175, v83
	v_fmac_f32_e32 v23, v175, v85
	v_fmac_f32_e32 v22, v175, v87
	v_fmac_f32_e32 v21, v175, v89
	v_fmac_f32_e32 v20, v175, v91
	v_fmac_f32_e32 v17, v175, v93
	v_fmac_f32_e32 v16, v175, v95
	v_fmac_f32_e32 v31, v175, v97
	v_fmac_f32_e32 v32, v175, v99
	v_fmac_f32_e32 v33, v175, v101
	v_fmac_f32_e32 v36, v175, v103
	v_fmac_f32_e32 v37, v175, v105
	v_fmac_f32_e32 v38, v175, v107
	v_fmac_f32_e32 v39, v175, v109
	v_fmac_f32_e32 v40, v175, v111
	v_fmac_f32_e32 v41, v175, v113
	v_fmac_f32_e32 v44, v175, v115
	v_fmac_f32_e32 v45, v175, v117
	v_fmac_f32_e32 v46, v175, v119
	v_fmac_f32_e32 v47, v175, v121
	v_fmac_f32_e32 v48, v175, v123
	v_fmac_f32_e32 v49, v175, v125
	v_fmac_f32_e32 v60, v175, v129
	global_load_dword v206, v[50:51], off
	v_add_co_u32_e32 v62, vcc, s60, v50
	s_nop 1
	v_addc_co_u32_e32 v63, vcc, 0, v51, vcc
	v_lshl_add_u64 v[50:51], v[50:51], 0, s[24:25]
	global_load_dword v207, v[62:63], off
	v_add_u32_e32 v61, 48, v57
	v_add_u32_e32 v150, 48, v149
	ds_read2st64_b64 v[62:65], v61 offset1:4
	ds_read2st64_b64 v[66:69], v61 offset0:8 offset1:12
	ds_read2st64_b64 v[70:73], v61 offset0:16 offset1:20
	ds_read2st64_b64 v[74:77], v61 offset0:24 offset1:28
	ds_read2st64_b64 v[78:81], v61 offset0:32 offset1:36
	ds_read2st64_b64 v[82:85], v61 offset0:40 offset1:44
	ds_read2st64_b64 v[86:89], v61 offset0:48 offset1:52
	ds_read2st64_b64 v[90:93], v61 offset0:56 offset1:60
	ds_read2st64_b64 v[94:97], v61 offset0:64 offset1:68
	ds_read2st64_b64 v[98:101], v61 offset0:72 offset1:76
	ds_read2st64_b64 v[102:105], v61 offset0:80 offset1:84
	ds_read2st64_b64 v[106:109], v61 offset0:88 offset1:92
	ds_read2st64_b64 v[110:113], v61 offset0:96 offset1:100
	ds_read2st64_b64 v[114:117], v61 offset0:104 offset1:108
	ds_read2st64_b64 v[118:121], v61 offset0:112 offset1:116
	ds_read2st64_b64 v[122:125], v61 offset0:120 offset1:124
	ds_read_b64 v[128:129], v150
	s_waitcnt vmcnt(30)
	s_waitcnt lgkmcnt(15)
	v_fmac_f32_e32 v30, v176, v62
	v_fmac_f32_e32 v43, v176, v64
	s_waitcnt lgkmcnt(15)
	v_fmac_f32_e32 v42, v176, v66
	v_fmac_f32_e32 v35, v176, v68
	s_waitcnt lgkmcnt(14)
	v_fmac_f32_e32 v34, v176, v70
	v_fmac_f32_e32 v29, v176, v72
	s_waitcnt lgkmcnt(13)
	v_fmac_f32_e32 v28, v176, v74
	v_fmac_f32_e32 v27, v176, v76
	s_waitcnt lgkmcnt(12)
	v_fmac_f32_e32 v26, v176, v78
	v_fmac_f32_e32 v25, v176, v80
	s_waitcnt lgkmcnt(11)
	v_fmac_f32_e32 v24, v176, v82
	v_fmac_f32_e32 v23, v176, v84
	s_waitcnt lgkmcnt(10)
	v_fmac_f32_e32 v22, v176, v86
	v_fmac_f32_e32 v21, v176, v88
	s_waitcnt lgkmcnt(9)
	v_fmac_f32_e32 v20, v176, v90
	v_fmac_f32_e32 v17, v176, v92
	s_waitcnt lgkmcnt(8)
	v_fmac_f32_e32 v16, v176, v94
	v_fmac_f32_e32 v31, v176, v96
	s_waitcnt lgkmcnt(7)
	v_fmac_f32_e32 v32, v176, v98
	v_fmac_f32_e32 v33, v176, v100
	s_waitcnt lgkmcnt(6)
	v_fmac_f32_e32 v36, v176, v102
	v_fmac_f32_e32 v37, v176, v104
	s_waitcnt lgkmcnt(5)
	v_fmac_f32_e32 v38, v176, v106
	v_fmac_f32_e32 v39, v176, v108
	s_waitcnt lgkmcnt(4)
	v_fmac_f32_e32 v40, v176, v110
	v_fmac_f32_e32 v41, v176, v112
	s_waitcnt lgkmcnt(3)
	v_fmac_f32_e32 v44, v176, v114
	v_fmac_f32_e32 v45, v176, v116
	s_waitcnt lgkmcnt(2)
	v_fmac_f32_e32 v46, v176, v118
	v_fmac_f32_e32 v47, v176, v120
	s_waitcnt lgkmcnt(1)
	v_fmac_f32_e32 v48, v176, v122
	v_fmac_f32_e32 v49, v176, v124
	s_waitcnt lgkmcnt(0)
	v_fmac_f32_e32 v60, v176, v128
	v_fmac_f32_e32 v30, v177, v63
	v_fmac_f32_e32 v43, v177, v65
	v_fmac_f32_e32 v42, v177, v67
	v_fmac_f32_e32 v35, v177, v69
	v_fmac_f32_e32 v34, v177, v71
	v_fmac_f32_e32 v29, v177, v73
	v_fmac_f32_e32 v28, v177, v75
	v_fmac_f32_e32 v27, v177, v77
	v_fmac_f32_e32 v26, v177, v79
	v_fmac_f32_e32 v25, v177, v81
	v_fmac_f32_e32 v24, v177, v83
	v_fmac_f32_e32 v23, v177, v85
	v_fmac_f32_e32 v22, v177, v87
	v_fmac_f32_e32 v21, v177, v89
	v_fmac_f32_e32 v20, v177, v91
	v_fmac_f32_e32 v17, v177, v93
	v_fmac_f32_e32 v16, v177, v95
	v_fmac_f32_e32 v31, v177, v97
	v_fmac_f32_e32 v32, v177, v99
	v_fmac_f32_e32 v33, v177, v101
	v_fmac_f32_e32 v36, v177, v103
	v_fmac_f32_e32 v37, v177, v105
	v_fmac_f32_e32 v38, v177, v107
	v_fmac_f32_e32 v39, v177, v109
	v_fmac_f32_e32 v40, v177, v111
	v_fmac_f32_e32 v41, v177, v113
	v_fmac_f32_e32 v44, v177, v115
	v_fmac_f32_e32 v45, v177, v117
	v_fmac_f32_e32 v46, v177, v119
	v_fmac_f32_e32 v47, v177, v121
	v_fmac_f32_e32 v48, v177, v123
	v_fmac_f32_e32 v49, v177, v125
	v_fmac_f32_e32 v60, v177, v129
	global_load_dword v208, v[50:51], off
	v_add_co_u32_e32 v62, vcc, s60, v50
	s_nop 1
	v_addc_co_u32_e32 v63, vcc, 0, v51, vcc
	v_lshl_add_u64 v[50:51], v[50:51], 0, s[24:25]
	global_load_dword v209, v[62:63], off
	v_add_u32_e32 v61, 56, v57
	v_add_u32_e32 v150, 56, v149
	ds_read2st64_b64 v[62:65], v61 offset1:4
	ds_read2st64_b64 v[66:69], v61 offset0:8 offset1:12
	ds_read2st64_b64 v[70:73], v61 offset0:16 offset1:20
	ds_read2st64_b64 v[74:77], v61 offset0:24 offset1:28
	ds_read2st64_b64 v[78:81], v61 offset0:32 offset1:36
	ds_read2st64_b64 v[82:85], v61 offset0:40 offset1:44
	ds_read2st64_b64 v[86:89], v61 offset0:48 offset1:52
	ds_read2st64_b64 v[90:93], v61 offset0:56 offset1:60
	ds_read2st64_b64 v[94:97], v61 offset0:64 offset1:68
	ds_read2st64_b64 v[98:101], v61 offset0:72 offset1:76
	ds_read2st64_b64 v[102:105], v61 offset0:80 offset1:84
	ds_read2st64_b64 v[106:109], v61 offset0:88 offset1:92
	ds_read2st64_b64 v[110:113], v61 offset0:96 offset1:100
	ds_read2st64_b64 v[114:117], v61 offset0:104 offset1:108
	ds_read2st64_b64 v[118:121], v61 offset0:112 offset1:116
	ds_read2st64_b64 v[122:125], v61 offset0:120 offset1:124
	ds_read_b64 v[128:129], v150
	s_waitcnt vmcnt(30)
	s_waitcnt lgkmcnt(15)
	v_fmac_f32_e32 v30, v178, v62
	v_fmac_f32_e32 v43, v178, v64
	s_waitcnt lgkmcnt(15)
	v_fmac_f32_e32 v42, v178, v66
	v_fmac_f32_e32 v35, v178, v68
	s_waitcnt lgkmcnt(14)
	v_fmac_f32_e32 v34, v178, v70
	v_fmac_f32_e32 v29, v178, v72
	s_waitcnt lgkmcnt(13)
	v_fmac_f32_e32 v28, v178, v74
	v_fmac_f32_e32 v27, v178, v76
	s_waitcnt lgkmcnt(12)
	v_fmac_f32_e32 v26, v178, v78
	v_fmac_f32_e32 v25, v178, v80
	s_waitcnt lgkmcnt(11)
	v_fmac_f32_e32 v24, v178, v82
	v_fmac_f32_e32 v23, v178, v84
	s_waitcnt lgkmcnt(10)
	v_fmac_f32_e32 v22, v178, v86
	v_fmac_f32_e32 v21, v178, v88
	s_waitcnt lgkmcnt(9)
	v_fmac_f32_e32 v20, v178, v90
	v_fmac_f32_e32 v17, v178, v92
	s_waitcnt lgkmcnt(8)
	v_fmac_f32_e32 v16, v178, v94
	v_fmac_f32_e32 v31, v178, v96
	s_waitcnt lgkmcnt(7)
	v_fmac_f32_e32 v32, v178, v98
	v_fmac_f32_e32 v33, v178, v100
	s_waitcnt lgkmcnt(6)
	v_fmac_f32_e32 v36, v178, v102
	v_fmac_f32_e32 v37, v178, v104
	s_waitcnt lgkmcnt(5)
	v_fmac_f32_e32 v38, v178, v106
	v_fmac_f32_e32 v39, v178, v108
	s_waitcnt lgkmcnt(4)
	v_fmac_f32_e32 v40, v178, v110
	v_fmac_f32_e32 v41, v178, v112
	s_waitcnt lgkmcnt(3)
	v_fmac_f32_e32 v44, v178, v114
	v_fmac_f32_e32 v45, v178, v116
	s_waitcnt lgkmcnt(2)
	v_fmac_f32_e32 v46, v178, v118
	v_fmac_f32_e32 v47, v178, v120
	s_waitcnt lgkmcnt(1)
	v_fmac_f32_e32 v48, v178, v122
	v_fmac_f32_e32 v49, v178, v124
	s_waitcnt lgkmcnt(0)
	v_fmac_f32_e32 v60, v178, v128
	v_fmac_f32_e32 v30, v179, v63
	v_fmac_f32_e32 v43, v179, v65
	v_fmac_f32_e32 v42, v179, v67
	v_fmac_f32_e32 v35, v179, v69
	v_fmac_f32_e32 v34, v179, v71
	v_fmac_f32_e32 v29, v179, v73
	v_fmac_f32_e32 v28, v179, v75
	v_fmac_f32_e32 v27, v179, v77
	v_fmac_f32_e32 v26, v179, v79
	v_fmac_f32_e32 v25, v179, v81
	v_fmac_f32_e32 v24, v179, v83
	v_fmac_f32_e32 v23, v179, v85
	v_fmac_f32_e32 v22, v179, v87
	v_fmac_f32_e32 v21, v179, v89
	v_fmac_f32_e32 v20, v179, v91
	v_fmac_f32_e32 v17, v179, v93
	v_fmac_f32_e32 v16, v179, v95
	v_fmac_f32_e32 v31, v179, v97
	v_fmac_f32_e32 v32, v179, v99
	v_fmac_f32_e32 v33, v179, v101
	v_fmac_f32_e32 v36, v179, v103
	v_fmac_f32_e32 v37, v179, v105
	v_fmac_f32_e32 v38, v179, v107
	v_fmac_f32_e32 v39, v179, v109
	v_fmac_f32_e32 v40, v179, v111
	v_fmac_f32_e32 v41, v179, v113
	v_fmac_f32_e32 v44, v179, v115
	v_fmac_f32_e32 v45, v179, v117
	v_fmac_f32_e32 v46, v179, v119
	v_fmac_f32_e32 v47, v179, v121
	v_fmac_f32_e32 v48, v179, v123
	v_fmac_f32_e32 v49, v179, v125
	v_fmac_f32_e32 v60, v179, v129
	global_load_dword v210, v[50:51], off
	v_add_co_u32_e32 v62, vcc, s60, v50
	s_nop 1
	v_addc_co_u32_e32 v63, vcc, 0, v51, vcc
	v_lshl_add_u64 v[50:51], v[50:51], 0, s[24:25]
	global_load_dword v212, v[62:63], off
	v_add_u32_e32 v61, 64, v57
	v_add_u32_e32 v150, 64, v149
	ds_read2st64_b64 v[62:65], v61 offset1:4
	ds_read2st64_b64 v[66:69], v61 offset0:8 offset1:12
	ds_read2st64_b64 v[70:73], v61 offset0:16 offset1:20
	ds_read2st64_b64 v[74:77], v61 offset0:24 offset1:28
	ds_read2st64_b64 v[78:81], v61 offset0:32 offset1:36
	ds_read2st64_b64 v[82:85], v61 offset0:40 offset1:44
	ds_read2st64_b64 v[86:89], v61 offset0:48 offset1:52
	ds_read2st64_b64 v[90:93], v61 offset0:56 offset1:60
	ds_read2st64_b64 v[94:97], v61 offset0:64 offset1:68
	ds_read2st64_b64 v[98:101], v61 offset0:72 offset1:76
	ds_read2st64_b64 v[102:105], v61 offset0:80 offset1:84
	ds_read2st64_b64 v[106:109], v61 offset0:88 offset1:92
	ds_read2st64_b64 v[110:113], v61 offset0:96 offset1:100
	ds_read2st64_b64 v[114:117], v61 offset0:104 offset1:108
	ds_read2st64_b64 v[118:121], v61 offset0:112 offset1:116
	ds_read2st64_b64 v[122:125], v61 offset0:120 offset1:124
	ds_read_b64 v[128:129], v150
	s_waitcnt vmcnt(30)
	s_waitcnt lgkmcnt(15)
	v_fmac_f32_e32 v30, v180, v62
	v_fmac_f32_e32 v43, v180, v64
	s_waitcnt lgkmcnt(15)
	v_fmac_f32_e32 v42, v180, v66
	v_fmac_f32_e32 v35, v180, v68
	s_waitcnt lgkmcnt(14)
	v_fmac_f32_e32 v34, v180, v70
	v_fmac_f32_e32 v29, v180, v72
	s_waitcnt lgkmcnt(13)
	v_fmac_f32_e32 v28, v180, v74
	v_fmac_f32_e32 v27, v180, v76
	s_waitcnt lgkmcnt(12)
	v_fmac_f32_e32 v26, v180, v78
	v_fmac_f32_e32 v25, v180, v80
	s_waitcnt lgkmcnt(11)
	v_fmac_f32_e32 v24, v180, v82
	v_fmac_f32_e32 v23, v180, v84
	s_waitcnt lgkmcnt(10)
	v_fmac_f32_e32 v22, v180, v86
	v_fmac_f32_e32 v21, v180, v88
	s_waitcnt lgkmcnt(9)
	v_fmac_f32_e32 v20, v180, v90
	v_fmac_f32_e32 v17, v180, v92
	s_waitcnt lgkmcnt(8)
	v_fmac_f32_e32 v16, v180, v94
	v_fmac_f32_e32 v31, v180, v96
	s_waitcnt lgkmcnt(7)
	v_fmac_f32_e32 v32, v180, v98
	v_fmac_f32_e32 v33, v180, v100
	s_waitcnt lgkmcnt(6)
	v_fmac_f32_e32 v36, v180, v102
	v_fmac_f32_e32 v37, v180, v104
	s_waitcnt lgkmcnt(5)
	v_fmac_f32_e32 v38, v180, v106
	v_fmac_f32_e32 v39, v180, v108
	s_waitcnt lgkmcnt(4)
	v_fmac_f32_e32 v40, v180, v110
	v_fmac_f32_e32 v41, v180, v112
	s_waitcnt lgkmcnt(3)
	v_fmac_f32_e32 v44, v180, v114
	v_fmac_f32_e32 v45, v180, v116
	s_waitcnt lgkmcnt(2)
	v_fmac_f32_e32 v46, v180, v118
	v_fmac_f32_e32 v47, v180, v120
	s_waitcnt lgkmcnt(1)
	v_fmac_f32_e32 v48, v180, v122
	v_fmac_f32_e32 v49, v180, v124
	s_waitcnt lgkmcnt(0)
	v_fmac_f32_e32 v60, v180, v128
	v_fmac_f32_e32 v30, v181, v63
	v_fmac_f32_e32 v43, v181, v65
	v_fmac_f32_e32 v42, v181, v67
	v_fmac_f32_e32 v35, v181, v69
	v_fmac_f32_e32 v34, v181, v71
	v_fmac_f32_e32 v29, v181, v73
	v_fmac_f32_e32 v28, v181, v75
	v_fmac_f32_e32 v27, v181, v77
	v_fmac_f32_e32 v26, v181, v79
	v_fmac_f32_e32 v25, v181, v81
	v_fmac_f32_e32 v24, v181, v83
	v_fmac_f32_e32 v23, v181, v85
	v_fmac_f32_e32 v22, v181, v87
	v_fmac_f32_e32 v21, v181, v89
	v_fmac_f32_e32 v20, v181, v91
	v_fmac_f32_e32 v17, v181, v93
	v_fmac_f32_e32 v16, v181, v95
	v_fmac_f32_e32 v31, v181, v97
	v_fmac_f32_e32 v32, v181, v99
	v_fmac_f32_e32 v33, v181, v101
	v_fmac_f32_e32 v36, v181, v103
	v_fmac_f32_e32 v37, v181, v105
	v_fmac_f32_e32 v38, v181, v107
	v_fmac_f32_e32 v39, v181, v109
	v_fmac_f32_e32 v40, v181, v111
	v_fmac_f32_e32 v41, v181, v113
	v_fmac_f32_e32 v44, v181, v115
	v_fmac_f32_e32 v45, v181, v117
	v_fmac_f32_e32 v46, v181, v119
	v_fmac_f32_e32 v47, v181, v121
	v_fmac_f32_e32 v48, v181, v123
	v_fmac_f32_e32 v49, v181, v125
	v_fmac_f32_e32 v60, v181, v129
	global_load_dword v213, v[50:51], off
	v_add_co_u32_e32 v62, vcc, s60, v50
	s_nop 1
	v_addc_co_u32_e32 v63, vcc, 0, v51, vcc
	v_lshl_add_u64 v[50:51], v[50:51], 0, s[24:25]
	global_load_dword v214, v[62:63], off
	v_add_u32_e32 v61, 72, v57
	v_add_u32_e32 v150, 72, v149
	ds_read2st64_b64 v[62:65], v61 offset1:4
	ds_read2st64_b64 v[66:69], v61 offset0:8 offset1:12
	ds_read2st64_b64 v[70:73], v61 offset0:16 offset1:20
	ds_read2st64_b64 v[74:77], v61 offset0:24 offset1:28
	ds_read2st64_b64 v[78:81], v61 offset0:32 offset1:36
	ds_read2st64_b64 v[82:85], v61 offset0:40 offset1:44
	ds_read2st64_b64 v[86:89], v61 offset0:48 offset1:52
	ds_read2st64_b64 v[90:93], v61 offset0:56 offset1:60
	ds_read2st64_b64 v[94:97], v61 offset0:64 offset1:68
	ds_read2st64_b64 v[98:101], v61 offset0:72 offset1:76
	ds_read2st64_b64 v[102:105], v61 offset0:80 offset1:84
	ds_read2st64_b64 v[106:109], v61 offset0:88 offset1:92
	ds_read2st64_b64 v[110:113], v61 offset0:96 offset1:100
	ds_read2st64_b64 v[114:117], v61 offset0:104 offset1:108
	ds_read2st64_b64 v[118:121], v61 offset0:112 offset1:116
	ds_read2st64_b64 v[122:125], v61 offset0:120 offset1:124
	ds_read_b64 v[128:129], v150
	s_waitcnt vmcnt(30)
	s_waitcnt lgkmcnt(15)
	v_fmac_f32_e32 v30, v182, v62
	v_fmac_f32_e32 v43, v182, v64
	s_waitcnt lgkmcnt(15)
	v_fmac_f32_e32 v42, v182, v66
	v_fmac_f32_e32 v35, v182, v68
	s_waitcnt lgkmcnt(14)
	v_fmac_f32_e32 v34, v182, v70
	v_fmac_f32_e32 v29, v182, v72
	s_waitcnt lgkmcnt(13)
	v_fmac_f32_e32 v28, v182, v74
	v_fmac_f32_e32 v27, v182, v76
	s_waitcnt lgkmcnt(12)
	v_fmac_f32_e32 v26, v182, v78
	v_fmac_f32_e32 v25, v182, v80
	s_waitcnt lgkmcnt(11)
	v_fmac_f32_e32 v24, v182, v82
	v_fmac_f32_e32 v23, v182, v84
	s_waitcnt lgkmcnt(10)
	v_fmac_f32_e32 v22, v182, v86
	v_fmac_f32_e32 v21, v182, v88
	s_waitcnt lgkmcnt(9)
	v_fmac_f32_e32 v20, v182, v90
	v_fmac_f32_e32 v17, v182, v92
	s_waitcnt lgkmcnt(8)
	v_fmac_f32_e32 v16, v182, v94
	v_fmac_f32_e32 v31, v182, v96
	s_waitcnt lgkmcnt(7)
	v_fmac_f32_e32 v32, v182, v98
	v_fmac_f32_e32 v33, v182, v100
	s_waitcnt lgkmcnt(6)
	v_fmac_f32_e32 v36, v182, v102
	v_fmac_f32_e32 v37, v182, v104
	s_waitcnt lgkmcnt(5)
	v_fmac_f32_e32 v38, v182, v106
	v_fmac_f32_e32 v39, v182, v108
	s_waitcnt lgkmcnt(4)
	v_fmac_f32_e32 v40, v182, v110
	v_fmac_f32_e32 v41, v182, v112
	s_waitcnt lgkmcnt(3)
	v_fmac_f32_e32 v44, v182, v114
	v_fmac_f32_e32 v45, v182, v116
	s_waitcnt lgkmcnt(2)
	v_fmac_f32_e32 v46, v182, v118
	v_fmac_f32_e32 v47, v182, v120
	s_waitcnt lgkmcnt(1)
	v_fmac_f32_e32 v48, v182, v122
	v_fmac_f32_e32 v49, v182, v124
	s_waitcnt lgkmcnt(0)
	v_fmac_f32_e32 v60, v182, v128
	v_fmac_f32_e32 v30, v183, v63
	v_fmac_f32_e32 v43, v183, v65
	v_fmac_f32_e32 v42, v183, v67
	v_fmac_f32_e32 v35, v183, v69
	v_fmac_f32_e32 v34, v183, v71
	v_fmac_f32_e32 v29, v183, v73
	v_fmac_f32_e32 v28, v183, v75
	v_fmac_f32_e32 v27, v183, v77
	v_fmac_f32_e32 v26, v183, v79
	v_fmac_f32_e32 v25, v183, v81
	v_fmac_f32_e32 v24, v183, v83
	v_fmac_f32_e32 v23, v183, v85
	v_fmac_f32_e32 v22, v183, v87
	v_fmac_f32_e32 v21, v183, v89
	v_fmac_f32_e32 v20, v183, v91
	v_fmac_f32_e32 v17, v183, v93
	v_fmac_f32_e32 v16, v183, v95
	v_fmac_f32_e32 v31, v183, v97
	v_fmac_f32_e32 v32, v183, v99
	v_fmac_f32_e32 v33, v183, v101
	v_fmac_f32_e32 v36, v183, v103
	v_fmac_f32_e32 v37, v183, v105
	v_fmac_f32_e32 v38, v183, v107
	v_fmac_f32_e32 v39, v183, v109
	v_fmac_f32_e32 v40, v183, v111
	v_fmac_f32_e32 v41, v183, v113
	v_fmac_f32_e32 v44, v183, v115
	v_fmac_f32_e32 v45, v183, v117
	v_fmac_f32_e32 v46, v183, v119
	v_fmac_f32_e32 v47, v183, v121
	v_fmac_f32_e32 v48, v183, v123
	v_fmac_f32_e32 v49, v183, v125
	v_fmac_f32_e32 v60, v183, v129
	global_load_dword v215, v[50:51], off
	v_add_co_u32_e32 v62, vcc, s60, v50
	s_nop 1
	v_addc_co_u32_e32 v63, vcc, 0, v51, vcc
	v_lshl_add_u64 v[50:51], v[50:51], 0, s[24:25]
	global_load_dword v216, v[62:63], off
	v_add_u32_e32 v61, 80, v57
	v_add_u32_e32 v150, 80, v149
	ds_read2st64_b64 v[62:65], v61 offset1:4
	ds_read2st64_b64 v[66:69], v61 offset0:8 offset1:12
	ds_read2st64_b64 v[70:73], v61 offset0:16 offset1:20
	ds_read2st64_b64 v[74:77], v61 offset0:24 offset1:28
	ds_read2st64_b64 v[78:81], v61 offset0:32 offset1:36
	ds_read2st64_b64 v[82:85], v61 offset0:40 offset1:44
	ds_read2st64_b64 v[86:89], v61 offset0:48 offset1:52
	ds_read2st64_b64 v[90:93], v61 offset0:56 offset1:60
	ds_read2st64_b64 v[94:97], v61 offset0:64 offset1:68
	ds_read2st64_b64 v[98:101], v61 offset0:72 offset1:76
	ds_read2st64_b64 v[102:105], v61 offset0:80 offset1:84
	ds_read2st64_b64 v[106:109], v61 offset0:88 offset1:92
	ds_read2st64_b64 v[110:113], v61 offset0:96 offset1:100
	ds_read2st64_b64 v[114:117], v61 offset0:104 offset1:108
	ds_read2st64_b64 v[118:121], v61 offset0:112 offset1:116
	ds_read2st64_b64 v[122:125], v61 offset0:120 offset1:124
	ds_read_b64 v[128:129], v150
	s_waitcnt vmcnt(30)
	s_waitcnt lgkmcnt(15)
	v_fmac_f32_e32 v30, v184, v62
	v_fmac_f32_e32 v43, v184, v64
	s_waitcnt lgkmcnt(15)
	v_fmac_f32_e32 v42, v184, v66
	v_fmac_f32_e32 v35, v184, v68
	s_waitcnt lgkmcnt(14)
	v_fmac_f32_e32 v34, v184, v70
	v_fmac_f32_e32 v29, v184, v72
	s_waitcnt lgkmcnt(13)
	v_fmac_f32_e32 v28, v184, v74
	v_fmac_f32_e32 v27, v184, v76
	s_waitcnt lgkmcnt(12)
	v_fmac_f32_e32 v26, v184, v78
	v_fmac_f32_e32 v25, v184, v80
	s_waitcnt lgkmcnt(11)
	v_fmac_f32_e32 v24, v184, v82
	v_fmac_f32_e32 v23, v184, v84
	s_waitcnt lgkmcnt(10)
	v_fmac_f32_e32 v22, v184, v86
	v_fmac_f32_e32 v21, v184, v88
	s_waitcnt lgkmcnt(9)
	v_fmac_f32_e32 v20, v184, v90
	v_fmac_f32_e32 v17, v184, v92
	s_waitcnt lgkmcnt(8)
	v_fmac_f32_e32 v16, v184, v94
	v_fmac_f32_e32 v31, v184, v96
	s_waitcnt lgkmcnt(7)
	v_fmac_f32_e32 v32, v184, v98
	v_fmac_f32_e32 v33, v184, v100
	s_waitcnt lgkmcnt(6)
	v_fmac_f32_e32 v36, v184, v102
	v_fmac_f32_e32 v37, v184, v104
	s_waitcnt lgkmcnt(5)
	v_fmac_f32_e32 v38, v184, v106
	v_fmac_f32_e32 v39, v184, v108
	s_waitcnt lgkmcnt(4)
	v_fmac_f32_e32 v40, v184, v110
	v_fmac_f32_e32 v41, v184, v112
	s_waitcnt lgkmcnt(3)
	v_fmac_f32_e32 v44, v184, v114
	v_fmac_f32_e32 v45, v184, v116
	s_waitcnt lgkmcnt(2)
	v_fmac_f32_e32 v46, v184, v118
	v_fmac_f32_e32 v47, v184, v120
	s_waitcnt lgkmcnt(1)
	v_fmac_f32_e32 v48, v184, v122
	v_fmac_f32_e32 v49, v184, v124
	s_waitcnt lgkmcnt(0)
	v_fmac_f32_e32 v60, v184, v128
	v_fmac_f32_e32 v30, v185, v63
	v_fmac_f32_e32 v43, v185, v65
	v_fmac_f32_e32 v42, v185, v67
	v_fmac_f32_e32 v35, v185, v69
	v_fmac_f32_e32 v34, v185, v71
	v_fmac_f32_e32 v29, v185, v73
	v_fmac_f32_e32 v28, v185, v75
	v_fmac_f32_e32 v27, v185, v77
	v_fmac_f32_e32 v26, v185, v79
	v_fmac_f32_e32 v25, v185, v81
	v_fmac_f32_e32 v24, v185, v83
	v_fmac_f32_e32 v23, v185, v85
	v_fmac_f32_e32 v22, v185, v87
	v_fmac_f32_e32 v21, v185, v89
	v_fmac_f32_e32 v20, v185, v91
	v_fmac_f32_e32 v17, v185, v93
	v_fmac_f32_e32 v16, v185, v95
	v_fmac_f32_e32 v31, v185, v97
	v_fmac_f32_e32 v32, v185, v99
	v_fmac_f32_e32 v33, v185, v101
	v_fmac_f32_e32 v36, v185, v103
	v_fmac_f32_e32 v37, v185, v105
	v_fmac_f32_e32 v38, v185, v107
	v_fmac_f32_e32 v39, v185, v109
	v_fmac_f32_e32 v40, v185, v111
	v_fmac_f32_e32 v41, v185, v113
	v_fmac_f32_e32 v44, v185, v115
	v_fmac_f32_e32 v45, v185, v117
	v_fmac_f32_e32 v46, v185, v119
	v_fmac_f32_e32 v47, v185, v121
	v_fmac_f32_e32 v48, v185, v123
	v_fmac_f32_e32 v49, v185, v125
	v_fmac_f32_e32 v60, v185, v129
	global_load_dword v217, v[50:51], off
	v_add_co_u32_e32 v62, vcc, s60, v50
	s_nop 1
	v_addc_co_u32_e32 v63, vcc, 0, v51, vcc
	v_lshl_add_u64 v[50:51], v[50:51], 0, s[24:25]
	global_load_dword v218, v[62:63], off
	v_add_u32_e32 v61, 88, v57
	v_add_u32_e32 v150, 88, v149
	ds_read2st64_b64 v[62:65], v61 offset1:4
	ds_read2st64_b64 v[66:69], v61 offset0:8 offset1:12
	ds_read2st64_b64 v[70:73], v61 offset0:16 offset1:20
	ds_read2st64_b64 v[74:77], v61 offset0:24 offset1:28
	ds_read2st64_b64 v[78:81], v61 offset0:32 offset1:36
	ds_read2st64_b64 v[82:85], v61 offset0:40 offset1:44
	ds_read2st64_b64 v[86:89], v61 offset0:48 offset1:52
	ds_read2st64_b64 v[90:93], v61 offset0:56 offset1:60
	ds_read2st64_b64 v[94:97], v61 offset0:64 offset1:68
	ds_read2st64_b64 v[98:101], v61 offset0:72 offset1:76
	ds_read2st64_b64 v[102:105], v61 offset0:80 offset1:84
	ds_read2st64_b64 v[106:109], v61 offset0:88 offset1:92
	ds_read2st64_b64 v[110:113], v61 offset0:96 offset1:100
	ds_read2st64_b64 v[114:117], v61 offset0:104 offset1:108
	ds_read2st64_b64 v[118:121], v61 offset0:112 offset1:116
	ds_read2st64_b64 v[122:125], v61 offset0:120 offset1:124
	ds_read_b64 v[128:129], v150
	s_waitcnt vmcnt(30)
	s_waitcnt lgkmcnt(15)
	v_fmac_f32_e32 v30, v186, v62
	v_fmac_f32_e32 v43, v186, v64
	s_waitcnt lgkmcnt(15)
	v_fmac_f32_e32 v42, v186, v66
	v_fmac_f32_e32 v35, v186, v68
	s_waitcnt lgkmcnt(14)
	v_fmac_f32_e32 v34, v186, v70
	v_fmac_f32_e32 v29, v186, v72
	s_waitcnt lgkmcnt(13)
	v_fmac_f32_e32 v28, v186, v74
	v_fmac_f32_e32 v27, v186, v76
	s_waitcnt lgkmcnt(12)
	v_fmac_f32_e32 v26, v186, v78
	v_fmac_f32_e32 v25, v186, v80
	s_waitcnt lgkmcnt(11)
	v_fmac_f32_e32 v24, v186, v82
	v_fmac_f32_e32 v23, v186, v84
	s_waitcnt lgkmcnt(10)
	v_fmac_f32_e32 v22, v186, v86
	v_fmac_f32_e32 v21, v186, v88
	s_waitcnt lgkmcnt(9)
	v_fmac_f32_e32 v20, v186, v90
	v_fmac_f32_e32 v17, v186, v92
	s_waitcnt lgkmcnt(8)
	v_fmac_f32_e32 v16, v186, v94
	v_fmac_f32_e32 v31, v186, v96
	s_waitcnt lgkmcnt(7)
	v_fmac_f32_e32 v32, v186, v98
	v_fmac_f32_e32 v33, v186, v100
	s_waitcnt lgkmcnt(6)
	v_fmac_f32_e32 v36, v186, v102
	v_fmac_f32_e32 v37, v186, v104
	s_waitcnt lgkmcnt(5)
	v_fmac_f32_e32 v38, v186, v106
	v_fmac_f32_e32 v39, v186, v108
	s_waitcnt lgkmcnt(4)
	v_fmac_f32_e32 v40, v186, v110
	v_fmac_f32_e32 v41, v186, v112
	s_waitcnt lgkmcnt(3)
	v_fmac_f32_e32 v44, v186, v114
	v_fmac_f32_e32 v45, v186, v116
	s_waitcnt lgkmcnt(2)
	v_fmac_f32_e32 v46, v186, v118
	v_fmac_f32_e32 v47, v186, v120
	s_waitcnt lgkmcnt(1)
	v_fmac_f32_e32 v48, v186, v122
	v_fmac_f32_e32 v49, v186, v124
	s_waitcnt lgkmcnt(0)
	v_fmac_f32_e32 v60, v186, v128
	v_fmac_f32_e32 v30, v187, v63
	v_fmac_f32_e32 v43, v187, v65
	v_fmac_f32_e32 v42, v187, v67
	v_fmac_f32_e32 v35, v187, v69
	v_fmac_f32_e32 v34, v187, v71
	v_fmac_f32_e32 v29, v187, v73
	v_fmac_f32_e32 v28, v187, v75
	v_fmac_f32_e32 v27, v187, v77
	v_fmac_f32_e32 v26, v187, v79
	v_fmac_f32_e32 v25, v187, v81
	v_fmac_f32_e32 v24, v187, v83
	v_fmac_f32_e32 v23, v187, v85
	v_fmac_f32_e32 v22, v187, v87
	v_fmac_f32_e32 v21, v187, v89
	v_fmac_f32_e32 v20, v187, v91
	v_fmac_f32_e32 v17, v187, v93
	v_fmac_f32_e32 v16, v187, v95
	v_fmac_f32_e32 v31, v187, v97
	v_fmac_f32_e32 v32, v187, v99
	v_fmac_f32_e32 v33, v187, v101
	v_fmac_f32_e32 v36, v187, v103
	v_fmac_f32_e32 v37, v187, v105
	v_fmac_f32_e32 v38, v187, v107
	v_fmac_f32_e32 v39, v187, v109
	v_fmac_f32_e32 v40, v187, v111
	v_fmac_f32_e32 v41, v187, v113
	v_fmac_f32_e32 v44, v187, v115
	v_fmac_f32_e32 v45, v187, v117
	v_fmac_f32_e32 v46, v187, v119
	v_fmac_f32_e32 v47, v187, v121
	v_fmac_f32_e32 v48, v187, v123
	v_fmac_f32_e32 v49, v187, v125
	v_fmac_f32_e32 v60, v187, v129
	global_load_dword v219, v[50:51], off
	v_add_co_u32_e32 v62, vcc, s60, v50
	s_nop 1
	v_addc_co_u32_e32 v63, vcc, 0, v51, vcc
	v_lshl_add_u64 v[50:51], v[50:51], 0, s[24:25]
	global_load_dword v220, v[62:63], off
	v_add_u32_e32 v61, 96, v57
	v_add_u32_e32 v150, 96, v149
	ds_read2st64_b64 v[62:65], v61 offset1:4
	ds_read2st64_b64 v[66:69], v61 offset0:8 offset1:12
	ds_read2st64_b64 v[70:73], v61 offset0:16 offset1:20
	ds_read2st64_b64 v[74:77], v61 offset0:24 offset1:28
	ds_read2st64_b64 v[78:81], v61 offset0:32 offset1:36
	ds_read2st64_b64 v[82:85], v61 offset0:40 offset1:44
	ds_read2st64_b64 v[86:89], v61 offset0:48 offset1:52
	ds_read2st64_b64 v[90:93], v61 offset0:56 offset1:60
	ds_read2st64_b64 v[94:97], v61 offset0:64 offset1:68
	ds_read2st64_b64 v[98:101], v61 offset0:72 offset1:76
	ds_read2st64_b64 v[102:105], v61 offset0:80 offset1:84
	ds_read2st64_b64 v[106:109], v61 offset0:88 offset1:92
	ds_read2st64_b64 v[110:113], v61 offset0:96 offset1:100
	ds_read2st64_b64 v[114:117], v61 offset0:104 offset1:108
	ds_read2st64_b64 v[118:121], v61 offset0:112 offset1:116
	ds_read2st64_b64 v[122:125], v61 offset0:120 offset1:124
	ds_read_b64 v[128:129], v150
	s_waitcnt vmcnt(30)
	s_waitcnt lgkmcnt(15)
	v_fmac_f32_e32 v30, v188, v62
	v_fmac_f32_e32 v43, v188, v64
	s_waitcnt lgkmcnt(15)
	v_fmac_f32_e32 v42, v188, v66
	v_fmac_f32_e32 v35, v188, v68
	s_waitcnt lgkmcnt(14)
	v_fmac_f32_e32 v34, v188, v70
	v_fmac_f32_e32 v29, v188, v72
	s_waitcnt lgkmcnt(13)
	v_fmac_f32_e32 v28, v188, v74
	v_fmac_f32_e32 v27, v188, v76
	s_waitcnt lgkmcnt(12)
	v_fmac_f32_e32 v26, v188, v78
	v_fmac_f32_e32 v25, v188, v80
	s_waitcnt lgkmcnt(11)
	v_fmac_f32_e32 v24, v188, v82
	v_fmac_f32_e32 v23, v188, v84
	s_waitcnt lgkmcnt(10)
	v_fmac_f32_e32 v22, v188, v86
	v_fmac_f32_e32 v21, v188, v88
	s_waitcnt lgkmcnt(9)
	v_fmac_f32_e32 v20, v188, v90
	v_fmac_f32_e32 v17, v188, v92
	s_waitcnt lgkmcnt(8)
	v_fmac_f32_e32 v16, v188, v94
	v_fmac_f32_e32 v31, v188, v96
	s_waitcnt lgkmcnt(7)
	v_fmac_f32_e32 v32, v188, v98
	v_fmac_f32_e32 v33, v188, v100
	s_waitcnt lgkmcnt(6)
	v_fmac_f32_e32 v36, v188, v102
	v_fmac_f32_e32 v37, v188, v104
	s_waitcnt lgkmcnt(5)
	v_fmac_f32_e32 v38, v188, v106
	v_fmac_f32_e32 v39, v188, v108
	s_waitcnt lgkmcnt(4)
	v_fmac_f32_e32 v40, v188, v110
	v_fmac_f32_e32 v41, v188, v112
	s_waitcnt lgkmcnt(3)
	v_fmac_f32_e32 v44, v188, v114
	v_fmac_f32_e32 v45, v188, v116
	s_waitcnt lgkmcnt(2)
	v_fmac_f32_e32 v46, v188, v118
	v_fmac_f32_e32 v47, v188, v120
	s_waitcnt lgkmcnt(1)
	v_fmac_f32_e32 v48, v188, v122
	v_fmac_f32_e32 v49, v188, v124
	s_waitcnt lgkmcnt(0)
	v_fmac_f32_e32 v60, v188, v128
	v_fmac_f32_e32 v30, v189, v63
	v_fmac_f32_e32 v43, v189, v65
	v_fmac_f32_e32 v42, v189, v67
	v_fmac_f32_e32 v35, v189, v69
	v_fmac_f32_e32 v34, v189, v71
	v_fmac_f32_e32 v29, v189, v73
	v_fmac_f32_e32 v28, v189, v75
	v_fmac_f32_e32 v27, v189, v77
	v_fmac_f32_e32 v26, v189, v79
	v_fmac_f32_e32 v25, v189, v81
	v_fmac_f32_e32 v24, v189, v83
	v_fmac_f32_e32 v23, v189, v85
	v_fmac_f32_e32 v22, v189, v87
	v_fmac_f32_e32 v21, v189, v89
	v_fmac_f32_e32 v20, v189, v91
	v_fmac_f32_e32 v17, v189, v93
	v_fmac_f32_e32 v16, v189, v95
	v_fmac_f32_e32 v31, v189, v97
	v_fmac_f32_e32 v32, v189, v99
	v_fmac_f32_e32 v33, v189, v101
	v_fmac_f32_e32 v36, v189, v103
	v_fmac_f32_e32 v37, v189, v105
	v_fmac_f32_e32 v38, v189, v107
	v_fmac_f32_e32 v39, v189, v109
	v_fmac_f32_e32 v40, v189, v111
	v_fmac_f32_e32 v41, v189, v113
	v_fmac_f32_e32 v44, v189, v115
	v_fmac_f32_e32 v45, v189, v117
	v_fmac_f32_e32 v46, v189, v119
	v_fmac_f32_e32 v47, v189, v121
	v_fmac_f32_e32 v48, v189, v123
	v_fmac_f32_e32 v49, v189, v125
	v_fmac_f32_e32 v60, v189, v129
	global_load_dword v221, v[50:51], off
	v_add_co_u32_e32 v62, vcc, s60, v50
	s_nop 1
	v_addc_co_u32_e32 v63, vcc, 0, v51, vcc
	v_lshl_add_u64 v[50:51], v[50:51], 0, s[24:25]
	global_load_dword v222, v[62:63], off
	v_add_u32_e32 v61, 104, v57
	v_add_u32_e32 v150, 104, v149
	ds_read2st64_b64 v[62:65], v61 offset1:4
	ds_read2st64_b64 v[66:69], v61 offset0:8 offset1:12
	ds_read2st64_b64 v[70:73], v61 offset0:16 offset1:20
	ds_read2st64_b64 v[74:77], v61 offset0:24 offset1:28
	ds_read2st64_b64 v[78:81], v61 offset0:32 offset1:36
	ds_read2st64_b64 v[82:85], v61 offset0:40 offset1:44
	ds_read2st64_b64 v[86:89], v61 offset0:48 offset1:52
	ds_read2st64_b64 v[90:93], v61 offset0:56 offset1:60
	ds_read2st64_b64 v[94:97], v61 offset0:64 offset1:68
	ds_read2st64_b64 v[98:101], v61 offset0:72 offset1:76
	ds_read2st64_b64 v[102:105], v61 offset0:80 offset1:84
	ds_read2st64_b64 v[106:109], v61 offset0:88 offset1:92
	ds_read2st64_b64 v[110:113], v61 offset0:96 offset1:100
	ds_read2st64_b64 v[114:117], v61 offset0:104 offset1:108
	ds_read2st64_b64 v[118:121], v61 offset0:112 offset1:116
	ds_read2st64_b64 v[122:125], v61 offset0:120 offset1:124
	ds_read_b64 v[128:129], v150
	s_waitcnt vmcnt(30)
	s_waitcnt lgkmcnt(15)
	v_fmac_f32_e32 v30, v190, v62
	v_fmac_f32_e32 v43, v190, v64
	s_waitcnt lgkmcnt(15)
	v_fmac_f32_e32 v42, v190, v66
	v_fmac_f32_e32 v35, v190, v68
	s_waitcnt lgkmcnt(14)
	v_fmac_f32_e32 v34, v190, v70
	v_fmac_f32_e32 v29, v190, v72
	s_waitcnt lgkmcnt(13)
	v_fmac_f32_e32 v28, v190, v74
	v_fmac_f32_e32 v27, v190, v76
	s_waitcnt lgkmcnt(12)
	v_fmac_f32_e32 v26, v190, v78
	v_fmac_f32_e32 v25, v190, v80
	s_waitcnt lgkmcnt(11)
	v_fmac_f32_e32 v24, v190, v82
	v_fmac_f32_e32 v23, v190, v84
	s_waitcnt lgkmcnt(10)
	v_fmac_f32_e32 v22, v190, v86
	v_fmac_f32_e32 v21, v190, v88
	s_waitcnt lgkmcnt(9)
	v_fmac_f32_e32 v20, v190, v90
	v_fmac_f32_e32 v17, v190, v92
	s_waitcnt lgkmcnt(8)
	v_fmac_f32_e32 v16, v190, v94
	v_fmac_f32_e32 v31, v190, v96
	s_waitcnt lgkmcnt(7)
	v_fmac_f32_e32 v32, v190, v98
	v_fmac_f32_e32 v33, v190, v100
	s_waitcnt lgkmcnt(6)
	v_fmac_f32_e32 v36, v190, v102
	v_fmac_f32_e32 v37, v190, v104
	s_waitcnt lgkmcnt(5)
	v_fmac_f32_e32 v38, v190, v106
	v_fmac_f32_e32 v39, v190, v108
	s_waitcnt lgkmcnt(4)
	v_fmac_f32_e32 v40, v190, v110
	v_fmac_f32_e32 v41, v190, v112
	s_waitcnt lgkmcnt(3)
	v_fmac_f32_e32 v44, v190, v114
	v_fmac_f32_e32 v45, v190, v116
	s_waitcnt lgkmcnt(2)
	v_fmac_f32_e32 v46, v190, v118
	v_fmac_f32_e32 v47, v190, v120
	s_waitcnt lgkmcnt(1)
	v_fmac_f32_e32 v48, v190, v122
	v_fmac_f32_e32 v49, v190, v124
	s_waitcnt lgkmcnt(0)
	v_fmac_f32_e32 v60, v190, v128
	v_fmac_f32_e32 v30, v191, v63
	v_fmac_f32_e32 v43, v191, v65
	v_fmac_f32_e32 v42, v191, v67
	v_fmac_f32_e32 v35, v191, v69
	v_fmac_f32_e32 v34, v191, v71
	v_fmac_f32_e32 v29, v191, v73
	v_fmac_f32_e32 v28, v191, v75
	v_fmac_f32_e32 v27, v191, v77
	v_fmac_f32_e32 v26, v191, v79
	v_fmac_f32_e32 v25, v191, v81
	v_fmac_f32_e32 v24, v191, v83
	v_fmac_f32_e32 v23, v191, v85
	v_fmac_f32_e32 v22, v191, v87
	v_fmac_f32_e32 v21, v191, v89
	v_fmac_f32_e32 v20, v191, v91
	v_fmac_f32_e32 v17, v191, v93
	v_fmac_f32_e32 v16, v191, v95
	v_fmac_f32_e32 v31, v191, v97
	v_fmac_f32_e32 v32, v191, v99
	v_fmac_f32_e32 v33, v191, v101
	v_fmac_f32_e32 v36, v191, v103
	v_fmac_f32_e32 v37, v191, v105
	v_fmac_f32_e32 v38, v191, v107
	v_fmac_f32_e32 v39, v191, v109
	v_fmac_f32_e32 v40, v191, v111
	v_fmac_f32_e32 v41, v191, v113
	v_fmac_f32_e32 v44, v191, v115
	v_fmac_f32_e32 v45, v191, v117
	v_fmac_f32_e32 v46, v191, v119
	v_fmac_f32_e32 v47, v191, v121
	v_fmac_f32_e32 v48, v191, v123
	v_fmac_f32_e32 v49, v191, v125
	v_fmac_f32_e32 v60, v191, v129
	global_load_dword v223, v[50:51], off
	v_add_co_u32_e32 v62, vcc, s60, v50
	s_nop 1
	v_addc_co_u32_e32 v63, vcc, 0, v51, vcc
	v_lshl_add_u64 v[50:51], v[50:51], 0, s[24:25]
	global_load_dword v224, v[62:63], off
	v_add_u32_e32 v61, 112, v57
	v_add_u32_e32 v150, 112, v149
	ds_read2st64_b64 v[62:65], v61 offset1:4
	ds_read2st64_b64 v[66:69], v61 offset0:8 offset1:12
	ds_read2st64_b64 v[70:73], v61 offset0:16 offset1:20
	ds_read2st64_b64 v[74:77], v61 offset0:24 offset1:28
	ds_read2st64_b64 v[78:81], v61 offset0:32 offset1:36
	ds_read2st64_b64 v[82:85], v61 offset0:40 offset1:44
	ds_read2st64_b64 v[86:89], v61 offset0:48 offset1:52
	ds_read2st64_b64 v[90:93], v61 offset0:56 offset1:60
	ds_read2st64_b64 v[94:97], v61 offset0:64 offset1:68
	ds_read2st64_b64 v[98:101], v61 offset0:72 offset1:76
	ds_read2st64_b64 v[102:105], v61 offset0:80 offset1:84
	ds_read2st64_b64 v[106:109], v61 offset0:88 offset1:92
	ds_read2st64_b64 v[110:113], v61 offset0:96 offset1:100
	ds_read2st64_b64 v[114:117], v61 offset0:104 offset1:108
	ds_read2st64_b64 v[118:121], v61 offset0:112 offset1:116
	ds_read2st64_b64 v[122:125], v61 offset0:120 offset1:124
	ds_read_b64 v[128:129], v150
	s_waitcnt vmcnt(30)
	s_waitcnt lgkmcnt(15)
	v_fmac_f32_e32 v30, v192, v62
	v_fmac_f32_e32 v43, v192, v64
	s_waitcnt lgkmcnt(15)
	v_fmac_f32_e32 v42, v192, v66
	v_fmac_f32_e32 v35, v192, v68
	s_waitcnt lgkmcnt(14)
	v_fmac_f32_e32 v34, v192, v70
	v_fmac_f32_e32 v29, v192, v72
	s_waitcnt lgkmcnt(13)
	v_fmac_f32_e32 v28, v192, v74
	v_fmac_f32_e32 v27, v192, v76
	s_waitcnt lgkmcnt(12)
	v_fmac_f32_e32 v26, v192, v78
	v_fmac_f32_e32 v25, v192, v80
	s_waitcnt lgkmcnt(11)
	v_fmac_f32_e32 v24, v192, v82
	v_fmac_f32_e32 v23, v192, v84
	s_waitcnt lgkmcnt(10)
	v_fmac_f32_e32 v22, v192, v86
	v_fmac_f32_e32 v21, v192, v88
	s_waitcnt lgkmcnt(9)
	v_fmac_f32_e32 v20, v192, v90
	v_fmac_f32_e32 v17, v192, v92
	s_waitcnt lgkmcnt(8)
	v_fmac_f32_e32 v16, v192, v94
	v_fmac_f32_e32 v31, v192, v96
	s_waitcnt lgkmcnt(7)
	v_fmac_f32_e32 v32, v192, v98
	v_fmac_f32_e32 v33, v192, v100
	s_waitcnt lgkmcnt(6)
	v_fmac_f32_e32 v36, v192, v102
	v_fmac_f32_e32 v37, v192, v104
	s_waitcnt lgkmcnt(5)
	v_fmac_f32_e32 v38, v192, v106
	v_fmac_f32_e32 v39, v192, v108
	s_waitcnt lgkmcnt(4)
	v_fmac_f32_e32 v40, v192, v110
	v_fmac_f32_e32 v41, v192, v112
	s_waitcnt lgkmcnt(3)
	v_fmac_f32_e32 v44, v192, v114
	v_fmac_f32_e32 v45, v192, v116
	s_waitcnt lgkmcnt(2)
	v_fmac_f32_e32 v46, v192, v118
	v_fmac_f32_e32 v47, v192, v120
	s_waitcnt lgkmcnt(1)
	v_fmac_f32_e32 v48, v192, v122
	v_fmac_f32_e32 v49, v192, v124
	s_waitcnt lgkmcnt(0)
	v_fmac_f32_e32 v60, v192, v128
	v_fmac_f32_e32 v30, v193, v63
	v_fmac_f32_e32 v43, v193, v65
	v_fmac_f32_e32 v42, v193, v67
	v_fmac_f32_e32 v35, v193, v69
	v_fmac_f32_e32 v34, v193, v71
	v_fmac_f32_e32 v29, v193, v73
	v_fmac_f32_e32 v28, v193, v75
	v_fmac_f32_e32 v27, v193, v77
	v_fmac_f32_e32 v26, v193, v79
	v_fmac_f32_e32 v25, v193, v81
	v_fmac_f32_e32 v24, v193, v83
	v_fmac_f32_e32 v23, v193, v85
	v_fmac_f32_e32 v22, v193, v87
	v_fmac_f32_e32 v21, v193, v89
	v_fmac_f32_e32 v20, v193, v91
	v_fmac_f32_e32 v17, v193, v93
	v_fmac_f32_e32 v16, v193, v95
	v_fmac_f32_e32 v31, v193, v97
	v_fmac_f32_e32 v32, v193, v99
	v_fmac_f32_e32 v33, v193, v101
	v_fmac_f32_e32 v36, v193, v103
	v_fmac_f32_e32 v37, v193, v105
	v_fmac_f32_e32 v38, v193, v107
	v_fmac_f32_e32 v39, v193, v109
	v_fmac_f32_e32 v40, v193, v111
	v_fmac_f32_e32 v41, v193, v113
	v_fmac_f32_e32 v44, v193, v115
	v_fmac_f32_e32 v45, v193, v117
	v_fmac_f32_e32 v46, v193, v119
	v_fmac_f32_e32 v47, v193, v121
	v_fmac_f32_e32 v48, v193, v123
	v_fmac_f32_e32 v49, v193, v125
	v_fmac_f32_e32 v60, v193, v129
	global_load_dword v225, v[50:51], off
	v_add_co_u32_e32 v62, vcc, s60, v50
	s_nop 1
	v_addc_co_u32_e32 v63, vcc, 0, v51, vcc
	v_lshl_add_u64 v[50:51], v[50:51], 0, s[24:25]
	global_load_dword v226, v[62:63], off
	v_add_u32_e32 v61, 120, v57
	v_add_u32_e32 v150, 120, v149
	ds_read2st64_b64 v[62:65], v61 offset1:4
	ds_read2st64_b64 v[66:69], v61 offset0:8 offset1:12
	ds_read2st64_b64 v[70:73], v61 offset0:16 offset1:20
	ds_read2st64_b64 v[74:77], v61 offset0:24 offset1:28
	ds_read2st64_b64 v[78:81], v61 offset0:32 offset1:36
	ds_read2st64_b64 v[82:85], v61 offset0:40 offset1:44
	ds_read2st64_b64 v[86:89], v61 offset0:48 offset1:52
	ds_read2st64_b64 v[90:93], v61 offset0:56 offset1:60
	ds_read2st64_b64 v[94:97], v61 offset0:64 offset1:68
	ds_read2st64_b64 v[98:101], v61 offset0:72 offset1:76
	ds_read2st64_b64 v[102:105], v61 offset0:80 offset1:84
	ds_read2st64_b64 v[106:109], v61 offset0:88 offset1:92
	ds_read2st64_b64 v[110:113], v61 offset0:96 offset1:100
	ds_read2st64_b64 v[114:117], v61 offset0:104 offset1:108
	ds_read2st64_b64 v[118:121], v61 offset0:112 offset1:116
	ds_read2st64_b64 v[122:125], v61 offset0:120 offset1:124
	ds_read_b64 v[128:129], v150
	s_waitcnt vmcnt(30)
	s_waitcnt lgkmcnt(15)
	v_fmac_f32_e32 v30, v194, v62
	v_fmac_f32_e32 v43, v194, v64
	s_waitcnt lgkmcnt(15)
	v_fmac_f32_e32 v42, v194, v66
	v_fmac_f32_e32 v35, v194, v68
	s_waitcnt lgkmcnt(14)
	v_fmac_f32_e32 v34, v194, v70
	v_fmac_f32_e32 v29, v194, v72
	s_waitcnt lgkmcnt(13)
	v_fmac_f32_e32 v28, v194, v74
	v_fmac_f32_e32 v27, v194, v76
	s_waitcnt lgkmcnt(12)
	v_fmac_f32_e32 v26, v194, v78
	v_fmac_f32_e32 v25, v194, v80
	s_waitcnt lgkmcnt(11)
	v_fmac_f32_e32 v24, v194, v82
	v_fmac_f32_e32 v23, v194, v84
	s_waitcnt lgkmcnt(10)
	v_fmac_f32_e32 v22, v194, v86
	v_fmac_f32_e32 v21, v194, v88
	s_waitcnt lgkmcnt(9)
	v_fmac_f32_e32 v20, v194, v90
	v_fmac_f32_e32 v17, v194, v92
	s_waitcnt lgkmcnt(8)
	v_fmac_f32_e32 v16, v194, v94
	v_fmac_f32_e32 v31, v194, v96
	s_waitcnt lgkmcnt(7)
	v_fmac_f32_e32 v32, v194, v98
	v_fmac_f32_e32 v33, v194, v100
	s_waitcnt lgkmcnt(6)
	v_fmac_f32_e32 v36, v194, v102
	v_fmac_f32_e32 v37, v194, v104
	s_waitcnt lgkmcnt(5)
	v_fmac_f32_e32 v38, v194, v106
	v_fmac_f32_e32 v39, v194, v108
	s_waitcnt lgkmcnt(4)
	v_fmac_f32_e32 v40, v194, v110
	v_fmac_f32_e32 v41, v194, v112
	s_waitcnt lgkmcnt(3)
	v_fmac_f32_e32 v44, v194, v114
	v_fmac_f32_e32 v45, v194, v116
	s_waitcnt lgkmcnt(2)
	v_fmac_f32_e32 v46, v194, v118
	v_fmac_f32_e32 v47, v194, v120
	s_waitcnt lgkmcnt(1)
	v_fmac_f32_e32 v48, v194, v122
	v_fmac_f32_e32 v49, v194, v124
	s_waitcnt lgkmcnt(0)
	v_fmac_f32_e32 v60, v194, v128
	v_fmac_f32_e32 v30, v195, v63
	v_fmac_f32_e32 v43, v195, v65
	v_fmac_f32_e32 v42, v195, v67
	v_fmac_f32_e32 v35, v195, v69
	v_fmac_f32_e32 v34, v195, v71
	v_fmac_f32_e32 v29, v195, v73
	v_fmac_f32_e32 v28, v195, v75
	v_fmac_f32_e32 v27, v195, v77
	v_fmac_f32_e32 v26, v195, v79
	v_fmac_f32_e32 v25, v195, v81
	v_fmac_f32_e32 v24, v195, v83
	v_fmac_f32_e32 v23, v195, v85
	v_fmac_f32_e32 v22, v195, v87
	v_fmac_f32_e32 v21, v195, v89
	v_fmac_f32_e32 v20, v195, v91
	v_fmac_f32_e32 v17, v195, v93
	v_fmac_f32_e32 v16, v195, v95
	v_fmac_f32_e32 v31, v195, v97
	v_fmac_f32_e32 v32, v195, v99
	v_fmac_f32_e32 v33, v195, v101
	v_fmac_f32_e32 v36, v195, v103
	v_fmac_f32_e32 v37, v195, v105
	v_fmac_f32_e32 v38, v195, v107
	v_fmac_f32_e32 v39, v195, v109
	v_fmac_f32_e32 v40, v195, v111
	v_fmac_f32_e32 v41, v195, v113
	v_fmac_f32_e32 v44, v195, v115
	v_fmac_f32_e32 v45, v195, v117
	v_fmac_f32_e32 v46, v195, v119
	v_fmac_f32_e32 v47, v195, v121
	v_fmac_f32_e32 v48, v195, v123
	v_fmac_f32_e32 v49, v195, v125
	v_fmac_f32_e32 v60, v195, v129
	global_load_dword v227, v[50:51], off
	v_add_co_u32_e32 v62, vcc, s60, v50
	s_nop 1
	v_addc_co_u32_e32 v63, vcc, 0, v51, vcc
	v_lshl_add_u64 v[50:51], v[50:51], 0, s[24:25]
	global_load_dword v228, v[62:63], off
	v_add_u32_e32 v61, 128, v57
	v_add_u32_e32 v150, 128, v149
	ds_read2st64_b64 v[62:65], v61 offset1:4
	ds_read2st64_b64 v[66:69], v61 offset0:8 offset1:12
	ds_read2st64_b64 v[70:73], v61 offset0:16 offset1:20
	ds_read2st64_b64 v[74:77], v61 offset0:24 offset1:28
	ds_read2st64_b64 v[78:81], v61 offset0:32 offset1:36
	ds_read2st64_b64 v[82:85], v61 offset0:40 offset1:44
	ds_read2st64_b64 v[86:89], v61 offset0:48 offset1:52
	ds_read2st64_b64 v[90:93], v61 offset0:56 offset1:60
	ds_read2st64_b64 v[94:97], v61 offset0:64 offset1:68
	ds_read2st64_b64 v[98:101], v61 offset0:72 offset1:76
	ds_read2st64_b64 v[102:105], v61 offset0:80 offset1:84
	ds_read2st64_b64 v[106:109], v61 offset0:88 offset1:92
	ds_read2st64_b64 v[110:113], v61 offset0:96 offset1:100
	ds_read2st64_b64 v[114:117], v61 offset0:104 offset1:108
	ds_read2st64_b64 v[118:121], v61 offset0:112 offset1:116
	ds_read2st64_b64 v[122:125], v61 offset0:120 offset1:124
	ds_read_b64 v[128:129], v150
	s_waitcnt vmcnt(30)
	s_waitcnt lgkmcnt(15)
	v_fmac_f32_e32 v30, v196, v62
	v_fmac_f32_e32 v43, v196, v64
	s_waitcnt lgkmcnt(15)
	v_fmac_f32_e32 v42, v196, v66
	v_fmac_f32_e32 v35, v196, v68
	s_waitcnt lgkmcnt(14)
	v_fmac_f32_e32 v34, v196, v70
	v_fmac_f32_e32 v29, v196, v72
	s_waitcnt lgkmcnt(13)
	v_fmac_f32_e32 v28, v196, v74
	v_fmac_f32_e32 v27, v196, v76
	s_waitcnt lgkmcnt(12)
	v_fmac_f32_e32 v26, v196, v78
	v_fmac_f32_e32 v25, v196, v80
	s_waitcnt lgkmcnt(11)
	v_fmac_f32_e32 v24, v196, v82
	v_fmac_f32_e32 v23, v196, v84
	s_waitcnt lgkmcnt(10)
	v_fmac_f32_e32 v22, v196, v86
	v_fmac_f32_e32 v21, v196, v88
	s_waitcnt lgkmcnt(9)
	v_fmac_f32_e32 v20, v196, v90
	v_fmac_f32_e32 v17, v196, v92
	s_waitcnt lgkmcnt(8)
	v_fmac_f32_e32 v16, v196, v94
	v_fmac_f32_e32 v31, v196, v96
	s_waitcnt lgkmcnt(7)
	v_fmac_f32_e32 v32, v196, v98
	v_fmac_f32_e32 v33, v196, v100
	s_waitcnt lgkmcnt(6)
	v_fmac_f32_e32 v36, v196, v102
	v_fmac_f32_e32 v37, v196, v104
	s_waitcnt lgkmcnt(5)
	v_fmac_f32_e32 v38, v196, v106
	v_fmac_f32_e32 v39, v196, v108
	s_waitcnt lgkmcnt(4)
	v_fmac_f32_e32 v40, v196, v110
	v_fmac_f32_e32 v41, v196, v112
	s_waitcnt lgkmcnt(3)
	v_fmac_f32_e32 v44, v196, v114
	v_fmac_f32_e32 v45, v196, v116
	s_waitcnt lgkmcnt(2)
	v_fmac_f32_e32 v46, v196, v118
	v_fmac_f32_e32 v47, v196, v120
	s_waitcnt lgkmcnt(1)
	v_fmac_f32_e32 v48, v196, v122
	v_fmac_f32_e32 v49, v196, v124
	s_waitcnt lgkmcnt(0)
	v_fmac_f32_e32 v60, v196, v128
	v_fmac_f32_e32 v30, v197, v63
	v_fmac_f32_e32 v43, v197, v65
	v_fmac_f32_e32 v42, v197, v67
	v_fmac_f32_e32 v35, v197, v69
	v_fmac_f32_e32 v34, v197, v71
	v_fmac_f32_e32 v29, v197, v73
	v_fmac_f32_e32 v28, v197, v75
	v_fmac_f32_e32 v27, v197, v77
	v_fmac_f32_e32 v26, v197, v79
	v_fmac_f32_e32 v25, v197, v81
	v_fmac_f32_e32 v24, v197, v83
	v_fmac_f32_e32 v23, v197, v85
	v_fmac_f32_e32 v22, v197, v87
	v_fmac_f32_e32 v21, v197, v89
	v_fmac_f32_e32 v20, v197, v91
	v_fmac_f32_e32 v17, v197, v93
	v_fmac_f32_e32 v16, v197, v95
	v_fmac_f32_e32 v31, v197, v97
	v_fmac_f32_e32 v32, v197, v99
	v_fmac_f32_e32 v33, v197, v101
	v_fmac_f32_e32 v36, v197, v103
	v_fmac_f32_e32 v37, v197, v105
	v_fmac_f32_e32 v38, v197, v107
	v_fmac_f32_e32 v39, v197, v109
	v_fmac_f32_e32 v40, v197, v111
	v_fmac_f32_e32 v41, v197, v113
	v_fmac_f32_e32 v44, v197, v115
	v_fmac_f32_e32 v45, v197, v117
	v_fmac_f32_e32 v46, v197, v119
	v_fmac_f32_e32 v47, v197, v121
	v_fmac_f32_e32 v48, v197, v123
	v_fmac_f32_e32 v49, v197, v125
	v_fmac_f32_e32 v60, v197, v129
	v_add_u32_e32 v61, 136, v57
	v_add_u32_e32 v150, 136, v149
	ds_read2st64_b64 v[62:65], v61 offset1:4
	ds_read2st64_b64 v[66:69], v61 offset0:8 offset1:12
	ds_read2st64_b64 v[70:73], v61 offset0:16 offset1:20
	ds_read2st64_b64 v[74:77], v61 offset0:24 offset1:28
	ds_read2st64_b64 v[78:81], v61 offset0:32 offset1:36
	ds_read2st64_b64 v[82:85], v61 offset0:40 offset1:44
	ds_read2st64_b64 v[86:89], v61 offset0:48 offset1:52
	ds_read2st64_b64 v[90:93], v61 offset0:56 offset1:60
	ds_read2st64_b64 v[94:97], v61 offset0:64 offset1:68
	ds_read2st64_b64 v[98:101], v61 offset0:72 offset1:76
	ds_read2st64_b64 v[102:105], v61 offset0:80 offset1:84
	ds_read2st64_b64 v[106:109], v61 offset0:88 offset1:92
	ds_read2st64_b64 v[110:113], v61 offset0:96 offset1:100
	ds_read2st64_b64 v[114:117], v61 offset0:104 offset1:108
	ds_read2st64_b64 v[118:121], v61 offset0:112 offset1:116
	ds_read2st64_b64 v[122:125], v61 offset0:120 offset1:124
	ds_read_b64 v[128:129], v150
	s_waitcnt vmcnt(28)
	s_waitcnt lgkmcnt(15)
	v_fmac_f32_e32 v30, v198, v62
	v_fmac_f32_e32 v43, v198, v64
	s_waitcnt lgkmcnt(15)
	v_fmac_f32_e32 v42, v198, v66
	v_fmac_f32_e32 v35, v198, v68
	s_waitcnt lgkmcnt(14)
	v_fmac_f32_e32 v34, v198, v70
	v_fmac_f32_e32 v29, v198, v72
	s_waitcnt lgkmcnt(13)
	v_fmac_f32_e32 v28, v198, v74
	v_fmac_f32_e32 v27, v198, v76
	s_waitcnt lgkmcnt(12)
	v_fmac_f32_e32 v26, v198, v78
	v_fmac_f32_e32 v25, v198, v80
	s_waitcnt lgkmcnt(11)
	v_fmac_f32_e32 v24, v198, v82
	v_fmac_f32_e32 v23, v198, v84
	s_waitcnt lgkmcnt(10)
	v_fmac_f32_e32 v22, v198, v86
	v_fmac_f32_e32 v21, v198, v88
	s_waitcnt lgkmcnt(9)
	v_fmac_f32_e32 v20, v198, v90
	v_fmac_f32_e32 v17, v198, v92
	s_waitcnt lgkmcnt(8)
	v_fmac_f32_e32 v16, v198, v94
	v_fmac_f32_e32 v31, v198, v96
	s_waitcnt lgkmcnt(7)
	v_fmac_f32_e32 v32, v198, v98
	v_fmac_f32_e32 v33, v198, v100
	s_waitcnt lgkmcnt(6)
	v_fmac_f32_e32 v36, v198, v102
	v_fmac_f32_e32 v37, v198, v104
	s_waitcnt lgkmcnt(5)
	v_fmac_f32_e32 v38, v198, v106
	v_fmac_f32_e32 v39, v198, v108
	s_waitcnt lgkmcnt(4)
	v_fmac_f32_e32 v40, v198, v110
	v_fmac_f32_e32 v41, v198, v112
	s_waitcnt lgkmcnt(3)
	v_fmac_f32_e32 v44, v198, v114
	v_fmac_f32_e32 v45, v198, v116
	s_waitcnt lgkmcnt(2)
	v_fmac_f32_e32 v46, v198, v118
	v_fmac_f32_e32 v47, v198, v120
	s_waitcnt lgkmcnt(1)
	v_fmac_f32_e32 v48, v198, v122
	v_fmac_f32_e32 v49, v198, v124
	s_waitcnt lgkmcnt(0)
	v_fmac_f32_e32 v60, v198, v128
	v_fmac_f32_e32 v30, v199, v63
	v_fmac_f32_e32 v43, v199, v65
	v_fmac_f32_e32 v42, v199, v67
	v_fmac_f32_e32 v35, v199, v69
	v_fmac_f32_e32 v34, v199, v71
	v_fmac_f32_e32 v29, v199, v73
	v_fmac_f32_e32 v28, v199, v75
	v_fmac_f32_e32 v27, v199, v77
	v_fmac_f32_e32 v26, v199, v79
	v_fmac_f32_e32 v25, v199, v81
	v_fmac_f32_e32 v24, v199, v83
	v_fmac_f32_e32 v23, v199, v85
	v_fmac_f32_e32 v22, v199, v87
	v_fmac_f32_e32 v21, v199, v89
	v_fmac_f32_e32 v20, v199, v91
	v_fmac_f32_e32 v17, v199, v93
	v_fmac_f32_e32 v16, v199, v95
	v_fmac_f32_e32 v31, v199, v97
	v_fmac_f32_e32 v32, v199, v99
	v_fmac_f32_e32 v33, v199, v101
	v_fmac_f32_e32 v36, v199, v103
	v_fmac_f32_e32 v37, v199, v105
	v_fmac_f32_e32 v38, v199, v107
	v_fmac_f32_e32 v39, v199, v109
	v_fmac_f32_e32 v40, v199, v111
	v_fmac_f32_e32 v41, v199, v113
	v_fmac_f32_e32 v44, v199, v115
	v_fmac_f32_e32 v45, v199, v117
	v_fmac_f32_e32 v46, v199, v119
	v_fmac_f32_e32 v47, v199, v121
	v_fmac_f32_e32 v48, v199, v123
	v_fmac_f32_e32 v49, v199, v125
	v_fmac_f32_e32 v60, v199, v129
	v_add_u32_e32 v61, 144, v57
	v_add_u32_e32 v150, 144, v149
	ds_read2st64_b64 v[62:65], v61 offset1:4
	ds_read2st64_b64 v[66:69], v61 offset0:8 offset1:12
	ds_read2st64_b64 v[70:73], v61 offset0:16 offset1:20
	ds_read2st64_b64 v[74:77], v61 offset0:24 offset1:28
	ds_read2st64_b64 v[78:81], v61 offset0:32 offset1:36
	ds_read2st64_b64 v[82:85], v61 offset0:40 offset1:44
	ds_read2st64_b64 v[86:89], v61 offset0:48 offset1:52
	ds_read2st64_b64 v[90:93], v61 offset0:56 offset1:60
	ds_read2st64_b64 v[94:97], v61 offset0:64 offset1:68
	ds_read2st64_b64 v[98:101], v61 offset0:72 offset1:76
	ds_read2st64_b64 v[102:105], v61 offset0:80 offset1:84
	ds_read2st64_b64 v[106:109], v61 offset0:88 offset1:92
	ds_read2st64_b64 v[110:113], v61 offset0:96 offset1:100
	ds_read2st64_b64 v[114:117], v61 offset0:104 offset1:108
	ds_read2st64_b64 v[118:121], v61 offset0:112 offset1:116
	ds_read2st64_b64 v[122:125], v61 offset0:120 offset1:124
	ds_read_b64 v[128:129], v150
	s_waitcnt vmcnt(26)
	s_waitcnt lgkmcnt(15)
	v_fmac_f32_e32 v30, v200, v62
	v_fmac_f32_e32 v43, v200, v64
	s_waitcnt lgkmcnt(15)
	v_fmac_f32_e32 v42, v200, v66
	v_fmac_f32_e32 v35, v200, v68
	s_waitcnt lgkmcnt(14)
	v_fmac_f32_e32 v34, v200, v70
	v_fmac_f32_e32 v29, v200, v72
	s_waitcnt lgkmcnt(13)
	v_fmac_f32_e32 v28, v200, v74
	v_fmac_f32_e32 v27, v200, v76
	s_waitcnt lgkmcnt(12)
	v_fmac_f32_e32 v26, v200, v78
	v_fmac_f32_e32 v25, v200, v80
	s_waitcnt lgkmcnt(11)
	v_fmac_f32_e32 v24, v200, v82
	v_fmac_f32_e32 v23, v200, v84
	s_waitcnt lgkmcnt(10)
	v_fmac_f32_e32 v22, v200, v86
	v_fmac_f32_e32 v21, v200, v88
	s_waitcnt lgkmcnt(9)
	v_fmac_f32_e32 v20, v200, v90
	v_fmac_f32_e32 v17, v200, v92
	s_waitcnt lgkmcnt(8)
	v_fmac_f32_e32 v16, v200, v94
	v_fmac_f32_e32 v31, v200, v96
	s_waitcnt lgkmcnt(7)
	v_fmac_f32_e32 v32, v200, v98
	v_fmac_f32_e32 v33, v200, v100
	s_waitcnt lgkmcnt(6)
	v_fmac_f32_e32 v36, v200, v102
	v_fmac_f32_e32 v37, v200, v104
	s_waitcnt lgkmcnt(5)
	v_fmac_f32_e32 v38, v200, v106
	v_fmac_f32_e32 v39, v200, v108
	s_waitcnt lgkmcnt(4)
	v_fmac_f32_e32 v40, v200, v110
	v_fmac_f32_e32 v41, v200, v112
	s_waitcnt lgkmcnt(3)
	v_fmac_f32_e32 v44, v200, v114
	v_fmac_f32_e32 v45, v200, v116
	s_waitcnt lgkmcnt(2)
	v_fmac_f32_e32 v46, v200, v118
	v_fmac_f32_e32 v47, v200, v120
	s_waitcnt lgkmcnt(1)
	v_fmac_f32_e32 v48, v200, v122
	v_fmac_f32_e32 v49, v200, v124
	s_waitcnt lgkmcnt(0)
	v_fmac_f32_e32 v60, v200, v128
	v_fmac_f32_e32 v30, v201, v63
	v_fmac_f32_e32 v43, v201, v65
	v_fmac_f32_e32 v42, v201, v67
	v_fmac_f32_e32 v35, v201, v69
	v_fmac_f32_e32 v34, v201, v71
	v_fmac_f32_e32 v29, v201, v73
	v_fmac_f32_e32 v28, v201, v75
	v_fmac_f32_e32 v27, v201, v77
	v_fmac_f32_e32 v26, v201, v79
	v_fmac_f32_e32 v25, v201, v81
	v_fmac_f32_e32 v24, v201, v83
	v_fmac_f32_e32 v23, v201, v85
	v_fmac_f32_e32 v22, v201, v87
	v_fmac_f32_e32 v21, v201, v89
	v_fmac_f32_e32 v20, v201, v91
	v_fmac_f32_e32 v17, v201, v93
	v_fmac_f32_e32 v16, v201, v95
	v_fmac_f32_e32 v31, v201, v97
	v_fmac_f32_e32 v32, v201, v99
	v_fmac_f32_e32 v33, v201, v101
	v_fmac_f32_e32 v36, v201, v103
	v_fmac_f32_e32 v37, v201, v105
	v_fmac_f32_e32 v38, v201, v107
	v_fmac_f32_e32 v39, v201, v109
	v_fmac_f32_e32 v40, v201, v111
	v_fmac_f32_e32 v41, v201, v113
	v_fmac_f32_e32 v44, v201, v115
	v_fmac_f32_e32 v45, v201, v117
	v_fmac_f32_e32 v46, v201, v119
	v_fmac_f32_e32 v47, v201, v121
	v_fmac_f32_e32 v48, v201, v123
	v_fmac_f32_e32 v49, v201, v125
	v_fmac_f32_e32 v60, v201, v129
	v_add_u32_e32 v61, 152, v57
	v_add_u32_e32 v150, 152, v149
	ds_read2st64_b64 v[62:65], v61 offset1:4
	ds_read2st64_b64 v[66:69], v61 offset0:8 offset1:12
	ds_read2st64_b64 v[70:73], v61 offset0:16 offset1:20
	ds_read2st64_b64 v[74:77], v61 offset0:24 offset1:28
	ds_read2st64_b64 v[78:81], v61 offset0:32 offset1:36
	ds_read2st64_b64 v[82:85], v61 offset0:40 offset1:44
	ds_read2st64_b64 v[86:89], v61 offset0:48 offset1:52
	ds_read2st64_b64 v[90:93], v61 offset0:56 offset1:60
	ds_read2st64_b64 v[94:97], v61 offset0:64 offset1:68
	ds_read2st64_b64 v[98:101], v61 offset0:72 offset1:76
	ds_read2st64_b64 v[102:105], v61 offset0:80 offset1:84
	ds_read2st64_b64 v[106:109], v61 offset0:88 offset1:92
	ds_read2st64_b64 v[110:113], v61 offset0:96 offset1:100
	ds_read2st64_b64 v[114:117], v61 offset0:104 offset1:108
	ds_read2st64_b64 v[118:121], v61 offset0:112 offset1:116
	ds_read2st64_b64 v[122:125], v61 offset0:120 offset1:124
	ds_read_b64 v[128:129], v150
	s_waitcnt vmcnt(24)
	s_waitcnt lgkmcnt(15)
	v_fmac_f32_e32 v30, v202, v62
	v_fmac_f32_e32 v43, v202, v64
	s_waitcnt lgkmcnt(15)
	v_fmac_f32_e32 v42, v202, v66
	v_fmac_f32_e32 v35, v202, v68
	s_waitcnt lgkmcnt(14)
	v_fmac_f32_e32 v34, v202, v70
	v_fmac_f32_e32 v29, v202, v72
	s_waitcnt lgkmcnt(13)
	v_fmac_f32_e32 v28, v202, v74
	v_fmac_f32_e32 v27, v202, v76
	s_waitcnt lgkmcnt(12)
	v_fmac_f32_e32 v26, v202, v78
	v_fmac_f32_e32 v25, v202, v80
	s_waitcnt lgkmcnt(11)
	v_fmac_f32_e32 v24, v202, v82
	v_fmac_f32_e32 v23, v202, v84
	s_waitcnt lgkmcnt(10)
	v_fmac_f32_e32 v22, v202, v86
	v_fmac_f32_e32 v21, v202, v88
	s_waitcnt lgkmcnt(9)
	v_fmac_f32_e32 v20, v202, v90
	v_fmac_f32_e32 v17, v202, v92
	s_waitcnt lgkmcnt(8)
	v_fmac_f32_e32 v16, v202, v94
	v_fmac_f32_e32 v31, v202, v96
	s_waitcnt lgkmcnt(7)
	v_fmac_f32_e32 v32, v202, v98
	v_fmac_f32_e32 v33, v202, v100
	s_waitcnt lgkmcnt(6)
	v_fmac_f32_e32 v36, v202, v102
	v_fmac_f32_e32 v37, v202, v104
	s_waitcnt lgkmcnt(5)
	v_fmac_f32_e32 v38, v202, v106
	v_fmac_f32_e32 v39, v202, v108
	s_waitcnt lgkmcnt(4)
	v_fmac_f32_e32 v40, v202, v110
	v_fmac_f32_e32 v41, v202, v112
	s_waitcnt lgkmcnt(3)
	v_fmac_f32_e32 v44, v202, v114
	v_fmac_f32_e32 v45, v202, v116
	s_waitcnt lgkmcnt(2)
	v_fmac_f32_e32 v46, v202, v118
	v_fmac_f32_e32 v47, v202, v120
	s_waitcnt lgkmcnt(1)
	v_fmac_f32_e32 v48, v202, v122
	v_fmac_f32_e32 v49, v202, v124
	s_waitcnt lgkmcnt(0)
	v_fmac_f32_e32 v60, v202, v128
	v_fmac_f32_e32 v30, v203, v63
	v_fmac_f32_e32 v43, v203, v65
	v_fmac_f32_e32 v42, v203, v67
	v_fmac_f32_e32 v35, v203, v69
	v_fmac_f32_e32 v34, v203, v71
	v_fmac_f32_e32 v29, v203, v73
	v_fmac_f32_e32 v28, v203, v75
	v_fmac_f32_e32 v27, v203, v77
	v_fmac_f32_e32 v26, v203, v79
	v_fmac_f32_e32 v25, v203, v81
	v_fmac_f32_e32 v24, v203, v83
	v_fmac_f32_e32 v23, v203, v85
	v_fmac_f32_e32 v22, v203, v87
	v_fmac_f32_e32 v21, v203, v89
	v_fmac_f32_e32 v20, v203, v91
	v_fmac_f32_e32 v17, v203, v93
	v_fmac_f32_e32 v16, v203, v95
	v_fmac_f32_e32 v31, v203, v97
	v_fmac_f32_e32 v32, v203, v99
	v_fmac_f32_e32 v33, v203, v101
	v_fmac_f32_e32 v36, v203, v103
	v_fmac_f32_e32 v37, v203, v105
	v_fmac_f32_e32 v38, v203, v107
	v_fmac_f32_e32 v39, v203, v109
	v_fmac_f32_e32 v40, v203, v111
	v_fmac_f32_e32 v41, v203, v113
	v_fmac_f32_e32 v44, v203, v115
	v_fmac_f32_e32 v45, v203, v117
	v_fmac_f32_e32 v46, v203, v119
	v_fmac_f32_e32 v47, v203, v121
	v_fmac_f32_e32 v48, v203, v123
	v_fmac_f32_e32 v49, v203, v125
	v_fmac_f32_e32 v60, v203, v129
	v_add_u32_e32 v61, 160, v57
	v_add_u32_e32 v150, 160, v149
	ds_read2st64_b64 v[62:65], v61 offset1:4
	ds_read2st64_b64 v[66:69], v61 offset0:8 offset1:12
	ds_read2st64_b64 v[70:73], v61 offset0:16 offset1:20
	ds_read2st64_b64 v[74:77], v61 offset0:24 offset1:28
	ds_read2st64_b64 v[78:81], v61 offset0:32 offset1:36
	ds_read2st64_b64 v[82:85], v61 offset0:40 offset1:44
	ds_read2st64_b64 v[86:89], v61 offset0:48 offset1:52
	ds_read2st64_b64 v[90:93], v61 offset0:56 offset1:60
	ds_read2st64_b64 v[94:97], v61 offset0:64 offset1:68
	ds_read2st64_b64 v[98:101], v61 offset0:72 offset1:76
	ds_read2st64_b64 v[102:105], v61 offset0:80 offset1:84
	ds_read2st64_b64 v[106:109], v61 offset0:88 offset1:92
	ds_read2st64_b64 v[110:113], v61 offset0:96 offset1:100
	ds_read2st64_b64 v[114:117], v61 offset0:104 offset1:108
	ds_read2st64_b64 v[118:121], v61 offset0:112 offset1:116
	ds_read2st64_b64 v[122:125], v61 offset0:120 offset1:124
	ds_read_b64 v[128:129], v150
	s_waitcnt vmcnt(22)
	s_waitcnt lgkmcnt(15)
	v_fmac_f32_e32 v30, v204, v62
	v_fmac_f32_e32 v43, v204, v64
	s_waitcnt lgkmcnt(15)
	v_fmac_f32_e32 v42, v204, v66
	v_fmac_f32_e32 v35, v204, v68
	s_waitcnt lgkmcnt(14)
	v_fmac_f32_e32 v34, v204, v70
	v_fmac_f32_e32 v29, v204, v72
	s_waitcnt lgkmcnt(13)
	v_fmac_f32_e32 v28, v204, v74
	v_fmac_f32_e32 v27, v204, v76
	s_waitcnt lgkmcnt(12)
	v_fmac_f32_e32 v26, v204, v78
	v_fmac_f32_e32 v25, v204, v80
	s_waitcnt lgkmcnt(11)
	v_fmac_f32_e32 v24, v204, v82
	v_fmac_f32_e32 v23, v204, v84
	s_waitcnt lgkmcnt(10)
	v_fmac_f32_e32 v22, v204, v86
	v_fmac_f32_e32 v21, v204, v88
	s_waitcnt lgkmcnt(9)
	v_fmac_f32_e32 v20, v204, v90
	v_fmac_f32_e32 v17, v204, v92
	s_waitcnt lgkmcnt(8)
	v_fmac_f32_e32 v16, v204, v94
	v_fmac_f32_e32 v31, v204, v96
	s_waitcnt lgkmcnt(7)
	v_fmac_f32_e32 v32, v204, v98
	v_fmac_f32_e32 v33, v204, v100
	s_waitcnt lgkmcnt(6)
	v_fmac_f32_e32 v36, v204, v102
	v_fmac_f32_e32 v37, v204, v104
	s_waitcnt lgkmcnt(5)
	v_fmac_f32_e32 v38, v204, v106
	v_fmac_f32_e32 v39, v204, v108
	s_waitcnt lgkmcnt(4)
	v_fmac_f32_e32 v40, v204, v110
	v_fmac_f32_e32 v41, v204, v112
	s_waitcnt lgkmcnt(3)
	v_fmac_f32_e32 v44, v204, v114
	v_fmac_f32_e32 v45, v204, v116
	s_waitcnt lgkmcnt(2)
	v_fmac_f32_e32 v46, v204, v118
	v_fmac_f32_e32 v47, v204, v120
	s_waitcnt lgkmcnt(1)
	v_fmac_f32_e32 v48, v204, v122
	v_fmac_f32_e32 v49, v204, v124
	s_waitcnt lgkmcnt(0)
	v_fmac_f32_e32 v60, v204, v128
	v_fmac_f32_e32 v30, v205, v63
	v_fmac_f32_e32 v43, v205, v65
	v_fmac_f32_e32 v42, v205, v67
	v_fmac_f32_e32 v35, v205, v69
	v_fmac_f32_e32 v34, v205, v71
	v_fmac_f32_e32 v29, v205, v73
	v_fmac_f32_e32 v28, v205, v75
	v_fmac_f32_e32 v27, v205, v77
	v_fmac_f32_e32 v26, v205, v79
	v_fmac_f32_e32 v25, v205, v81
	v_fmac_f32_e32 v24, v205, v83
	v_fmac_f32_e32 v23, v205, v85
	v_fmac_f32_e32 v22, v205, v87
	v_fmac_f32_e32 v21, v205, v89
	v_fmac_f32_e32 v20, v205, v91
	v_fmac_f32_e32 v17, v205, v93
	v_fmac_f32_e32 v16, v205, v95
	v_fmac_f32_e32 v31, v205, v97
	v_fmac_f32_e32 v32, v205, v99
	v_fmac_f32_e32 v33, v205, v101
	v_fmac_f32_e32 v36, v205, v103
	v_fmac_f32_e32 v37, v205, v105
	v_fmac_f32_e32 v38, v205, v107
	v_fmac_f32_e32 v39, v205, v109
	v_fmac_f32_e32 v40, v205, v111
	v_fmac_f32_e32 v41, v205, v113
	v_fmac_f32_e32 v44, v205, v115
	v_fmac_f32_e32 v45, v205, v117
	v_fmac_f32_e32 v46, v205, v119
	v_fmac_f32_e32 v47, v205, v121
	v_fmac_f32_e32 v48, v205, v123
	v_fmac_f32_e32 v49, v205, v125
	v_fmac_f32_e32 v60, v205, v129
	v_add_u32_e32 v61, 168, v57
	v_add_u32_e32 v150, 168, v149
	ds_read2st64_b64 v[62:65], v61 offset1:4
	ds_read2st64_b64 v[66:69], v61 offset0:8 offset1:12
	ds_read2st64_b64 v[70:73], v61 offset0:16 offset1:20
	ds_read2st64_b64 v[74:77], v61 offset0:24 offset1:28
	ds_read2st64_b64 v[78:81], v61 offset0:32 offset1:36
	ds_read2st64_b64 v[82:85], v61 offset0:40 offset1:44
	ds_read2st64_b64 v[86:89], v61 offset0:48 offset1:52
	ds_read2st64_b64 v[90:93], v61 offset0:56 offset1:60
	ds_read2st64_b64 v[94:97], v61 offset0:64 offset1:68
	ds_read2st64_b64 v[98:101], v61 offset0:72 offset1:76
	ds_read2st64_b64 v[102:105], v61 offset0:80 offset1:84
	ds_read2st64_b64 v[106:109], v61 offset0:88 offset1:92
	ds_read2st64_b64 v[110:113], v61 offset0:96 offset1:100
	ds_read2st64_b64 v[114:117], v61 offset0:104 offset1:108
	ds_read2st64_b64 v[118:121], v61 offset0:112 offset1:116
	ds_read2st64_b64 v[122:125], v61 offset0:120 offset1:124
	ds_read_b64 v[128:129], v150
	s_waitcnt vmcnt(20)
	s_waitcnt lgkmcnt(15)
	v_fmac_f32_e32 v30, v206, v62
	v_fmac_f32_e32 v43, v206, v64
	s_waitcnt lgkmcnt(15)
	v_fmac_f32_e32 v42, v206, v66
	v_fmac_f32_e32 v35, v206, v68
	s_waitcnt lgkmcnt(14)
	v_fmac_f32_e32 v34, v206, v70
	v_fmac_f32_e32 v29, v206, v72
	s_waitcnt lgkmcnt(13)
	v_fmac_f32_e32 v28, v206, v74
	v_fmac_f32_e32 v27, v206, v76
	s_waitcnt lgkmcnt(12)
	v_fmac_f32_e32 v26, v206, v78
	v_fmac_f32_e32 v25, v206, v80
	s_waitcnt lgkmcnt(11)
	v_fmac_f32_e32 v24, v206, v82
	v_fmac_f32_e32 v23, v206, v84
	s_waitcnt lgkmcnt(10)
	v_fmac_f32_e32 v22, v206, v86
	v_fmac_f32_e32 v21, v206, v88
	s_waitcnt lgkmcnt(9)
	v_fmac_f32_e32 v20, v206, v90
	v_fmac_f32_e32 v17, v206, v92
	s_waitcnt lgkmcnt(8)
	v_fmac_f32_e32 v16, v206, v94
	v_fmac_f32_e32 v31, v206, v96
	s_waitcnt lgkmcnt(7)
	v_fmac_f32_e32 v32, v206, v98
	v_fmac_f32_e32 v33, v206, v100
	s_waitcnt lgkmcnt(6)
	v_fmac_f32_e32 v36, v206, v102
	v_fmac_f32_e32 v37, v206, v104
	s_waitcnt lgkmcnt(5)
	v_fmac_f32_e32 v38, v206, v106
	v_fmac_f32_e32 v39, v206, v108
	s_waitcnt lgkmcnt(4)
	v_fmac_f32_e32 v40, v206, v110
	v_fmac_f32_e32 v41, v206, v112
	s_waitcnt lgkmcnt(3)
	v_fmac_f32_e32 v44, v206, v114
	v_fmac_f32_e32 v45, v206, v116
	s_waitcnt lgkmcnt(2)
	v_fmac_f32_e32 v46, v206, v118
	v_fmac_f32_e32 v47, v206, v120
	s_waitcnt lgkmcnt(1)
	v_fmac_f32_e32 v48, v206, v122
	v_fmac_f32_e32 v49, v206, v124
	s_waitcnt lgkmcnt(0)
	v_fmac_f32_e32 v60, v206, v128
	v_fmac_f32_e32 v30, v207, v63
	v_fmac_f32_e32 v43, v207, v65
	v_fmac_f32_e32 v42, v207, v67
	v_fmac_f32_e32 v35, v207, v69
	v_fmac_f32_e32 v34, v207, v71
	v_fmac_f32_e32 v29, v207, v73
	v_fmac_f32_e32 v28, v207, v75
	v_fmac_f32_e32 v27, v207, v77
	v_fmac_f32_e32 v26, v207, v79
	v_fmac_f32_e32 v25, v207, v81
	v_fmac_f32_e32 v24, v207, v83
	v_fmac_f32_e32 v23, v207, v85
	v_fmac_f32_e32 v22, v207, v87
	v_fmac_f32_e32 v21, v207, v89
	v_fmac_f32_e32 v20, v207, v91
	v_fmac_f32_e32 v17, v207, v93
	v_fmac_f32_e32 v16, v207, v95
	v_fmac_f32_e32 v31, v207, v97
	v_fmac_f32_e32 v32, v207, v99
	v_fmac_f32_e32 v33, v207, v101
	v_fmac_f32_e32 v36, v207, v103
	v_fmac_f32_e32 v37, v207, v105
	v_fmac_f32_e32 v38, v207, v107
	v_fmac_f32_e32 v39, v207, v109
	v_fmac_f32_e32 v40, v207, v111
	v_fmac_f32_e32 v41, v207, v113
	v_fmac_f32_e32 v44, v207, v115
	v_fmac_f32_e32 v45, v207, v117
	v_fmac_f32_e32 v46, v207, v119
	v_fmac_f32_e32 v47, v207, v121
	v_fmac_f32_e32 v48, v207, v123
	v_fmac_f32_e32 v49, v207, v125
	v_fmac_f32_e32 v60, v207, v129
	v_add_u32_e32 v61, 176, v57
	v_add_u32_e32 v150, 176, v149
	ds_read2st64_b64 v[62:65], v61 offset1:4
	ds_read2st64_b64 v[66:69], v61 offset0:8 offset1:12
	ds_read2st64_b64 v[70:73], v61 offset0:16 offset1:20
	ds_read2st64_b64 v[74:77], v61 offset0:24 offset1:28
	ds_read2st64_b64 v[78:81], v61 offset0:32 offset1:36
	ds_read2st64_b64 v[82:85], v61 offset0:40 offset1:44
	ds_read2st64_b64 v[86:89], v61 offset0:48 offset1:52
	ds_read2st64_b64 v[90:93], v61 offset0:56 offset1:60
	ds_read2st64_b64 v[94:97], v61 offset0:64 offset1:68
	ds_read2st64_b64 v[98:101], v61 offset0:72 offset1:76
	ds_read2st64_b64 v[102:105], v61 offset0:80 offset1:84
	ds_read2st64_b64 v[106:109], v61 offset0:88 offset1:92
	ds_read2st64_b64 v[110:113], v61 offset0:96 offset1:100
	ds_read2st64_b64 v[114:117], v61 offset0:104 offset1:108
	ds_read2st64_b64 v[118:121], v61 offset0:112 offset1:116
	ds_read2st64_b64 v[122:125], v61 offset0:120 offset1:124
	ds_read_b64 v[128:129], v150
	s_waitcnt vmcnt(18)
	s_waitcnt lgkmcnt(15)
	v_fmac_f32_e32 v30, v208, v62
	v_fmac_f32_e32 v43, v208, v64
	s_waitcnt lgkmcnt(15)
	v_fmac_f32_e32 v42, v208, v66
	v_fmac_f32_e32 v35, v208, v68
	s_waitcnt lgkmcnt(14)
	v_fmac_f32_e32 v34, v208, v70
	v_fmac_f32_e32 v29, v208, v72
	s_waitcnt lgkmcnt(13)
	v_fmac_f32_e32 v28, v208, v74
	v_fmac_f32_e32 v27, v208, v76
	s_waitcnt lgkmcnt(12)
	v_fmac_f32_e32 v26, v208, v78
	v_fmac_f32_e32 v25, v208, v80
	s_waitcnt lgkmcnt(11)
	v_fmac_f32_e32 v24, v208, v82
	v_fmac_f32_e32 v23, v208, v84
	s_waitcnt lgkmcnt(10)
	v_fmac_f32_e32 v22, v208, v86
	v_fmac_f32_e32 v21, v208, v88
	s_waitcnt lgkmcnt(9)
	v_fmac_f32_e32 v20, v208, v90
	v_fmac_f32_e32 v17, v208, v92
	s_waitcnt lgkmcnt(8)
	v_fmac_f32_e32 v16, v208, v94
	v_fmac_f32_e32 v31, v208, v96
	s_waitcnt lgkmcnt(7)
	v_fmac_f32_e32 v32, v208, v98
	v_fmac_f32_e32 v33, v208, v100
	s_waitcnt lgkmcnt(6)
	v_fmac_f32_e32 v36, v208, v102
	v_fmac_f32_e32 v37, v208, v104
	s_waitcnt lgkmcnt(5)
	v_fmac_f32_e32 v38, v208, v106
	v_fmac_f32_e32 v39, v208, v108
	s_waitcnt lgkmcnt(4)
	v_fmac_f32_e32 v40, v208, v110
	v_fmac_f32_e32 v41, v208, v112
	s_waitcnt lgkmcnt(3)
	v_fmac_f32_e32 v44, v208, v114
	v_fmac_f32_e32 v45, v208, v116
	s_waitcnt lgkmcnt(2)
	v_fmac_f32_e32 v46, v208, v118
	v_fmac_f32_e32 v47, v208, v120
	s_waitcnt lgkmcnt(1)
	v_fmac_f32_e32 v48, v208, v122
	v_fmac_f32_e32 v49, v208, v124
	s_waitcnt lgkmcnt(0)
	v_fmac_f32_e32 v60, v208, v128
	v_fmac_f32_e32 v30, v209, v63
	v_fmac_f32_e32 v43, v209, v65
	v_fmac_f32_e32 v42, v209, v67
	v_fmac_f32_e32 v35, v209, v69
	v_fmac_f32_e32 v34, v209, v71
	v_fmac_f32_e32 v29, v209, v73
	v_fmac_f32_e32 v28, v209, v75
	v_fmac_f32_e32 v27, v209, v77
	v_fmac_f32_e32 v26, v209, v79
	v_fmac_f32_e32 v25, v209, v81
	v_fmac_f32_e32 v24, v209, v83
	v_fmac_f32_e32 v23, v209, v85
	v_fmac_f32_e32 v22, v209, v87
	v_fmac_f32_e32 v21, v209, v89
	v_fmac_f32_e32 v20, v209, v91
	v_fmac_f32_e32 v17, v209, v93
	v_fmac_f32_e32 v16, v209, v95
	v_fmac_f32_e32 v31, v209, v97
	v_fmac_f32_e32 v32, v209, v99
	v_fmac_f32_e32 v33, v209, v101
	v_fmac_f32_e32 v36, v209, v103
	v_fmac_f32_e32 v37, v209, v105
	v_fmac_f32_e32 v38, v209, v107
	v_fmac_f32_e32 v39, v209, v109
	v_fmac_f32_e32 v40, v209, v111
	v_fmac_f32_e32 v41, v209, v113
	v_fmac_f32_e32 v44, v209, v115
	v_fmac_f32_e32 v45, v209, v117
	v_fmac_f32_e32 v46, v209, v119
	v_fmac_f32_e32 v47, v209, v121
	v_fmac_f32_e32 v48, v209, v123
	v_fmac_f32_e32 v49, v209, v125
	v_fmac_f32_e32 v60, v209, v129
	v_add_u32_e32 v61, 184, v57
	v_add_u32_e32 v150, 184, v149
	ds_read2st64_b64 v[62:65], v61 offset1:4
	ds_read2st64_b64 v[66:69], v61 offset0:8 offset1:12
	ds_read2st64_b64 v[70:73], v61 offset0:16 offset1:20
	ds_read2st64_b64 v[74:77], v61 offset0:24 offset1:28
	ds_read2st64_b64 v[78:81], v61 offset0:32 offset1:36
	ds_read2st64_b64 v[82:85], v61 offset0:40 offset1:44
	ds_read2st64_b64 v[86:89], v61 offset0:48 offset1:52
	ds_read2st64_b64 v[90:93], v61 offset0:56 offset1:60
	ds_read2st64_b64 v[94:97], v61 offset0:64 offset1:68
	ds_read2st64_b64 v[98:101], v61 offset0:72 offset1:76
	ds_read2st64_b64 v[102:105], v61 offset0:80 offset1:84
	ds_read2st64_b64 v[106:109], v61 offset0:88 offset1:92
	ds_read2st64_b64 v[110:113], v61 offset0:96 offset1:100
	ds_read2st64_b64 v[114:117], v61 offset0:104 offset1:108
	ds_read2st64_b64 v[118:121], v61 offset0:112 offset1:116
	ds_read2st64_b64 v[122:125], v61 offset0:120 offset1:124
	ds_read_b64 v[128:129], v150
	s_waitcnt vmcnt(16)
	s_waitcnt lgkmcnt(15)
	v_fmac_f32_e32 v30, v210, v62
	v_fmac_f32_e32 v43, v210, v64
	s_waitcnt lgkmcnt(15)
	v_fmac_f32_e32 v42, v210, v66
	v_fmac_f32_e32 v35, v210, v68
	s_waitcnt lgkmcnt(14)
	v_fmac_f32_e32 v34, v210, v70
	v_fmac_f32_e32 v29, v210, v72
	s_waitcnt lgkmcnt(13)
	v_fmac_f32_e32 v28, v210, v74
	v_fmac_f32_e32 v27, v210, v76
	s_waitcnt lgkmcnt(12)
	v_fmac_f32_e32 v26, v210, v78
	v_fmac_f32_e32 v25, v210, v80
	s_waitcnt lgkmcnt(11)
	v_fmac_f32_e32 v24, v210, v82
	v_fmac_f32_e32 v23, v210, v84
	s_waitcnt lgkmcnt(10)
	v_fmac_f32_e32 v22, v210, v86
	v_fmac_f32_e32 v21, v210, v88
	s_waitcnt lgkmcnt(9)
	v_fmac_f32_e32 v20, v210, v90
	v_fmac_f32_e32 v17, v210, v92
	s_waitcnt lgkmcnt(8)
	v_fmac_f32_e32 v16, v210, v94
	v_fmac_f32_e32 v31, v210, v96
	s_waitcnt lgkmcnt(7)
	v_fmac_f32_e32 v32, v210, v98
	v_fmac_f32_e32 v33, v210, v100
	s_waitcnt lgkmcnt(6)
	v_fmac_f32_e32 v36, v210, v102
	v_fmac_f32_e32 v37, v210, v104
	s_waitcnt lgkmcnt(5)
	v_fmac_f32_e32 v38, v210, v106
	v_fmac_f32_e32 v39, v210, v108
	s_waitcnt lgkmcnt(4)
	v_fmac_f32_e32 v40, v210, v110
	v_fmac_f32_e32 v41, v210, v112
	s_waitcnt lgkmcnt(3)
	v_fmac_f32_e32 v44, v210, v114
	v_fmac_f32_e32 v45, v210, v116
	s_waitcnt lgkmcnt(2)
	v_fmac_f32_e32 v46, v210, v118
	v_fmac_f32_e32 v47, v210, v120
	s_waitcnt lgkmcnt(1)
	v_fmac_f32_e32 v48, v210, v122
	v_fmac_f32_e32 v49, v210, v124
	s_waitcnt lgkmcnt(0)
	v_fmac_f32_e32 v60, v210, v128
	v_fmac_f32_e32 v30, v212, v63
	v_fmac_f32_e32 v43, v212, v65
	v_fmac_f32_e32 v42, v212, v67
	v_fmac_f32_e32 v35, v212, v69
	v_fmac_f32_e32 v34, v212, v71
	v_fmac_f32_e32 v29, v212, v73
	v_fmac_f32_e32 v28, v212, v75
	v_fmac_f32_e32 v27, v212, v77
	v_fmac_f32_e32 v26, v212, v79
	v_fmac_f32_e32 v25, v212, v81
	v_fmac_f32_e32 v24, v212, v83
	v_fmac_f32_e32 v23, v212, v85
	v_fmac_f32_e32 v22, v212, v87
	v_fmac_f32_e32 v21, v212, v89
	v_fmac_f32_e32 v20, v212, v91
	v_fmac_f32_e32 v17, v212, v93
	v_fmac_f32_e32 v16, v212, v95
	v_fmac_f32_e32 v31, v212, v97
	v_fmac_f32_e32 v32, v212, v99
	v_fmac_f32_e32 v33, v212, v101
	v_fmac_f32_e32 v36, v212, v103
	v_fmac_f32_e32 v37, v212, v105
	v_fmac_f32_e32 v38, v212, v107
	v_fmac_f32_e32 v39, v212, v109
	v_fmac_f32_e32 v40, v212, v111
	v_fmac_f32_e32 v41, v212, v113
	v_fmac_f32_e32 v44, v212, v115
	v_fmac_f32_e32 v45, v212, v117
	v_fmac_f32_e32 v46, v212, v119
	v_fmac_f32_e32 v47, v212, v121
	v_fmac_f32_e32 v48, v212, v123
	v_fmac_f32_e32 v49, v212, v125
	v_fmac_f32_e32 v60, v212, v129
	v_add_u32_e32 v61, 192, v57
	v_add_u32_e32 v150, 192, v149
	ds_read2st64_b64 v[62:65], v61 offset1:4
	ds_read2st64_b64 v[66:69], v61 offset0:8 offset1:12
	ds_read2st64_b64 v[70:73], v61 offset0:16 offset1:20
	ds_read2st64_b64 v[74:77], v61 offset0:24 offset1:28
	ds_read2st64_b64 v[78:81], v61 offset0:32 offset1:36
	ds_read2st64_b64 v[82:85], v61 offset0:40 offset1:44
	ds_read2st64_b64 v[86:89], v61 offset0:48 offset1:52
	ds_read2st64_b64 v[90:93], v61 offset0:56 offset1:60
	ds_read2st64_b64 v[94:97], v61 offset0:64 offset1:68
	ds_read2st64_b64 v[98:101], v61 offset0:72 offset1:76
	ds_read2st64_b64 v[102:105], v61 offset0:80 offset1:84
	ds_read2st64_b64 v[106:109], v61 offset0:88 offset1:92
	ds_read2st64_b64 v[110:113], v61 offset0:96 offset1:100
	ds_read2st64_b64 v[114:117], v61 offset0:104 offset1:108
	ds_read2st64_b64 v[118:121], v61 offset0:112 offset1:116
	ds_read2st64_b64 v[122:125], v61 offset0:120 offset1:124
	ds_read_b64 v[128:129], v150
	s_waitcnt vmcnt(14)
	s_waitcnt lgkmcnt(15)
	v_fmac_f32_e32 v30, v213, v62
	v_fmac_f32_e32 v43, v213, v64
	s_waitcnt lgkmcnt(15)
	v_fmac_f32_e32 v42, v213, v66
	v_fmac_f32_e32 v35, v213, v68
	s_waitcnt lgkmcnt(14)
	v_fmac_f32_e32 v34, v213, v70
	v_fmac_f32_e32 v29, v213, v72
	s_waitcnt lgkmcnt(13)
	v_fmac_f32_e32 v28, v213, v74
	v_fmac_f32_e32 v27, v213, v76
	s_waitcnt lgkmcnt(12)
	v_fmac_f32_e32 v26, v213, v78
	v_fmac_f32_e32 v25, v213, v80
	s_waitcnt lgkmcnt(11)
	v_fmac_f32_e32 v24, v213, v82
	v_fmac_f32_e32 v23, v213, v84
	s_waitcnt lgkmcnt(10)
	v_fmac_f32_e32 v22, v213, v86
	v_fmac_f32_e32 v21, v213, v88
	s_waitcnt lgkmcnt(9)
	v_fmac_f32_e32 v20, v213, v90
	v_fmac_f32_e32 v17, v213, v92
	s_waitcnt lgkmcnt(8)
	v_fmac_f32_e32 v16, v213, v94
	v_fmac_f32_e32 v31, v213, v96
	s_waitcnt lgkmcnt(7)
	v_fmac_f32_e32 v32, v213, v98
	v_fmac_f32_e32 v33, v213, v100
	s_waitcnt lgkmcnt(6)
	v_fmac_f32_e32 v36, v213, v102
	v_fmac_f32_e32 v37, v213, v104
	s_waitcnt lgkmcnt(5)
	v_fmac_f32_e32 v38, v213, v106
	v_fmac_f32_e32 v39, v213, v108
	s_waitcnt lgkmcnt(4)
	v_fmac_f32_e32 v40, v213, v110
	v_fmac_f32_e32 v41, v213, v112
	s_waitcnt lgkmcnt(3)
	v_fmac_f32_e32 v44, v213, v114
	v_fmac_f32_e32 v45, v213, v116
	s_waitcnt lgkmcnt(2)
	v_fmac_f32_e32 v46, v213, v118
	v_fmac_f32_e32 v47, v213, v120
	s_waitcnt lgkmcnt(1)
	v_fmac_f32_e32 v48, v213, v122
	v_fmac_f32_e32 v49, v213, v124
	s_waitcnt lgkmcnt(0)
	v_fmac_f32_e32 v60, v213, v128
	v_fmac_f32_e32 v30, v214, v63
	v_fmac_f32_e32 v43, v214, v65
	v_fmac_f32_e32 v42, v214, v67
	v_fmac_f32_e32 v35, v214, v69
	v_fmac_f32_e32 v34, v214, v71
	v_fmac_f32_e32 v29, v214, v73
	v_fmac_f32_e32 v28, v214, v75
	v_fmac_f32_e32 v27, v214, v77
	v_fmac_f32_e32 v26, v214, v79
	v_fmac_f32_e32 v25, v214, v81
	v_fmac_f32_e32 v24, v214, v83
	v_fmac_f32_e32 v23, v214, v85
	v_fmac_f32_e32 v22, v214, v87
	v_fmac_f32_e32 v21, v214, v89
	v_fmac_f32_e32 v20, v214, v91
	v_fmac_f32_e32 v17, v214, v93
	v_fmac_f32_e32 v16, v214, v95
	v_fmac_f32_e32 v31, v214, v97
	v_fmac_f32_e32 v32, v214, v99
	v_fmac_f32_e32 v33, v214, v101
	v_fmac_f32_e32 v36, v214, v103
	v_fmac_f32_e32 v37, v214, v105
	v_fmac_f32_e32 v38, v214, v107
	v_fmac_f32_e32 v39, v214, v109
	v_fmac_f32_e32 v40, v214, v111
	v_fmac_f32_e32 v41, v214, v113
	v_fmac_f32_e32 v44, v214, v115
	v_fmac_f32_e32 v45, v214, v117
	v_fmac_f32_e32 v46, v214, v119
	v_fmac_f32_e32 v47, v214, v121
	v_fmac_f32_e32 v48, v214, v123
	v_fmac_f32_e32 v49, v214, v125
	v_fmac_f32_e32 v60, v214, v129
	v_add_u32_e32 v61, 200, v57
	v_add_u32_e32 v150, 200, v149
	ds_read2st64_b64 v[62:65], v61 offset1:4
	ds_read2st64_b64 v[66:69], v61 offset0:8 offset1:12
	ds_read2st64_b64 v[70:73], v61 offset0:16 offset1:20
	ds_read2st64_b64 v[74:77], v61 offset0:24 offset1:28
	ds_read2st64_b64 v[78:81], v61 offset0:32 offset1:36
	ds_read2st64_b64 v[82:85], v61 offset0:40 offset1:44
	ds_read2st64_b64 v[86:89], v61 offset0:48 offset1:52
	ds_read2st64_b64 v[90:93], v61 offset0:56 offset1:60
	ds_read2st64_b64 v[94:97], v61 offset0:64 offset1:68
	ds_read2st64_b64 v[98:101], v61 offset0:72 offset1:76
	ds_read2st64_b64 v[102:105], v61 offset0:80 offset1:84
	ds_read2st64_b64 v[106:109], v61 offset0:88 offset1:92
	ds_read2st64_b64 v[110:113], v61 offset0:96 offset1:100
	ds_read2st64_b64 v[114:117], v61 offset0:104 offset1:108
	ds_read2st64_b64 v[118:121], v61 offset0:112 offset1:116
	ds_read2st64_b64 v[122:125], v61 offset0:120 offset1:124
	ds_read_b64 v[128:129], v150
	s_waitcnt vmcnt(12)
	s_waitcnt lgkmcnt(15)
	v_fmac_f32_e32 v30, v215, v62
	v_fmac_f32_e32 v43, v215, v64
	s_waitcnt lgkmcnt(15)
	v_fmac_f32_e32 v42, v215, v66
	v_fmac_f32_e32 v35, v215, v68
	s_waitcnt lgkmcnt(14)
	v_fmac_f32_e32 v34, v215, v70
	v_fmac_f32_e32 v29, v215, v72
	s_waitcnt lgkmcnt(13)
	v_fmac_f32_e32 v28, v215, v74
	v_fmac_f32_e32 v27, v215, v76
	s_waitcnt lgkmcnt(12)
	v_fmac_f32_e32 v26, v215, v78
	v_fmac_f32_e32 v25, v215, v80
	s_waitcnt lgkmcnt(11)
	v_fmac_f32_e32 v24, v215, v82
	v_fmac_f32_e32 v23, v215, v84
	s_waitcnt lgkmcnt(10)
	v_fmac_f32_e32 v22, v215, v86
	v_fmac_f32_e32 v21, v215, v88
	s_waitcnt lgkmcnt(9)
	v_fmac_f32_e32 v20, v215, v90
	v_fmac_f32_e32 v17, v215, v92
	s_waitcnt lgkmcnt(8)
	v_fmac_f32_e32 v16, v215, v94
	v_fmac_f32_e32 v31, v215, v96
	s_waitcnt lgkmcnt(7)
	v_fmac_f32_e32 v32, v215, v98
	v_fmac_f32_e32 v33, v215, v100
	s_waitcnt lgkmcnt(6)
	v_fmac_f32_e32 v36, v215, v102
	v_fmac_f32_e32 v37, v215, v104
	s_waitcnt lgkmcnt(5)
	v_fmac_f32_e32 v38, v215, v106
	v_fmac_f32_e32 v39, v215, v108
	s_waitcnt lgkmcnt(4)
	v_fmac_f32_e32 v40, v215, v110
	v_fmac_f32_e32 v41, v215, v112
	s_waitcnt lgkmcnt(3)
	v_fmac_f32_e32 v44, v215, v114
	v_fmac_f32_e32 v45, v215, v116
	s_waitcnt lgkmcnt(2)
	v_fmac_f32_e32 v46, v215, v118
	v_fmac_f32_e32 v47, v215, v120
	s_waitcnt lgkmcnt(1)
	v_fmac_f32_e32 v48, v215, v122
	v_fmac_f32_e32 v49, v215, v124
	s_waitcnt lgkmcnt(0)
	v_fmac_f32_e32 v60, v215, v128
	v_fmac_f32_e32 v30, v216, v63
	v_fmac_f32_e32 v43, v216, v65
	v_fmac_f32_e32 v42, v216, v67
	v_fmac_f32_e32 v35, v216, v69
	v_fmac_f32_e32 v34, v216, v71
	v_fmac_f32_e32 v29, v216, v73
	v_fmac_f32_e32 v28, v216, v75
	v_fmac_f32_e32 v27, v216, v77
	v_fmac_f32_e32 v26, v216, v79
	v_fmac_f32_e32 v25, v216, v81
	v_fmac_f32_e32 v24, v216, v83
	v_fmac_f32_e32 v23, v216, v85
	v_fmac_f32_e32 v22, v216, v87
	v_fmac_f32_e32 v21, v216, v89
	v_fmac_f32_e32 v20, v216, v91
	v_fmac_f32_e32 v17, v216, v93
	v_fmac_f32_e32 v16, v216, v95
	v_fmac_f32_e32 v31, v216, v97
	v_fmac_f32_e32 v32, v216, v99
	v_fmac_f32_e32 v33, v216, v101
	v_fmac_f32_e32 v36, v216, v103
	v_fmac_f32_e32 v37, v216, v105
	v_fmac_f32_e32 v38, v216, v107
	v_fmac_f32_e32 v39, v216, v109
	v_fmac_f32_e32 v40, v216, v111
	v_fmac_f32_e32 v41, v216, v113
	v_fmac_f32_e32 v44, v216, v115
	v_fmac_f32_e32 v45, v216, v117
	v_fmac_f32_e32 v46, v216, v119
	v_fmac_f32_e32 v47, v216, v121
	v_fmac_f32_e32 v48, v216, v123
	v_fmac_f32_e32 v49, v216, v125
	v_fmac_f32_e32 v60, v216, v129
	v_add_u32_e32 v61, 208, v57
	v_add_u32_e32 v150, 208, v149
	ds_read2st64_b64 v[62:65], v61 offset1:4
	ds_read2st64_b64 v[66:69], v61 offset0:8 offset1:12
	ds_read2st64_b64 v[70:73], v61 offset0:16 offset1:20
	ds_read2st64_b64 v[74:77], v61 offset0:24 offset1:28
	ds_read2st64_b64 v[78:81], v61 offset0:32 offset1:36
	ds_read2st64_b64 v[82:85], v61 offset0:40 offset1:44
	ds_read2st64_b64 v[86:89], v61 offset0:48 offset1:52
	ds_read2st64_b64 v[90:93], v61 offset0:56 offset1:60
	ds_read2st64_b64 v[94:97], v61 offset0:64 offset1:68
	ds_read2st64_b64 v[98:101], v61 offset0:72 offset1:76
	ds_read2st64_b64 v[102:105], v61 offset0:80 offset1:84
	ds_read2st64_b64 v[106:109], v61 offset0:88 offset1:92
	ds_read2st64_b64 v[110:113], v61 offset0:96 offset1:100
	ds_read2st64_b64 v[114:117], v61 offset0:104 offset1:108
	ds_read2st64_b64 v[118:121], v61 offset0:112 offset1:116
	ds_read2st64_b64 v[122:125], v61 offset0:120 offset1:124
	ds_read_b64 v[128:129], v150
	s_waitcnt vmcnt(10)
	s_waitcnt lgkmcnt(15)
	v_fmac_f32_e32 v30, v217, v62
	v_fmac_f32_e32 v43, v217, v64
	s_waitcnt lgkmcnt(15)
	v_fmac_f32_e32 v42, v217, v66
	v_fmac_f32_e32 v35, v217, v68
	s_waitcnt lgkmcnt(14)
	v_fmac_f32_e32 v34, v217, v70
	v_fmac_f32_e32 v29, v217, v72
	s_waitcnt lgkmcnt(13)
	v_fmac_f32_e32 v28, v217, v74
	v_fmac_f32_e32 v27, v217, v76
	s_waitcnt lgkmcnt(12)
	v_fmac_f32_e32 v26, v217, v78
	v_fmac_f32_e32 v25, v217, v80
	s_waitcnt lgkmcnt(11)
	v_fmac_f32_e32 v24, v217, v82
	v_fmac_f32_e32 v23, v217, v84
	s_waitcnt lgkmcnt(10)
	v_fmac_f32_e32 v22, v217, v86
	v_fmac_f32_e32 v21, v217, v88
	s_waitcnt lgkmcnt(9)
	v_fmac_f32_e32 v20, v217, v90
	v_fmac_f32_e32 v17, v217, v92
	s_waitcnt lgkmcnt(8)
	v_fmac_f32_e32 v16, v217, v94
	v_fmac_f32_e32 v31, v217, v96
	s_waitcnt lgkmcnt(7)
	v_fmac_f32_e32 v32, v217, v98
	v_fmac_f32_e32 v33, v217, v100
	s_waitcnt lgkmcnt(6)
	v_fmac_f32_e32 v36, v217, v102
	v_fmac_f32_e32 v37, v217, v104
	s_waitcnt lgkmcnt(5)
	v_fmac_f32_e32 v38, v217, v106
	v_fmac_f32_e32 v39, v217, v108
	s_waitcnt lgkmcnt(4)
	v_fmac_f32_e32 v40, v217, v110
	v_fmac_f32_e32 v41, v217, v112
	s_waitcnt lgkmcnt(3)
	v_fmac_f32_e32 v44, v217, v114
	v_fmac_f32_e32 v45, v217, v116
	s_waitcnt lgkmcnt(2)
	v_fmac_f32_e32 v46, v217, v118
	v_fmac_f32_e32 v47, v217, v120
	s_waitcnt lgkmcnt(1)
	v_fmac_f32_e32 v48, v217, v122
	v_fmac_f32_e32 v49, v217, v124
	s_waitcnt lgkmcnt(0)
	v_fmac_f32_e32 v60, v217, v128
	v_fmac_f32_e32 v30, v218, v63
	v_fmac_f32_e32 v43, v218, v65
	v_fmac_f32_e32 v42, v218, v67
	v_fmac_f32_e32 v35, v218, v69
	v_fmac_f32_e32 v34, v218, v71
	v_fmac_f32_e32 v29, v218, v73
	v_fmac_f32_e32 v28, v218, v75
	v_fmac_f32_e32 v27, v218, v77
	v_fmac_f32_e32 v26, v218, v79
	v_fmac_f32_e32 v25, v218, v81
	v_fmac_f32_e32 v24, v218, v83
	v_fmac_f32_e32 v23, v218, v85
	v_fmac_f32_e32 v22, v218, v87
	v_fmac_f32_e32 v21, v218, v89
	v_fmac_f32_e32 v20, v218, v91
	v_fmac_f32_e32 v17, v218, v93
	v_fmac_f32_e32 v16, v218, v95
	v_fmac_f32_e32 v31, v218, v97
	v_fmac_f32_e32 v32, v218, v99
	v_fmac_f32_e32 v33, v218, v101
	v_fmac_f32_e32 v36, v218, v103
	v_fmac_f32_e32 v37, v218, v105
	v_fmac_f32_e32 v38, v218, v107
	v_fmac_f32_e32 v39, v218, v109
	v_fmac_f32_e32 v40, v218, v111
	v_fmac_f32_e32 v41, v218, v113
	v_fmac_f32_e32 v44, v218, v115
	v_fmac_f32_e32 v45, v218, v117
	v_fmac_f32_e32 v46, v218, v119
	v_fmac_f32_e32 v47, v218, v121
	v_fmac_f32_e32 v48, v218, v123
	v_fmac_f32_e32 v49, v218, v125
	v_fmac_f32_e32 v60, v218, v129
	v_add_u32_e32 v61, 216, v57
	v_add_u32_e32 v150, 216, v149
	ds_read2st64_b64 v[62:65], v61 offset1:4
	ds_read2st64_b64 v[66:69], v61 offset0:8 offset1:12
	ds_read2st64_b64 v[70:73], v61 offset0:16 offset1:20
	ds_read2st64_b64 v[74:77], v61 offset0:24 offset1:28
	ds_read2st64_b64 v[78:81], v61 offset0:32 offset1:36
	ds_read2st64_b64 v[82:85], v61 offset0:40 offset1:44
	ds_read2st64_b64 v[86:89], v61 offset0:48 offset1:52
	ds_read2st64_b64 v[90:93], v61 offset0:56 offset1:60
	ds_read2st64_b64 v[94:97], v61 offset0:64 offset1:68
	ds_read2st64_b64 v[98:101], v61 offset0:72 offset1:76
	ds_read2st64_b64 v[102:105], v61 offset0:80 offset1:84
	ds_read2st64_b64 v[106:109], v61 offset0:88 offset1:92
	ds_read2st64_b64 v[110:113], v61 offset0:96 offset1:100
	ds_read2st64_b64 v[114:117], v61 offset0:104 offset1:108
	ds_read2st64_b64 v[118:121], v61 offset0:112 offset1:116
	ds_read2st64_b64 v[122:125], v61 offset0:120 offset1:124
	ds_read_b64 v[128:129], v150
	s_waitcnt vmcnt(8)
	s_waitcnt lgkmcnt(15)
	v_fmac_f32_e32 v30, v219, v62
	v_fmac_f32_e32 v43, v219, v64
	s_waitcnt lgkmcnt(15)
	v_fmac_f32_e32 v42, v219, v66
	v_fmac_f32_e32 v35, v219, v68
	s_waitcnt lgkmcnt(14)
	v_fmac_f32_e32 v34, v219, v70
	v_fmac_f32_e32 v29, v219, v72
	s_waitcnt lgkmcnt(13)
	v_fmac_f32_e32 v28, v219, v74
	v_fmac_f32_e32 v27, v219, v76
	s_waitcnt lgkmcnt(12)
	v_fmac_f32_e32 v26, v219, v78
	v_fmac_f32_e32 v25, v219, v80
	s_waitcnt lgkmcnt(11)
	v_fmac_f32_e32 v24, v219, v82
	v_fmac_f32_e32 v23, v219, v84
	s_waitcnt lgkmcnt(10)
	v_fmac_f32_e32 v22, v219, v86
	v_fmac_f32_e32 v21, v219, v88
	s_waitcnt lgkmcnt(9)
	v_fmac_f32_e32 v20, v219, v90
	v_fmac_f32_e32 v17, v219, v92
	s_waitcnt lgkmcnt(8)
	v_fmac_f32_e32 v16, v219, v94
	v_fmac_f32_e32 v31, v219, v96
	s_waitcnt lgkmcnt(7)
	v_fmac_f32_e32 v32, v219, v98
	v_fmac_f32_e32 v33, v219, v100
	s_waitcnt lgkmcnt(6)
	v_fmac_f32_e32 v36, v219, v102
	v_fmac_f32_e32 v37, v219, v104
	s_waitcnt lgkmcnt(5)
	v_fmac_f32_e32 v38, v219, v106
	v_fmac_f32_e32 v39, v219, v108
	s_waitcnt lgkmcnt(4)
	v_fmac_f32_e32 v40, v219, v110
	v_fmac_f32_e32 v41, v219, v112
	s_waitcnt lgkmcnt(3)
	v_fmac_f32_e32 v44, v219, v114
	v_fmac_f32_e32 v45, v219, v116
	s_waitcnt lgkmcnt(2)
	v_fmac_f32_e32 v46, v219, v118
	v_fmac_f32_e32 v47, v219, v120
	s_waitcnt lgkmcnt(1)
	v_fmac_f32_e32 v48, v219, v122
	v_fmac_f32_e32 v49, v219, v124
	s_waitcnt lgkmcnt(0)
	v_fmac_f32_e32 v60, v219, v128
	v_fmac_f32_e32 v30, v220, v63
	v_fmac_f32_e32 v43, v220, v65
	v_fmac_f32_e32 v42, v220, v67
	v_fmac_f32_e32 v35, v220, v69
	v_fmac_f32_e32 v34, v220, v71
	v_fmac_f32_e32 v29, v220, v73
	v_fmac_f32_e32 v28, v220, v75
	v_fmac_f32_e32 v27, v220, v77
	v_fmac_f32_e32 v26, v220, v79
	v_fmac_f32_e32 v25, v220, v81
	v_fmac_f32_e32 v24, v220, v83
	v_fmac_f32_e32 v23, v220, v85
	v_fmac_f32_e32 v22, v220, v87
	v_fmac_f32_e32 v21, v220, v89
	v_fmac_f32_e32 v20, v220, v91
	v_fmac_f32_e32 v17, v220, v93
	v_fmac_f32_e32 v16, v220, v95
	v_fmac_f32_e32 v31, v220, v97
	v_fmac_f32_e32 v32, v220, v99
	v_fmac_f32_e32 v33, v220, v101
	v_fmac_f32_e32 v36, v220, v103
	v_fmac_f32_e32 v37, v220, v105
	v_fmac_f32_e32 v38, v220, v107
	v_fmac_f32_e32 v39, v220, v109
	v_fmac_f32_e32 v40, v220, v111
	v_fmac_f32_e32 v41, v220, v113
	v_fmac_f32_e32 v44, v220, v115
	v_fmac_f32_e32 v45, v220, v117
	v_fmac_f32_e32 v46, v220, v119
	v_fmac_f32_e32 v47, v220, v121
	v_fmac_f32_e32 v48, v220, v123
	v_fmac_f32_e32 v49, v220, v125
	v_fmac_f32_e32 v60, v220, v129
	v_add_u32_e32 v61, 224, v57
	v_add_u32_e32 v150, 224, v149
	ds_read2st64_b64 v[62:65], v61 offset1:4
	ds_read2st64_b64 v[66:69], v61 offset0:8 offset1:12
	ds_read2st64_b64 v[70:73], v61 offset0:16 offset1:20
	ds_read2st64_b64 v[74:77], v61 offset0:24 offset1:28
	ds_read2st64_b64 v[78:81], v61 offset0:32 offset1:36
	ds_read2st64_b64 v[82:85], v61 offset0:40 offset1:44
	ds_read2st64_b64 v[86:89], v61 offset0:48 offset1:52
	ds_read2st64_b64 v[90:93], v61 offset0:56 offset1:60
	ds_read2st64_b64 v[94:97], v61 offset0:64 offset1:68
	ds_read2st64_b64 v[98:101], v61 offset0:72 offset1:76
	ds_read2st64_b64 v[102:105], v61 offset0:80 offset1:84
	ds_read2st64_b64 v[106:109], v61 offset0:88 offset1:92
	ds_read2st64_b64 v[110:113], v61 offset0:96 offset1:100
	ds_read2st64_b64 v[114:117], v61 offset0:104 offset1:108
	ds_read2st64_b64 v[118:121], v61 offset0:112 offset1:116
	ds_read2st64_b64 v[122:125], v61 offset0:120 offset1:124
	ds_read_b64 v[128:129], v150
	s_waitcnt vmcnt(6)
	s_waitcnt lgkmcnt(15)
	v_fmac_f32_e32 v30, v221, v62
	v_fmac_f32_e32 v43, v221, v64
	s_waitcnt lgkmcnt(15)
	v_fmac_f32_e32 v42, v221, v66
	v_fmac_f32_e32 v35, v221, v68
	s_waitcnt lgkmcnt(14)
	v_fmac_f32_e32 v34, v221, v70
	v_fmac_f32_e32 v29, v221, v72
	s_waitcnt lgkmcnt(13)
	v_fmac_f32_e32 v28, v221, v74
	v_fmac_f32_e32 v27, v221, v76
	s_waitcnt lgkmcnt(12)
	v_fmac_f32_e32 v26, v221, v78
	v_fmac_f32_e32 v25, v221, v80
	s_waitcnt lgkmcnt(11)
	v_fmac_f32_e32 v24, v221, v82
	v_fmac_f32_e32 v23, v221, v84
	s_waitcnt lgkmcnt(10)
	v_fmac_f32_e32 v22, v221, v86
	v_fmac_f32_e32 v21, v221, v88
	s_waitcnt lgkmcnt(9)
	v_fmac_f32_e32 v20, v221, v90
	v_fmac_f32_e32 v17, v221, v92
	s_waitcnt lgkmcnt(8)
	v_fmac_f32_e32 v16, v221, v94
	v_fmac_f32_e32 v31, v221, v96
	s_waitcnt lgkmcnt(7)
	v_fmac_f32_e32 v32, v221, v98
	v_fmac_f32_e32 v33, v221, v100
	s_waitcnt lgkmcnt(6)
	v_fmac_f32_e32 v36, v221, v102
	v_fmac_f32_e32 v37, v221, v104
	s_waitcnt lgkmcnt(5)
	v_fmac_f32_e32 v38, v221, v106
	v_fmac_f32_e32 v39, v221, v108
	s_waitcnt lgkmcnt(4)
	v_fmac_f32_e32 v40, v221, v110
	v_fmac_f32_e32 v41, v221, v112
	s_waitcnt lgkmcnt(3)
	v_fmac_f32_e32 v44, v221, v114
	v_fmac_f32_e32 v45, v221, v116
	s_waitcnt lgkmcnt(2)
	v_fmac_f32_e32 v46, v221, v118
	v_fmac_f32_e32 v47, v221, v120
	s_waitcnt lgkmcnt(1)
	v_fmac_f32_e32 v48, v221, v122
	v_fmac_f32_e32 v49, v221, v124
	s_waitcnt lgkmcnt(0)
	v_fmac_f32_e32 v60, v221, v128
	v_fmac_f32_e32 v30, v222, v63
	v_fmac_f32_e32 v43, v222, v65
	v_fmac_f32_e32 v42, v222, v67
	v_fmac_f32_e32 v35, v222, v69
	v_fmac_f32_e32 v34, v222, v71
	v_fmac_f32_e32 v29, v222, v73
	v_fmac_f32_e32 v28, v222, v75
	v_fmac_f32_e32 v27, v222, v77
	v_fmac_f32_e32 v26, v222, v79
	v_fmac_f32_e32 v25, v222, v81
	v_fmac_f32_e32 v24, v222, v83
	v_fmac_f32_e32 v23, v222, v85
	v_fmac_f32_e32 v22, v222, v87
	v_fmac_f32_e32 v21, v222, v89
	v_fmac_f32_e32 v20, v222, v91
	v_fmac_f32_e32 v17, v222, v93
	v_fmac_f32_e32 v16, v222, v95
	v_fmac_f32_e32 v31, v222, v97
	v_fmac_f32_e32 v32, v222, v99
	v_fmac_f32_e32 v33, v222, v101
	v_fmac_f32_e32 v36, v222, v103
	v_fmac_f32_e32 v37, v222, v105
	v_fmac_f32_e32 v38, v222, v107
	v_fmac_f32_e32 v39, v222, v109
	v_fmac_f32_e32 v40, v222, v111
	v_fmac_f32_e32 v41, v222, v113
	v_fmac_f32_e32 v44, v222, v115
	v_fmac_f32_e32 v45, v222, v117
	v_fmac_f32_e32 v46, v222, v119
	v_fmac_f32_e32 v47, v222, v121
	v_fmac_f32_e32 v48, v222, v123
	v_fmac_f32_e32 v49, v222, v125
	v_fmac_f32_e32 v60, v222, v129
	v_add_u32_e32 v61, 232, v57
	v_add_u32_e32 v150, 232, v149
	ds_read2st64_b64 v[62:65], v61 offset1:4
	ds_read2st64_b64 v[66:69], v61 offset0:8 offset1:12
	ds_read2st64_b64 v[70:73], v61 offset0:16 offset1:20
	ds_read2st64_b64 v[74:77], v61 offset0:24 offset1:28
	ds_read2st64_b64 v[78:81], v61 offset0:32 offset1:36
	ds_read2st64_b64 v[82:85], v61 offset0:40 offset1:44
	ds_read2st64_b64 v[86:89], v61 offset0:48 offset1:52
	ds_read2st64_b64 v[90:93], v61 offset0:56 offset1:60
	ds_read2st64_b64 v[94:97], v61 offset0:64 offset1:68
	ds_read2st64_b64 v[98:101], v61 offset0:72 offset1:76
	ds_read2st64_b64 v[102:105], v61 offset0:80 offset1:84
	ds_read2st64_b64 v[106:109], v61 offset0:88 offset1:92
	ds_read2st64_b64 v[110:113], v61 offset0:96 offset1:100
	ds_read2st64_b64 v[114:117], v61 offset0:104 offset1:108
	ds_read2st64_b64 v[118:121], v61 offset0:112 offset1:116
	ds_read2st64_b64 v[122:125], v61 offset0:120 offset1:124
	ds_read_b64 v[128:129], v150
	s_waitcnt vmcnt(4)
	s_waitcnt lgkmcnt(15)
	v_fmac_f32_e32 v30, v223, v62
	v_fmac_f32_e32 v43, v223, v64
	s_waitcnt lgkmcnt(15)
	v_fmac_f32_e32 v42, v223, v66
	v_fmac_f32_e32 v35, v223, v68
	s_waitcnt lgkmcnt(14)
	v_fmac_f32_e32 v34, v223, v70
	v_fmac_f32_e32 v29, v223, v72
	s_waitcnt lgkmcnt(13)
	v_fmac_f32_e32 v28, v223, v74
	v_fmac_f32_e32 v27, v223, v76
	s_waitcnt lgkmcnt(12)
	v_fmac_f32_e32 v26, v223, v78
	v_fmac_f32_e32 v25, v223, v80
	s_waitcnt lgkmcnt(11)
	v_fmac_f32_e32 v24, v223, v82
	v_fmac_f32_e32 v23, v223, v84
	s_waitcnt lgkmcnt(10)
	v_fmac_f32_e32 v22, v223, v86
	v_fmac_f32_e32 v21, v223, v88
	s_waitcnt lgkmcnt(9)
	v_fmac_f32_e32 v20, v223, v90
	v_fmac_f32_e32 v17, v223, v92
	s_waitcnt lgkmcnt(8)
	v_fmac_f32_e32 v16, v223, v94
	v_fmac_f32_e32 v31, v223, v96
	s_waitcnt lgkmcnt(7)
	v_fmac_f32_e32 v32, v223, v98
	v_fmac_f32_e32 v33, v223, v100
	s_waitcnt lgkmcnt(6)
	v_fmac_f32_e32 v36, v223, v102
	v_fmac_f32_e32 v37, v223, v104
	s_waitcnt lgkmcnt(5)
	v_fmac_f32_e32 v38, v223, v106
	v_fmac_f32_e32 v39, v223, v108
	s_waitcnt lgkmcnt(4)
	v_fmac_f32_e32 v40, v223, v110
	v_fmac_f32_e32 v41, v223, v112
	s_waitcnt lgkmcnt(3)
	v_fmac_f32_e32 v44, v223, v114
	v_fmac_f32_e32 v45, v223, v116
	s_waitcnt lgkmcnt(2)
	v_fmac_f32_e32 v46, v223, v118
	v_fmac_f32_e32 v47, v223, v120
	s_waitcnt lgkmcnt(1)
	v_fmac_f32_e32 v48, v223, v122
	v_fmac_f32_e32 v49, v223, v124
	s_waitcnt lgkmcnt(0)
	v_fmac_f32_e32 v60, v223, v128
	v_fmac_f32_e32 v30, v224, v63
	v_fmac_f32_e32 v43, v224, v65
	v_fmac_f32_e32 v42, v224, v67
	v_fmac_f32_e32 v35, v224, v69
	v_fmac_f32_e32 v34, v224, v71
	v_fmac_f32_e32 v29, v224, v73
	v_fmac_f32_e32 v28, v224, v75
	v_fmac_f32_e32 v27, v224, v77
	v_fmac_f32_e32 v26, v224, v79
	v_fmac_f32_e32 v25, v224, v81
	v_fmac_f32_e32 v24, v224, v83
	v_fmac_f32_e32 v23, v224, v85
	v_fmac_f32_e32 v22, v224, v87
	v_fmac_f32_e32 v21, v224, v89
	v_fmac_f32_e32 v20, v224, v91
	v_fmac_f32_e32 v17, v224, v93
	v_fmac_f32_e32 v16, v224, v95
	v_fmac_f32_e32 v31, v224, v97
	v_fmac_f32_e32 v32, v224, v99
	v_fmac_f32_e32 v33, v224, v101
	v_fmac_f32_e32 v36, v224, v103
	v_fmac_f32_e32 v37, v224, v105
	v_fmac_f32_e32 v38, v224, v107
	v_fmac_f32_e32 v39, v224, v109
	v_fmac_f32_e32 v40, v224, v111
	v_fmac_f32_e32 v41, v224, v113
	v_fmac_f32_e32 v44, v224, v115
	v_fmac_f32_e32 v45, v224, v117
	v_fmac_f32_e32 v46, v224, v119
	v_fmac_f32_e32 v47, v224, v121
	v_fmac_f32_e32 v48, v224, v123
	v_fmac_f32_e32 v49, v224, v125
	v_fmac_f32_e32 v60, v224, v129
	v_add_u32_e32 v61, 240, v57
	v_add_u32_e32 v150, 240, v149
	ds_read2st64_b64 v[62:65], v61 offset1:4
	ds_read2st64_b64 v[66:69], v61 offset0:8 offset1:12
	ds_read2st64_b64 v[70:73], v61 offset0:16 offset1:20
	ds_read2st64_b64 v[74:77], v61 offset0:24 offset1:28
	ds_read2st64_b64 v[78:81], v61 offset0:32 offset1:36
	ds_read2st64_b64 v[82:85], v61 offset0:40 offset1:44
	ds_read2st64_b64 v[86:89], v61 offset0:48 offset1:52
	ds_read2st64_b64 v[90:93], v61 offset0:56 offset1:60
	ds_read2st64_b64 v[94:97], v61 offset0:64 offset1:68
	ds_read2st64_b64 v[98:101], v61 offset0:72 offset1:76
	ds_read2st64_b64 v[102:105], v61 offset0:80 offset1:84
	ds_read2st64_b64 v[106:109], v61 offset0:88 offset1:92
	ds_read2st64_b64 v[110:113], v61 offset0:96 offset1:100
	ds_read2st64_b64 v[114:117], v61 offset0:104 offset1:108
	ds_read2st64_b64 v[118:121], v61 offset0:112 offset1:116
	ds_read2st64_b64 v[122:125], v61 offset0:120 offset1:124
	ds_read_b64 v[128:129], v150
	s_waitcnt vmcnt(2)
	s_waitcnt lgkmcnt(15)
	v_fmac_f32_e32 v30, v225, v62
	v_fmac_f32_e32 v43, v225, v64
	s_waitcnt lgkmcnt(15)
	v_fmac_f32_e32 v42, v225, v66
	v_fmac_f32_e32 v35, v225, v68
	s_waitcnt lgkmcnt(14)
	v_fmac_f32_e32 v34, v225, v70
	v_fmac_f32_e32 v29, v225, v72
	s_waitcnt lgkmcnt(13)
	v_fmac_f32_e32 v28, v225, v74
	v_fmac_f32_e32 v27, v225, v76
	s_waitcnt lgkmcnt(12)
	v_fmac_f32_e32 v26, v225, v78
	v_fmac_f32_e32 v25, v225, v80
	s_waitcnt lgkmcnt(11)
	v_fmac_f32_e32 v24, v225, v82
	v_fmac_f32_e32 v23, v225, v84
	s_waitcnt lgkmcnt(10)
	v_fmac_f32_e32 v22, v225, v86
	v_fmac_f32_e32 v21, v225, v88
	s_waitcnt lgkmcnt(9)
	v_fmac_f32_e32 v20, v225, v90
	v_fmac_f32_e32 v17, v225, v92
	s_waitcnt lgkmcnt(8)
	v_fmac_f32_e32 v16, v225, v94
	v_fmac_f32_e32 v31, v225, v96
	s_waitcnt lgkmcnt(7)
	v_fmac_f32_e32 v32, v225, v98
	v_fmac_f32_e32 v33, v225, v100
	s_waitcnt lgkmcnt(6)
	v_fmac_f32_e32 v36, v225, v102
	v_fmac_f32_e32 v37, v225, v104
	s_waitcnt lgkmcnt(5)
	v_fmac_f32_e32 v38, v225, v106
	v_fmac_f32_e32 v39, v225, v108
	s_waitcnt lgkmcnt(4)
	v_fmac_f32_e32 v40, v225, v110
	v_fmac_f32_e32 v41, v225, v112
	s_waitcnt lgkmcnt(3)
	v_fmac_f32_e32 v44, v225, v114
	v_fmac_f32_e32 v45, v225, v116
	s_waitcnt lgkmcnt(2)
	v_fmac_f32_e32 v46, v225, v118
	v_fmac_f32_e32 v47, v225, v120
	s_waitcnt lgkmcnt(1)
	v_fmac_f32_e32 v48, v225, v122
	v_fmac_f32_e32 v49, v225, v124
	s_waitcnt lgkmcnt(0)
	v_fmac_f32_e32 v60, v225, v128
	v_fmac_f32_e32 v30, v226, v63
	v_fmac_f32_e32 v43, v226, v65
	v_fmac_f32_e32 v42, v226, v67
	v_fmac_f32_e32 v35, v226, v69
	v_fmac_f32_e32 v34, v226, v71
	v_fmac_f32_e32 v29, v226, v73
	v_fmac_f32_e32 v28, v226, v75
	v_fmac_f32_e32 v27, v226, v77
	v_fmac_f32_e32 v26, v226, v79
	v_fmac_f32_e32 v25, v226, v81
	v_fmac_f32_e32 v24, v226, v83
	v_fmac_f32_e32 v23, v226, v85
	v_fmac_f32_e32 v22, v226, v87
	v_fmac_f32_e32 v21, v226, v89
	v_fmac_f32_e32 v20, v226, v91
	v_fmac_f32_e32 v17, v226, v93
	v_fmac_f32_e32 v16, v226, v95
	v_fmac_f32_e32 v31, v226, v97
	v_fmac_f32_e32 v32, v226, v99
	v_fmac_f32_e32 v33, v226, v101
	v_fmac_f32_e32 v36, v226, v103
	v_fmac_f32_e32 v37, v226, v105
	v_fmac_f32_e32 v38, v226, v107
	v_fmac_f32_e32 v39, v226, v109
	v_fmac_f32_e32 v40, v226, v111
	v_fmac_f32_e32 v41, v226, v113
	v_fmac_f32_e32 v44, v226, v115
	v_fmac_f32_e32 v45, v226, v117
	v_fmac_f32_e32 v46, v226, v119
	v_fmac_f32_e32 v47, v226, v121
	v_fmac_f32_e32 v48, v226, v123
	v_fmac_f32_e32 v49, v226, v125
	v_fmac_f32_e32 v60, v226, v129
	v_add_u32_e32 v61, 248, v57
	v_add_u32_e32 v150, 248, v149
	ds_read2st64_b64 v[62:65], v61 offset1:4
	ds_read2st64_b64 v[66:69], v61 offset0:8 offset1:12
	ds_read2st64_b64 v[70:73], v61 offset0:16 offset1:20
	ds_read2st64_b64 v[74:77], v61 offset0:24 offset1:28
	ds_read2st64_b64 v[78:81], v61 offset0:32 offset1:36
	ds_read2st64_b64 v[82:85], v61 offset0:40 offset1:44
	ds_read2st64_b64 v[86:89], v61 offset0:48 offset1:52
	ds_read2st64_b64 v[90:93], v61 offset0:56 offset1:60
	ds_read2st64_b64 v[94:97], v61 offset0:64 offset1:68
	ds_read2st64_b64 v[98:101], v61 offset0:72 offset1:76
	ds_read2st64_b64 v[102:105], v61 offset0:80 offset1:84
	ds_read2st64_b64 v[106:109], v61 offset0:88 offset1:92
	ds_read2st64_b64 v[110:113], v61 offset0:96 offset1:100
	ds_read2st64_b64 v[114:117], v61 offset0:104 offset1:108
	ds_read2st64_b64 v[118:121], v61 offset0:112 offset1:116
	ds_read2st64_b64 v[122:125], v61 offset0:120 offset1:124
	ds_read_b64 v[128:129], v150
	s_waitcnt vmcnt(0)
	s_waitcnt lgkmcnt(15)
	v_fmac_f32_e32 v30, v227, v62
	v_fmac_f32_e32 v43, v227, v64
	s_waitcnt lgkmcnt(15)
	v_fmac_f32_e32 v42, v227, v66
	v_fmac_f32_e32 v35, v227, v68
	s_waitcnt lgkmcnt(14)
	v_fmac_f32_e32 v34, v227, v70
	v_fmac_f32_e32 v29, v227, v72
	s_waitcnt lgkmcnt(13)
	v_fmac_f32_e32 v28, v227, v74
	v_fmac_f32_e32 v27, v227, v76
	s_waitcnt lgkmcnt(12)
	v_fmac_f32_e32 v26, v227, v78
	v_fmac_f32_e32 v25, v227, v80
	s_waitcnt lgkmcnt(11)
	v_fmac_f32_e32 v24, v227, v82
	v_fmac_f32_e32 v23, v227, v84
	s_waitcnt lgkmcnt(10)
	v_fmac_f32_e32 v22, v227, v86
	v_fmac_f32_e32 v21, v227, v88
	s_waitcnt lgkmcnt(9)
	v_fmac_f32_e32 v20, v227, v90
	v_fmac_f32_e32 v17, v227, v92
	s_waitcnt lgkmcnt(8)
	v_fmac_f32_e32 v16, v227, v94
	v_fmac_f32_e32 v31, v227, v96
	s_waitcnt lgkmcnt(7)
	v_fmac_f32_e32 v32, v227, v98
	v_fmac_f32_e32 v33, v227, v100
	s_waitcnt lgkmcnt(6)
	v_fmac_f32_e32 v36, v227, v102
	v_fmac_f32_e32 v37, v227, v104
	s_waitcnt lgkmcnt(5)
	v_fmac_f32_e32 v38, v227, v106
	v_fmac_f32_e32 v39, v227, v108
	s_waitcnt lgkmcnt(4)
	v_fmac_f32_e32 v40, v227, v110
	v_fmac_f32_e32 v41, v227, v112
	s_waitcnt lgkmcnt(3)
	v_fmac_f32_e32 v44, v227, v114
	v_fmac_f32_e32 v45, v227, v116
	s_waitcnt lgkmcnt(2)
	v_fmac_f32_e32 v46, v227, v118
	v_fmac_f32_e32 v47, v227, v120
	s_waitcnt lgkmcnt(1)
	v_fmac_f32_e32 v48, v227, v122
	v_fmac_f32_e32 v49, v227, v124
	s_waitcnt lgkmcnt(0)
	v_fmac_f32_e32 v60, v227, v128
	v_fmac_f32_e32 v30, v228, v63
	v_fmac_f32_e32 v43, v228, v65
	v_fmac_f32_e32 v42, v228, v67
	v_fmac_f32_e32 v35, v228, v69
	v_fmac_f32_e32 v34, v228, v71
	v_fmac_f32_e32 v29, v228, v73
	v_fmac_f32_e32 v28, v228, v75
	v_fmac_f32_e32 v27, v228, v77
	v_fmac_f32_e32 v26, v228, v79
	v_fmac_f32_e32 v25, v228, v81
	v_fmac_f32_e32 v24, v228, v83
	v_fmac_f32_e32 v23, v228, v85
	v_fmac_f32_e32 v22, v228, v87
	v_fmac_f32_e32 v21, v228, v89
	v_fmac_f32_e32 v20, v228, v91
	v_fmac_f32_e32 v17, v228, v93
	v_fmac_f32_e32 v16, v228, v95
	v_fmac_f32_e32 v31, v228, v97
	v_fmac_f32_e32 v32, v228, v99
	v_fmac_f32_e32 v33, v228, v101
	v_fmac_f32_e32 v36, v228, v103
	v_fmac_f32_e32 v37, v228, v105
	v_fmac_f32_e32 v38, v228, v107
	v_fmac_f32_e32 v39, v228, v109
	v_fmac_f32_e32 v40, v228, v111
	v_fmac_f32_e32 v41, v228, v113
	v_fmac_f32_e32 v44, v228, v115
	v_fmac_f32_e32 v45, v228, v117
	v_fmac_f32_e32 v46, v228, v119
	v_fmac_f32_e32 v47, v228, v121
	v_fmac_f32_e32 v48, v228, v123
	v_fmac_f32_e32 v49, v228, v125
	v_fmac_f32_e32 v60, v228, v129
	s_barrier
	ds_write2st64_b32 v58, v30, v43 offset1:1
	ds_write2st64_b32 v58, v42, v35 offset0:2 offset1:3
	ds_write2st64_b32 v58, v34, v29 offset0:4 offset1:5
	ds_write2st64_b32 v58, v28, v27 offset0:6 offset1:7
	ds_write2st64_b32 v58, v26, v25 offset0:8 offset1:9
	ds_write2st64_b32 v58, v24, v23 offset0:10 offset1:11
	ds_write2st64_b32 v58, v22, v21 offset0:12 offset1:13
	ds_write2st64_b32 v58, v20, v17 offset0:14 offset1:15
	ds_write2st64_b32 v58, v16, v31 offset0:16 offset1:17
	ds_write2st64_b32 v58, v32, v33 offset0:18 offset1:19
	ds_write2st64_b32 v58, v36, v37 offset0:20 offset1:21
	ds_write2st64_b32 v58, v38, v39 offset0:22 offset1:23
	ds_write2st64_b32 v58, v40, v41 offset0:24 offset1:25
	ds_write2st64_b32 v58, v44, v45 offset0:26 offset1:27
	ds_write2st64_b32 v58, v46, v47 offset0:28 offset1:29
	ds_write2st64_b32 v58, v48, v49 offset0:30 offset1:31
	ds_write_b32 v58, v60 offset:8192
	s_waitcnt lgkmcnt(0)
	s_barrier
	s_and_saveexec_b64 s[18:19], s[8:9]
	s_cbranch_execz .LBB0_7
	s_mul_i32 s20, s66, 0x1800
	s_add_i32 s20, s20, s26
	v_or_b32_e32 v16, s20, v148
	v_ashrrev_i32_e32 v17, 31, v16
	s_mul_i32 s66, s66, 33
	v_lshl_add_u64 v[16:17], v[16:17], 2, s[46:47]
	v_lshl_add_u64 v[20:21], s[26:27], 2, v[8:9]
	s_mov_b64 s[20:21], 0
	v_mov_b32_e32 v22, v18
